# drop stale vmcnt(0) in phase-1 K loop; first two DMA loads of each next unit issued before the epilogue stores, first-iteration wait relaxed to vmcnt(22) (phases 1,6,8,12)
# speedup vs baseline: 1.0084x; 1.0084x over previous
; #define PG8_STAGE(bufoff, gbase, voff) do { _Pragma("unroll") for (int _i = 0; _i < 2; ++_i) \
;         __builtin_amdgcn_global_load_lds((const unsigned*)((const char*)(gbase) + (voff)[_i]), (LAS unsigned*)(lds + (bufoff) + ldsw + _i * 8192), 16, 0, 0); } while (0)
; template <class Epi>
; __device__ __forceinline__ void gemm_phase(LAS unsigned char* lds, const Gemm g, const StaticOrder& S, const Epi& E) {
;     const int tid = threadIdx.x, wid = __builtin_amdgcn_readfirstlane(tid >> 6), lane = tid & 63, wr = wid >> 2, wc = wid & 3, fr = lane & 15, fq = lane >> 4;
;     const int K = g.K, nt = K / BK, lda = g.lda;
;     unsigned voffA[2], voffB[2];
; #pragma unroll
;     for (int i = 0; i < 2; ++i) { int R, C; stage_rc(tid * 16 + i * 8192, R, C); const int Rb = Epi::PERM ? ((R & ~31) + perm32(R & 31)) : R;
;         voffA[i] = (unsigned)(R * lda + C) * 2u; voffB[i] = (unsigned)(Rb * K + C) * 2u; }
;     const size_t kstep = (size_t)(BK * 2);
;     const size_t hstepA = (size_t)HALF * lda * 2, hstepB = (size_t)HALF * K * 2;
;     const size_t tstepA = 2 * hstepA, tstepB = 2 * hstepB;
;     const unsigned ldsw = (unsigned)wid * 1024u;
;     const int aoff = lds_byte(wr * 64 + fr, fq * 8), boff = lds_byte(wc * 32 + fr, fq * 8);
;     ...
;     Unit cur, nxt; int ui = 0;
;     if (!S.next(0, cur)) return;
;     ...
;     for (int q_ = 0; q_ < ((S.c >> 3) & 3); ++q_) __builtin_amdgcn_s_sleep(100);
;     ...
;     f32x4 acc[2][2][4][2];
; #pragma unroll
;     for (int a = 0; a < 2; ++a)
; #pragma unroll
;         for (int b = 0; b < 2; ++b)
; #pragma unroll
;             for (int m = 0; m < 4; ++m)
; #pragma unroll
;                 for (int n = 0; n < 2; ++n) acc[a][b][m][n] = (f32x4){0.f, 0.f, 0.f, 0.f};
;     bf16x8 At[4][2], B0[2][2], B1[2][2]; float epre[8];
; #pragma unroll
;     for (int q_ = 0; q_ < 8; ++q_) epre[q_] = 0.f;
;     const char* cA = (const char*)g.A + (size_t)cur.pm * tstepA; const char* cB = (const char*)g.Bt + (size_t)cur.pn * tstepB;
;     PG8_STAGE(PG8_SB(0, 0), cB, voffB); PG8_STAGE(PG8_SA(0, 0), cA, voffA); PG8_STAGE(PG8_SB(0, 1), cB + hstepB, voffB); PG8_STAGE(PG8_SA(0, 1), cA + hstepA, voffA);
;     if (wr == 1) PG8_BAR;
;     PG8_WAIT_V(4); PG8_BAR;
;     PG8_STAGE(PG8_SB(1, 0), cB + kstep, voffB); PG8_STAGE(PG8_SA(1, 0), cA + kstep, voffA); PG8_STAGE(PG8_SB(1, 1), cB + hstepB + kstep, voffB);
;     PG8_WAIT_V(6); PG8_BAR;
.LBB0_200:
	s_and_b32 s10, s6, 3
	s_mov_b64 s[6:7], 0x80
	s_add_i32 m0, s30, 0x18000
	v_lshl_add_u64 v[6:7], v[6:7], 0, s[6:7]
	s_lshl_b32 s11, s1, 13
	s_lshl_b32 s12, s10, 12
	s_waitcnt vmcnt(4)
	s_barrier
	global_load_lds_dwordx4 v[6:7], off
	v_lshl_add_u64 v[4:5], v[4:5], 0, s[6:7]
	s_add_i32 m0, s30, 0x1a000
	s_add_i32 s36, s30, 0x8000
	s_add_i32 s37, s30, 0xa000
	global_load_lds_dwordx4 v[4:5], off
	v_lshl_add_u64 v[2:3], v[2:3], 0, s[6:7]
	s_mov_b32 m0, s36
	s_add_u32 s8, s22, 0x40080
	global_load_lds_dwordx4 v[2:3], off
	v_lshl_add_u64 v[0:1], v[0:1], 0, s[6:7]
	s_mov_b32 m0, s37
	s_addc_u32 s9, s23, 0
	global_load_lds_dwordx4 v[0:1], off
	s_add_i32 m0, s30, 0x1c000
	v_lshl_add_u64 v[0:1], s[8:9], 0, v[132:133]
	global_load_lds_dwordx4 v[0:1], off
	v_lshl_add_u64 v[0:1], s[8:9], 0, v[128:129]
	s_add_i32 m0, s30, 0x1e000
	v_lshlrev_b32_e32 v2, 2, v152
	global_load_lds_dwordx4 v[0:1], off
	v_and_b32_e32 v0, 15, v152
	v_lshlrev_b32_e32 v1, 1, v11
	v_lshl_or_b32 v153, s1, 6, v0
	v_lshl_or_b32 v0, v0, 6, v1
	v_and_b32_e32 v2, 32, v2
	s_sext_i32_i16 s43, s0
	v_bitop3_b32 v3, v0, s11, v2 bitop3:0xde
	v_lshlrev_b32_e32 v0, 6, v152
	s_movk_i32 s0, 0x3c0
	v_and_or_b32 v0, v0, s0, v1
	v_readlane_b32 s0, v251, 52
	v_bitop3_b32 v168, s12, v0, v2 bitop3:0xf6
	v_lshlrev_b32_e32 v0, 2, v11
	v_mov_b32_e32 v1, v133
	v_readlane_b32 s1, v251, 53
	s_waitcnt vmcnt(6)
	s_cmp_eq_u32 s10, 0
	s_cselect_b64 s[8:9], -1, 0
	v_lshl_add_u64 v[136:137], s[0:1], 0, v[0:1]
	v_lshlrev_b32_e32 v0, 8, v152
	v_and_b32_e32 v0, 0x38000, v0
	v_lshlrev_b32_e32 v1, 11, v12
	v_or3_b32 v0, v9, v0, v1
	v_add_u32_e32 v138, v0, v10
	v_lshlrev_b32_e32 v0, 4, v8
	v_and_b32_e32 v0, 0x78000, v0
	v_or3_b32 v0, v9, v0, v1
	s_add_i32 s39, 0, 0x10000
	s_add_i32 s40, 0, 0x14000
	s_ashr_i32 s38, s92, 31
	v_lshl_or_b32 v169, s10, 5, v11
	v_mov_b32_e32 v139, v133
	v_add_u32_e32 v140, v0, v10
	v_mov_b32_e32 v141, v133
	v_mov_b64_e32 v[142:143], 0x1500
	v_mov_b64_e32 v[144:145], 0x14ff
	v_add_u32_e32 v170, s39, v168
	v_add_u32_e32 v171, 0, v3
	v_add_u32_e32 v172, s40, v168
	v_mov_b32_e32 v173, 0x358637bd
	s_mov_b32 s41, 0x800000
	s_movk_i32 s42, 0x2800
	s_add_u32 vcc_lo, s20, 0x40080
	s_addc_u32 vcc_hi, s21, 0
	s_add_i32 m0, s30, 0xc000
	v_lshl_add_u64 v[236:237], vcc, 0, v[138:139]
	v_lshl_add_u64 v[238:239], vcc, 0, v[140:141]
	global_load_lds_dwordx4 v[236:237], off
	s_add_i32 m0, s30, 0xe000
	s_nop 0
	global_load_lds_dwordx4 v[238:239], off
	s_waitcnt vmcnt(0)
	s_barrier
	s_branch .LBB0_202

; #define PG8_STAGE(bufoff, gbase, voff) do { _Pragma("unroll") for (int _i = 0; _i < 2; ++_i) \
;         __builtin_amdgcn_global_load_lds((const unsigned*)((const char*)(gbase) + (voff)[_i]), (LAS unsigned*)(lds + (bufoff) + ldsw + _i * 8192), 16, 0, 0); } while (0)
; #define PG8_LDA(dst, b, h) do { _Pragma("unroll") for (int m = 0; m < 4; ++m) _Pragma("unroll") for (int k = 0; k < 2; ++k) dst[m][k] = *(const LAS bf16x8*)(lds + PG8_SA(b, h) + aoff + m * 2048 + k * 1024); } while (0)
; #define PG8_LDB(dst, b, h) do { _Pragma("unroll") for (int n = 0; n < 2; ++n) _Pragma("unroll") for (int k = 0; k < 2; ++k) dst[n][k] = *(const LAS bf16x8*)(lds + PG8_SB(b, h) + boff + n * 2048 + k * 1024); } while (0)
; #define PG8_WAIT_V(n) asm volatile("s_waitcnt vmcnt(" #n ")" ::: "memory")
; #define PG8_WAIT_L(n) asm volatile("s_waitcnt lgkmcnt(" #n ")" ::: "memory")
; #define PG8_BAR __builtin_amdgcn_s_barrier()
; #define PG8_SCHED __builtin_amdgcn_sched_barrier(0)
; template <class Epi>
; __device__ __forceinline__ void gemm_phase(LAS unsigned char* lds, const Gemm g, const StaticOrder& S, const Epi& E) {
;     ...
;     for (;;) {
;         const bool has_next = S.next(ui + 1, nxt);
;         const char* nA = has_next ? (const char*)g.A + (size_t)nxt.pm * tstepA : cA; const char* nB = has_next ? (const char*)g.Bt + (size_t)nxt.pn * tstepB : cB;
;         for (int t = 0; t < nt; t += 2) {
;             const bool last = (t == nt - 2);
;             const char* a1 = cA + (size_t)(t + 1) * kstep;
;             const char* a2 = last ? nA : cA + (size_t)(t + 2) * kstep; const char* b2 = last ? nB : cB + (size_t)(t + 2) * kstep;
;             const char* a3 = a2 + kstep; const char* b3 = b2 + kstep;
;             if (last) E.pre(cur, wr, fr, epre);
;             PG8_LDB(B0, 0, 0); PG8_SCHED; PG8_LDA(At, 0, 0); PG8_STAGE(PG8_SA(1, 1), a1 + hstepA, voffA);
;             PG8_WAIT_L(8); PG8_BAR; PG8_WAIT_L(0); PG8_MMA(0, 0, At, B0); PG8_BAR; PG8_SCHED;
;             PG8_LDB(B1, 0, 1); PG8_STAGE(PG8_SB(0, 0), b2, voffB);
;             PG8_BAR; PG8_WAIT_L(0); PG8_MMA(0, 1, At, B1); PG8_BAR;
;             PG8_LDA(At, 0, 1); PG8_STAGE(PG8_SA(0, 0), a2, voffA);
;             PG8_BAR; PG8_WAIT_L(0); PG8_MMA(1, 0, At, B0); PG8_BAR; PG8_SCHED;
;             PG8_STAGE(PG8_SB(0, 1), b2 + hstepB, voffB);
;             PG8_WAIT_V(6); PG8_BAR; PG8_MMA(1, 1, At, B1); PG8_BAR;
.LBB0_204:
	s_ashr_i32 s13, s12, 31
	v_cmp_lt_i64_e32 vcc, s[14:15], v[142:143]
	s_lshl_b64 s[14:15], s[12:13], 19
	s_add_u32 s14, s76, s14
	s_addc_u32 s15, s77, s15
	s_and_b64 s[16:17], vcc, exec
	s_cselect_b32 s13, s15, s21
	s_cselect_b32 s19, s14, s20
	s_ashr_i32 s11, s10, 31
	s_lshl_b64 s[16:17], s[10:11], 19
	s_add_u32 s16, s74, s16
	s_addc_u32 s17, s75, s17
	s_and_b64 s[24:25], vcc, exec
	s_cselect_b32 s11, s17, s23
	s_cselect_b32 s44, s16, s22
	s_add_u32 s20, s20, 0x40080
	s_addc_u32 s21, s21, 0
	s_add_u32 s45, s22, 0x100
	s_addc_u32 s46, s23, 0
	s_mov_b32 s47, -2
	s_waitcnt lgkmcnt(0)
	ds_read_b128 v[146:149], v170
	ds_read_b128 v[154:157], v170 offset:1024
	ds_read_b128 v[158:161], v170 offset:2048
	ds_read_b128 v[162:165], v170 offset:3072
	s_add_u32 s22, s20, 0xfffc0080
	s_addc_u32 s23, s21, -1
	s_cmp_eq_u32 s47, 12
	s_cselect_b32 s25, s13, s23
	s_cselect_b32 s24, s19, s22
	s_cselect_b32 s23, s11, s46
	s_cselect_b32 s22, s44, s45
	ds_read_b128 v[174:177], v171
	ds_read_b128 v[178:181], v171 offset:1024
	ds_read_b128 v[182:185], v171 offset:2048
	ds_read_b128 v[186:189], v171 offset:3072
	ds_read_b128 v[190:193], v171 offset:4096
	ds_read_b128 v[194:197], v171 offset:5120
	ds_read_b128 v[198:201], v171 offset:6144
	ds_read_b128 v[202:205], v171 offset:7168
	s_waitcnt lgkmcnt(8)
	s_barrier
	s_waitcnt lgkmcnt(0)
	s_setprio 1
	s_waitcnt lgkmcnt(0)
	v_mfma_f32_16x16x32_bf16 v[76:79], v[146:149], v[174:177], 0
	v_mfma_f32_16x16x32_bf16 v[64:67], v[158:161], v[174:177], 0
	v_mfma_f32_16x16x32_bf16 v[60:63], v[146:149], v[182:185], 0
	v_mfma_f32_16x16x32_bf16 v[56:59], v[158:161], v[182:185], 0
	v_mfma_f32_16x16x32_bf16 v[48:51], v[146:149], v[190:193], 0
	v_mfma_f32_16x16x32_bf16 v[40:43], v[158:161], v[190:193], 0
	v_mfma_f32_16x16x32_bf16 v[36:39], v[146:149], v[198:201], 0
	v_mfma_f32_16x16x32_bf16 v[32:35], v[158:161], v[198:201], 0
	v_mfma_f32_16x16x32_bf16 v[76:79], v[154:157], v[178:181], v[76:79]
	v_mfma_f32_16x16x32_bf16 v[64:67], v[162:165], v[178:181], v[64:67]
	v_mfma_f32_16x16x32_bf16 v[60:63], v[154:157], v[186:189], v[60:63]
	v_mfma_f32_16x16x32_bf16 v[56:59], v[162:165], v[186:189], v[56:59]
	v_mfma_f32_16x16x32_bf16 v[48:51], v[154:157], v[194:197], v[48:51]
	v_mfma_f32_16x16x32_bf16 v[40:43], v[162:165], v[194:197], v[40:43]
	v_mfma_f32_16x16x32_bf16 v[36:39], v[154:157], v[202:205], v[36:39]
	v_mfma_f32_16x16x32_bf16 v[32:35], v[162:165], v[202:205], v[32:35]
	s_setprio 0
	s_barrier
	s_add_i32 s48, s39, s27
	v_lshl_add_u64 v[150:151], s[22:23], 0, v[132:133]
	s_mov_b32 m0, s48
	ds_read_b128 v[206:209], v172
	ds_read_b128 v[210:213], v172 offset:1024
	ds_read_b128 v[214:217], v172 offset:2048
	ds_read_b128 v[218:221], v172 offset:3072
	global_load_lds_dwordx4 v[150:151], off
	v_lshl_add_u64 v[166:167], s[22:23], 0, v[128:129]
	s_add_i32 m0, s48, 0x2000
	s_nop 0
	global_load_lds_dwordx4 v[166:167], off
	s_barrier
	s_waitcnt lgkmcnt(0)
	s_setprio 1
	s_waitcnt lgkmcnt(0)
	v_mfma_f32_16x16x32_bf16 v[124:127], v[206:209], v[174:177], 0
	v_mfma_f32_16x16x32_bf16 v[120:123], v[214:217], v[174:177], 0
	v_mfma_f32_16x16x32_bf16 v[116:119], v[206:209], v[182:185], 0
	v_mfma_f32_16x16x32_bf16 v[112:115], v[214:217], v[182:185], 0
	v_mfma_f32_16x16x32_bf16 v[108:111], v[206:209], v[190:193], 0
	v_mfma_f32_16x16x32_bf16 v[104:107], v[214:217], v[190:193], 0
	v_mfma_f32_16x16x32_bf16 v[100:103], v[206:209], v[198:201], 0
	v_mfma_f32_16x16x32_bf16 v[96:99], v[214:217], v[198:201], 0
	v_mfma_f32_16x16x32_bf16 v[124:127], v[210:213], v[178:181], v[124:127]
	v_mfma_f32_16x16x32_bf16 v[120:123], v[218:221], v[178:181], v[120:123]
	v_mfma_f32_16x16x32_bf16 v[116:119], v[210:213], v[186:189], v[116:119]
	v_mfma_f32_16x16x32_bf16 v[112:115], v[218:221], v[186:189], v[112:115]
	v_mfma_f32_16x16x32_bf16 v[108:111], v[210:213], v[194:197], v[108:111]
	v_mfma_f32_16x16x32_bf16 v[104:107], v[218:221], v[194:197], v[104:107]
	v_mfma_f32_16x16x32_bf16 v[100:103], v[210:213], v[202:205], v[100:103]
	v_mfma_f32_16x16x32_bf16 v[96:99], v[218:221], v[202:205], v[96:99]
	s_setprio 0
	s_mov_b32 m0, s30
	v_lshl_add_u64 v[222:223], s[24:25], 0, v[134:135]
	s_barrier
	ds_read_b128 v[174:177], v171 offset:16384
	ds_read_b128 v[178:181], v171 offset:17408
	ds_read_b128 v[182:185], v171 offset:18432
	ds_read_b128 v[186:189], v171 offset:19456
	ds_read_b128 v[190:193], v171 offset:20480
	ds_read_b128 v[194:197], v171 offset:21504
	ds_read_b128 v[198:201], v171 offset:22528
	ds_read_b128 v[202:205], v171 offset:23552
	global_load_lds_dwordx4 v[222:223], off
	v_lshl_add_u64 v[224:225], s[24:25], 0, v[130:131]
	s_mov_b32 m0, s31
	s_nop 0
	global_load_lds_dwordx4 v[224:225], off
	s_barrier
	s_waitcnt lgkmcnt(0)
	s_setprio 1
	s_waitcnt lgkmcnt(0)
	v_mfma_f32_16x16x32_bf16 v[28:31], v[146:149], v[174:177], 0
	v_mfma_f32_16x16x32_bf16 v[24:27], v[158:161], v[174:177], 0
	v_mfma_f32_16x16x32_bf16 v[20:23], v[146:149], v[182:185], 0
	v_mfma_f32_16x16x32_bf16 v[16:19], v[158:161], v[182:185], 0
	v_mfma_f32_16x16x32_bf16 v[12:15], v[146:149], v[190:193], 0
	v_mfma_f32_16x16x32_bf16 v[8:11], v[158:161], v[190:193], 0
	v_mfma_f32_16x16x32_bf16 v[4:7], v[146:149], v[198:201], 0
	v_mfma_f32_16x16x32_bf16 v[0:3], v[158:161], v[198:201], 0
	v_mfma_f32_16x16x32_bf16 v[28:31], v[154:157], v[178:181], v[28:31]
	v_mfma_f32_16x16x32_bf16 v[24:27], v[162:165], v[178:181], v[24:27]
	v_mfma_f32_16x16x32_bf16 v[20:23], v[154:157], v[186:189], v[20:23]
	v_mfma_f32_16x16x32_bf16 v[16:19], v[162:165], v[186:189], v[16:19]
	v_mfma_f32_16x16x32_bf16 v[12:15], v[154:157], v[194:197], v[12:15]
	v_mfma_f32_16x16x32_bf16 v[8:11], v[162:165], v[194:197], v[8:11]
	v_mfma_f32_16x16x32_bf16 v[4:7], v[154:157], v[202:205], v[4:7]
	v_mfma_f32_16x16x32_bf16 v[0:3], v[162:165], v[202:205], v[0:3]
	s_setprio 0
	s_barrier
; #define PG8_STAGE(bufoff, gbase, voff) do { _Pragma("unroll") for (int _i = 0; _i < 2; ++_i) \
;         __builtin_amdgcn_global_load_lds((const unsigned*)((const char*)(gbase) + (voff)[_i]), (LAS unsigned*)(lds + (bufoff) + ldsw + _i * 8192), 16, 0, 0); } while (0)
; #define PG8_LDA(dst, b, h) do { _Pragma("unroll") for (int m = 0; m < 4; ++m) _Pragma("unroll") for (int k = 0; k < 2; ++k) dst[m][k] = *(const LAS bf16x8*)(lds + PG8_SA(b, h) + aoff + m * 2048 + k * 1024); } while (0)
; #define PG8_LDB(dst, b, h) do { _Pragma("unroll") for (int n = 0; n < 2; ++n) _Pragma("unroll") for (int k = 0; k < 2; ++k) dst[n][k] = *(const LAS bf16x8*)(lds + PG8_SB(b, h) + boff + n * 2048 + k * 1024); } while (0)
; #define PG8_MMA(ai, bj, At, Bt) do { __builtin_amdgcn_s_setprio(1); _Pragma("unroll") for (int m = 0; m < 4; ++m) _Pragma("unroll") for (int n = 0; n < 2; ++n) _Pragma("unroll") for (int k = 0; k < 2; ++k) \
;         acc[ai][bj][m][n] = __builtin_amdgcn_mfma_f32_16x16x32_bf16(Bt[n][k], At[m][k], acc[ai][bj][m][n], 0, 0, 0); __builtin_amdgcn_s_setprio(0); } while (0)
; #define PG8_WAIT_V(n) asm volatile("s_waitcnt vmcnt(" #n ")" ::: "memory")
; #define PG8_WAIT_L(n) asm volatile("s_waitcnt lgkmcnt(" #n ")" ::: "memory")
; #define PG8_BAR __builtin_amdgcn_s_barrier()
; #define PG8_SCHED __builtin_amdgcn_sched_barrier(0)
; template <class Epi>
; __device__ __forceinline__ void gemm_phase(LAS unsigned char* lds, const Gemm g, const StaticOrder& S, const Epi& E) {
;     ...
;             PG8_WAIT_V(6); PG8_BAR; PG8_MMA(1, 1, At, B1); PG8_BAR;
;             PG8_LDB(B0, 1, 0); PG8_SCHED; PG8_LDA(At, 1, 0); PG8_STAGE(PG8_SA(0, 1), a2 + hstepA, voffA);
;             PG8_WAIT_L(8); PG8_BAR; PG8_WAIT_L(0); PG8_MMA(0, 0, At, B0); PG8_BAR; PG8_SCHED;
;             PG8_LDB(B1, 1, 1); PG8_STAGE(PG8_SB(1, 0), b3, voffB);
;             PG8_BAR; PG8_WAIT_L(0); PG8_MMA(0, 1, At, B1); PG8_BAR;
;             PG8_LDA(At, 1, 1); PG8_STAGE(PG8_SA(1, 0), a3, voffA);
;             PG8_BAR; PG8_WAIT_L(0); PG8_MMA(1, 0, At, B0); PG8_BAR; PG8_SCHED;
	s_add_u32 s48, s22, 0x40000
	s_addc_u32 s49, s23, 0
	s_add_i32 s50, s40, s27
	v_lshl_add_u64 v[146:147], s[48:49], 0, v[132:133]
	s_mov_b32 m0, s50
	s_nop 0
	global_load_lds_dwordx4 v[146:147], off
	v_lshl_add_u64 v[146:147], s[48:49], 0, v[128:129]
	s_add_i32 m0, s50, 0x2000
	s_nop 0
	global_load_lds_dwordx4 v[146:147], off
	s_waitcnt vmcnt(22)
	s_barrier
	s_setprio 1
	v_mfma_f32_16x16x32_bf16 v[92:95], v[206:209], v[174:177], 0
	v_mfma_f32_16x16x32_bf16 v[88:91], v[214:217], v[174:177], 0
	v_mfma_f32_16x16x32_bf16 v[84:87], v[206:209], v[182:185], 0
	v_mfma_f32_16x16x32_bf16 v[80:83], v[214:217], v[182:185], 0
	v_mfma_f32_16x16x32_bf16 v[72:75], v[206:209], v[190:193], 0
	v_mfma_f32_16x16x32_bf16 v[68:71], v[214:217], v[190:193], 0
	v_mfma_f32_16x16x32_bf16 v[52:55], v[206:209], v[198:201], 0
	v_mfma_f32_16x16x32_bf16 v[44:47], v[214:217], v[198:201], 0
	v_mfma_f32_16x16x32_bf16 v[92:95], v[210:213], v[178:181], v[92:95]
	v_mfma_f32_16x16x32_bf16 v[88:91], v[218:221], v[178:181], v[88:91]
	v_mfma_f32_16x16x32_bf16 v[84:87], v[210:213], v[186:189], v[84:87]
	v_mfma_f32_16x16x32_bf16 v[80:83], v[218:221], v[186:189], v[80:83]
	v_mfma_f32_16x16x32_bf16 v[72:75], v[210:213], v[194:197], v[72:75]
	v_mfma_f32_16x16x32_bf16 v[68:71], v[218:221], v[194:197], v[68:71]
	v_mfma_f32_16x16x32_bf16 v[52:55], v[210:213], v[202:205], v[52:55]
	v_mfma_f32_16x16x32_bf16 v[44:47], v[218:221], v[202:205], v[44:47]
	s_setprio 0
	s_add_i32 s48, 0, 0x18000
	v_add_u32_e32 v162, s48, v168
	s_barrier
	ds_read_b128 v[146:149], v162
	ds_read_b128 v[154:157], v162 offset:1024
	ds_read_b128 v[158:161], v162 offset:2048
	ds_read_b128 v[162:165], v162 offset:3072
	s_add_u32 s24, s24, 0x40000
	s_addc_u32 s25, s25, 0
	s_mov_b32 m0, s33
	v_lshl_add_u64 v[206:207], s[24:25], 0, v[134:135]
	ds_read_b128 v[174:177], v171 offset:32768
	ds_read_b128 v[178:181], v171 offset:33792
	ds_read_b128 v[182:185], v171 offset:34816
	ds_read_b128 v[186:189], v171 offset:35840
	ds_read_b128 v[190:193], v171 offset:36864
	ds_read_b128 v[194:197], v171 offset:37888
	ds_read_b128 v[198:201], v171 offset:38912
	ds_read_b128 v[202:205], v171 offset:39936
	global_load_lds_dwordx4 v[206:207], off
	v_lshl_add_u64 v[206:207], s[24:25], 0, v[130:131]
	s_mov_b32 m0, s34
	s_nop 0
	global_load_lds_dwordx4 v[206:207], off
	s_waitcnt lgkmcnt(8)
	s_barrier
	s_waitcnt lgkmcnt(0)
	s_setprio 1
	s_waitcnt lgkmcnt(0)
	v_mfma_f32_16x16x32_bf16 v[76:79], v[146:149], v[174:177], v[76:79]
	v_mfma_f32_16x16x32_bf16 v[64:67], v[158:161], v[174:177], v[64:67]
	v_mfma_f32_16x16x32_bf16 v[60:63], v[146:149], v[182:185], v[60:63]
	v_mfma_f32_16x16x32_bf16 v[56:59], v[158:161], v[182:185], v[56:59]
	v_mfma_f32_16x16x32_bf16 v[48:51], v[146:149], v[190:193], v[48:51]
	v_mfma_f32_16x16x32_bf16 v[40:43], v[158:161], v[190:193], v[40:43]
	v_mfma_f32_16x16x32_bf16 v[36:39], v[146:149], v[198:201], v[36:39]
	v_mfma_f32_16x16x32_bf16 v[32:35], v[158:161], v[198:201], v[32:35]
	v_mfma_f32_16x16x32_bf16 v[76:79], v[154:157], v[178:181], v[76:79]
	v_mfma_f32_16x16x32_bf16 v[64:67], v[162:165], v[178:181], v[64:67]
	v_mfma_f32_16x16x32_bf16 v[60:63], v[154:157], v[186:189], v[60:63]
	v_mfma_f32_16x16x32_bf16 v[56:59], v[162:165], v[186:189], v[56:59]
	v_mfma_f32_16x16x32_bf16 v[48:51], v[154:157], v[194:197], v[48:51]
	v_mfma_f32_16x16x32_bf16 v[40:43], v[162:165], v[194:197], v[40:43]
	v_mfma_f32_16x16x32_bf16 v[36:39], v[154:157], v[202:205], v[36:39]
	v_mfma_f32_16x16x32_bf16 v[32:35], v[162:165], v[202:205], v[32:35]
	s_setprio 0
	s_barrier
	s_add_i32 s24, 0, 0x1c000
	s_add_i32 s25, s48, s27
	v_add_u32_e32 v218, s24, v168
	v_lshl_add_u64 v[150:151], v[150:151], 0, s[6:7]
	s_mov_b32 m0, s25
	ds_read_b128 v[206:209], v218
	ds_read_b128 v[210:213], v218 offset:1024
	ds_read_b128 v[214:217], v218 offset:2048
	ds_read_b128 v[218:221], v218 offset:3072
	global_load_lds_dwordx4 v[150:151], off
	v_lshl_add_u64 v[150:151], v[166:167], 0, s[6:7]
	s_add_i32 m0, s25, 0x2000
	s_nop 0
	global_load_lds_dwordx4 v[150:151], off
	s_barrier
	s_waitcnt lgkmcnt(0)
	s_setprio 1
	s_waitcnt lgkmcnt(0)
	v_mfma_f32_16x16x32_bf16 v[124:127], v[206:209], v[174:177], v[124:127]
	v_mfma_f32_16x16x32_bf16 v[120:123], v[214:217], v[174:177], v[120:123]
	v_mfma_f32_16x16x32_bf16 v[116:119], v[206:209], v[182:185], v[116:119]
	v_mfma_f32_16x16x32_bf16 v[112:115], v[214:217], v[182:185], v[112:115]
	v_mfma_f32_16x16x32_bf16 v[108:111], v[206:209], v[190:193], v[108:111]
	v_mfma_f32_16x16x32_bf16 v[104:107], v[214:217], v[190:193], v[104:107]
	v_mfma_f32_16x16x32_bf16 v[100:103], v[206:209], v[198:201], v[100:103]
	v_mfma_f32_16x16x32_bf16 v[96:99], v[214:217], v[198:201], v[96:99]
	v_mfma_f32_16x16x32_bf16 v[124:127], v[210:213], v[178:181], v[124:127]
	v_mfma_f32_16x16x32_bf16 v[120:123], v[218:221], v[178:181], v[120:123]
	v_mfma_f32_16x16x32_bf16 v[116:119], v[210:213], v[186:189], v[116:119]
	v_mfma_f32_16x16x32_bf16 v[112:115], v[218:221], v[186:189], v[112:115]
	v_mfma_f32_16x16x32_bf16 v[108:111], v[210:213], v[194:197], v[108:111]
	v_mfma_f32_16x16x32_bf16 v[104:107], v[218:221], v[194:197], v[104:107]
	v_mfma_f32_16x16x32_bf16 v[100:103], v[210:213], v[202:205], v[100:103]
	v_mfma_f32_16x16x32_bf16 v[96:99], v[218:221], v[202:205], v[96:99]
	s_setprio 0
	s_mov_b32 m0, s36
	v_lshl_add_u64 v[150:151], v[222:223], 0, s[6:7]
	s_barrier
	ds_read_b128 v[174:177], v171 offset:49152
	ds_read_b128 v[178:181], v171 offset:50176
	ds_read_b128 v[182:185], v171 offset:51200
	ds_read_b128 v[186:189], v171 offset:52224
	ds_read_b128 v[190:193], v171 offset:53248
	ds_read_b128 v[194:197], v171 offset:54272
	ds_read_b128 v[198:201], v171 offset:55296
	ds_read_b128 v[202:205], v171 offset:56320
	global_load_lds_dwordx4 v[150:151], off
	v_lshl_add_u64 v[150:151], v[224:225], 0, s[6:7]
	s_mov_b32 m0, s37
	s_nop 0
	global_load_lds_dwordx4 v[150:151], off
	s_barrier
; #define PG8_STAGE(bufoff, gbase, voff) do { _Pragma("unroll") for (int _i = 0; _i < 2; ++_i) \
;         __builtin_amdgcn_global_load_lds((const unsigned*)((const char*)(gbase) + (voff)[_i]), (LAS unsigned*)(lds + (bufoff) + ldsw + _i * 8192), 16, 0, 0); } while (0)
; #define PG8_LDA(dst, b, h) do { _Pragma("unroll") for (int m = 0; m < 4; ++m) _Pragma("unroll") for (int k = 0; k < 2; ++k) dst[m][k] = *(const LAS bf16x8*)(lds + PG8_SA(b, h) + aoff + m * 2048 + k * 1024); } while (0)
; #define PG8_LDB(dst, b, h) do { _Pragma("unroll") for (int n = 0; n < 2; ++n) _Pragma("unroll") for (int k = 0; k < 2; ++k) dst[n][k] = *(const LAS bf16x8*)(lds + PG8_SB(b, h) + boff + n * 2048 + k * 1024); } while (0)
; #define PG8_MMA(ai, bj, At, Bt) do { __builtin_amdgcn_s_setprio(1); _Pragma("unroll") for (int m = 0; m < 4; ++m) _Pragma("unroll") for (int n = 0; n < 2; ++n) _Pragma("unroll") for (int k = 0; k < 2; ++k) \
;         acc[ai][bj][m][n] = __builtin_amdgcn_mfma_f32_16x16x32_bf16(Bt[n][k], At[m][k], acc[ai][bj][m][n], 0, 0, 0); __builtin_amdgcn_s_setprio(0); } while (0)
; #define PG8_WAIT_V(n) asm volatile("s_waitcnt vmcnt(" #n ")" ::: "memory")
; #define PG8_WAIT_L(n) asm volatile("s_waitcnt lgkmcnt(" #n ")" ::: "memory")
; #define PG8_BAR __builtin_amdgcn_s_barrier()
; template <class Epi>
; __device__ __forceinline__ void gemm_phase(LAS unsigned char* lds, const Gemm g, const StaticOrder& S, const Epi& E) {
;     ...
;         for (int t = 0; t < nt; t += 2) {
;             const bool last = (t == nt - 2);
;             const char* a1 = cA + (size_t)(t + 1) * kstep;
;             const char* a2 = last ? nA : cA + (size_t)(t + 2) * kstep; const char* b2 = last ? nB : cB + (size_t)(t + 2) * kstep;
;             const char* a3 = a2 + kstep; const char* b3 = b2 + kstep;
;             if (last) E.pre(cur, wr, fr, epre);
;             PG8_LDB(B0, 0, 0); PG8_SCHED; PG8_LDA(At, 0, 0); PG8_STAGE(PG8_SA(1, 1), a1 + hstepA, voffA);
;             PG8_WAIT_L(8); PG8_BAR; PG8_WAIT_L(0); PG8_MMA(0, 0, At, B0); PG8_BAR; PG8_SCHED;
;             PG8_LDB(B1, 0, 1); PG8_STAGE(PG8_SB(0, 0), b2, voffB);
;             PG8_BAR; PG8_WAIT_L(0); PG8_MMA(0, 1, At, B1); PG8_BAR;
;     ...
;             PG8_BAR; PG8_WAIT_L(0); PG8_MMA(1, 0, At, B0); PG8_BAR; PG8_SCHED;
;             PG8_STAGE(PG8_SB(1, 1), b3 + hstepB, voffB);
;             PG8_WAIT_V(6); PG8_BAR; PG8_MMA(1, 1, At, B1); PG8_BAR;
	s_waitcnt lgkmcnt(0)
	s_setprio 1
	s_waitcnt lgkmcnt(0)
	v_mfma_f32_16x16x32_bf16 v[28:31], v[146:149], v[174:177], v[28:31]
	v_mfma_f32_16x16x32_bf16 v[24:27], v[158:161], v[174:177], v[24:27]
	v_mfma_f32_16x16x32_bf16 v[20:23], v[146:149], v[182:185], v[20:23]
	v_mfma_f32_16x16x32_bf16 v[16:19], v[158:161], v[182:185], v[16:19]
	v_mfma_f32_16x16x32_bf16 v[12:15], v[146:149], v[190:193], v[12:15]
	v_mfma_f32_16x16x32_bf16 v[8:11], v[158:161], v[190:193], v[8:11]
	v_mfma_f32_16x16x32_bf16 v[4:7], v[146:149], v[198:201], v[4:7]
	v_mfma_f32_16x16x32_bf16 v[0:3], v[158:161], v[198:201], v[0:3]
	v_mfma_f32_16x16x32_bf16 v[28:31], v[154:157], v[178:181], v[28:31]
	v_mfma_f32_16x16x32_bf16 v[24:27], v[162:165], v[178:181], v[24:27]
	v_mfma_f32_16x16x32_bf16 v[20:23], v[154:157], v[186:189], v[20:23]
	v_mfma_f32_16x16x32_bf16 v[16:19], v[162:165], v[186:189], v[16:19]
	v_mfma_f32_16x16x32_bf16 v[12:15], v[154:157], v[194:197], v[12:15]
	v_mfma_f32_16x16x32_bf16 v[8:11], v[162:165], v[194:197], v[8:11]
	v_mfma_f32_16x16x32_bf16 v[4:7], v[154:157], v[202:205], v[4:7]
	v_mfma_f32_16x16x32_bf16 v[0:3], v[162:165], v[202:205], v[0:3]
	s_setprio 0
	s_barrier
	s_add_u32 s22, s22, 0x40080
	s_addc_u32 s23, s23, 0
	s_add_i32 s24, s24, s27
	v_lshl_add_u64 v[146:147], s[22:23], 0, v[132:133]
	s_mov_b32 m0, s24
	s_nop 0
	global_load_lds_dwordx4 v[146:147], off
	v_lshl_add_u64 v[146:147], s[22:23], 0, v[128:129]
	s_add_i32 m0, s24, 0x2000
	s_nop 0
	global_load_lds_dwordx4 v[146:147], off
	s_waitcnt vmcnt(6)
	s_barrier
	s_setprio 1
	v_mfma_f32_16x16x32_bf16 v[92:95], v[206:209], v[174:177], v[92:95]
	v_mfma_f32_16x16x32_bf16 v[88:91], v[214:217], v[174:177], v[88:91]
	v_mfma_f32_16x16x32_bf16 v[84:87], v[206:209], v[182:185], v[84:87]
	v_mfma_f32_16x16x32_bf16 v[80:83], v[214:217], v[182:185], v[80:83]
	v_mfma_f32_16x16x32_bf16 v[72:75], v[206:209], v[190:193], v[72:75]
	v_mfma_f32_16x16x32_bf16 v[68:71], v[214:217], v[190:193], v[68:71]
	v_mfma_f32_16x16x32_bf16 v[52:55], v[206:209], v[198:201], v[52:55]
	v_mfma_f32_16x16x32_bf16 v[44:47], v[214:217], v[198:201], v[44:47]
	v_mfma_f32_16x16x32_bf16 v[92:95], v[210:213], v[178:181], v[92:95]
	v_mfma_f32_16x16x32_bf16 v[88:91], v[218:221], v[178:181], v[88:91]
	v_mfma_f32_16x16x32_bf16 v[84:87], v[210:213], v[186:189], v[84:87]
	v_mfma_f32_16x16x32_bf16 v[80:83], v[218:221], v[186:189], v[80:83]
	v_mfma_f32_16x16x32_bf16 v[72:75], v[210:213], v[194:197], v[72:75]
	v_mfma_f32_16x16x32_bf16 v[68:71], v[218:221], v[194:197], v[68:71]
	v_mfma_f32_16x16x32_bf16 v[52:55], v[210:213], v[202:205], v[52:55]
	v_mfma_f32_16x16x32_bf16 v[44:47], v[218:221], v[202:205], v[44:47]
	s_setprio 0
	s_add_i32 s47, s47, 2
	s_add_u32 s20, s20, 0x100
	s_addc_u32 s21, s21, 0
	s_add_u32 s45, s45, 0x100
	s_addc_u32 s46, s46, 0
	s_cmp_gt_u32 s47, 13
	s_barrier
.LBB0_205:
	ds_read_b128 v[146:149], v170
	ds_read_b128 v[154:157], v170 offset:1024
	ds_read_b128 v[158:161], v170 offset:2048
	ds_read_b128 v[162:165], v170 offset:3072
	s_add_u32 s22, s20, 0xfffc0080
	s_addc_u32 s23, s21, -1
	s_cmp_eq_u32 s47, 12
	s_cselect_b32 s25, s13, s23
	s_cselect_b32 s24, s19, s22
	s_cselect_b32 s23, s11, s46
	s_cselect_b32 s22, s44, s45
	v_lshl_add_u64 v[150:151], s[20:21], 0, v[138:139]
	s_add_i32 m0, s30, 0xc000
	ds_read_b128 v[174:177], v171
	ds_read_b128 v[178:181], v171 offset:1024
	ds_read_b128 v[182:185], v171 offset:2048
	ds_read_b128 v[186:189], v171 offset:3072
	ds_read_b128 v[190:193], v171 offset:4096
	ds_read_b128 v[194:197], v171 offset:5120
	ds_read_b128 v[198:201], v171 offset:6144
	ds_read_b128 v[202:205], v171 offset:7168
	global_load_lds_dwordx4 v[150:151], off
	v_lshl_add_u64 v[150:151], s[20:21], 0, v[140:141]
	s_add_i32 m0, s30, 0xe000
	s_nop 0
	global_load_lds_dwordx4 v[150:151], off
	s_waitcnt lgkmcnt(8)
	s_barrier
	s_waitcnt lgkmcnt(0)
	s_setprio 1
	s_waitcnt lgkmcnt(0)
	v_mfma_f32_16x16x32_bf16 v[76:79], v[146:149], v[174:177], v[76:79]
	v_mfma_f32_16x16x32_bf16 v[64:67], v[158:161], v[174:177], v[64:67]
	v_mfma_f32_16x16x32_bf16 v[60:63], v[146:149], v[182:185], v[60:63]
	v_mfma_f32_16x16x32_bf16 v[56:59], v[158:161], v[182:185], v[56:59]
	v_mfma_f32_16x16x32_bf16 v[48:51], v[146:149], v[190:193], v[48:51]
	v_mfma_f32_16x16x32_bf16 v[40:43], v[158:161], v[190:193], v[40:43]
	v_mfma_f32_16x16x32_bf16 v[36:39], v[146:149], v[198:201], v[36:39]
	v_mfma_f32_16x16x32_bf16 v[32:35], v[158:161], v[198:201], v[32:35]
	v_mfma_f32_16x16x32_bf16 v[76:79], v[154:157], v[178:181], v[76:79]
	v_mfma_f32_16x16x32_bf16 v[64:67], v[162:165], v[178:181], v[64:67]
	v_mfma_f32_16x16x32_bf16 v[60:63], v[154:157], v[186:189], v[60:63]
	v_mfma_f32_16x16x32_bf16 v[56:59], v[162:165], v[186:189], v[56:59]
	v_mfma_f32_16x16x32_bf16 v[48:51], v[154:157], v[194:197], v[48:51]
	v_mfma_f32_16x16x32_bf16 v[40:43], v[162:165], v[194:197], v[40:43]
	v_mfma_f32_16x16x32_bf16 v[36:39], v[154:157], v[202:205], v[36:39]
	v_mfma_f32_16x16x32_bf16 v[32:35], v[162:165], v[202:205], v[32:35]
	s_setprio 0
	s_barrier
	s_add_i32 s48, s39, s27
	v_lshl_add_u64 v[150:151], s[22:23], 0, v[132:133]
	s_mov_b32 m0, s48
	ds_read_b128 v[206:209], v172
	ds_read_b128 v[210:213], v172 offset:1024
	ds_read_b128 v[214:217], v172 offset:2048
	ds_read_b128 v[218:221], v172 offset:3072
	global_load_lds_dwordx4 v[150:151], off
	v_lshl_add_u64 v[166:167], s[22:23], 0, v[128:129]
	s_add_i32 m0, s48, 0x2000
	s_nop 0
	global_load_lds_dwordx4 v[166:167], off
	s_barrier
; #define PG8_STAGE(bufoff, gbase, voff) do { _Pragma("unroll") for (int _i = 0; _i < 2; ++_i) \
;         __builtin_amdgcn_global_load_lds((const unsigned*)((const char*)(gbase) + (voff)[_i]), (LAS unsigned*)(lds + (bufoff) + ldsw + _i * 8192), 16, 0, 0); } while (0)
; #define PG8_LDA(dst, b, h) do { _Pragma("unroll") for (int m = 0; m < 4; ++m) _Pragma("unroll") for (int k = 0; k < 2; ++k) dst[m][k] = *(const LAS bf16x8*)(lds + PG8_SA(b, h) + aoff + m * 2048 + k * 1024); } while (0)
; #define PG8_LDB(dst, b, h) do { _Pragma("unroll") for (int n = 0; n < 2; ++n) _Pragma("unroll") for (int k = 0; k < 2; ++k) dst[n][k] = *(const LAS bf16x8*)(lds + PG8_SB(b, h) + boff + n * 2048 + k * 1024); } while (0)
; #define PG8_MMA(ai, bj, At, Bt) do { __builtin_amdgcn_s_setprio(1); _Pragma("unroll") for (int m = 0; m < 4; ++m) _Pragma("unroll") for (int n = 0; n < 2; ++n) _Pragma("unroll") for (int k = 0; k < 2; ++k) \
;         acc[ai][bj][m][n] = __builtin_amdgcn_mfma_f32_16x16x32_bf16(Bt[n][k], At[m][k], acc[ai][bj][m][n], 0, 0, 0); __builtin_amdgcn_s_setprio(0); } while (0)
; #define PG8_WAIT_V(n) asm volatile("s_waitcnt vmcnt(" #n ")" ::: "memory")
; #define PG8_WAIT_L(n) asm volatile("s_waitcnt lgkmcnt(" #n ")" ::: "memory")
; #define PG8_BAR __builtin_amdgcn_s_barrier()
; #define PG8_SCHED __builtin_amdgcn_sched_barrier(0)
; template <class Epi>
; __device__ __forceinline__ void gemm_phase(LAS unsigned char* lds, const Gemm g, const StaticOrder& S, const Epi& E) {
;     ...
;             PG8_BAR; PG8_WAIT_L(0); PG8_MMA(0, 1, At, B1); PG8_BAR;
;             PG8_LDA(At, 0, 1); PG8_STAGE(PG8_SA(0, 0), a2, voffA);
;             PG8_BAR; PG8_WAIT_L(0); PG8_MMA(1, 0, At, B0); PG8_BAR; PG8_SCHED;
;             PG8_STAGE(PG8_SB(0, 1), b2 + hstepB, voffB);
;             PG8_WAIT_V(6); PG8_BAR; PG8_MMA(1, 1, At, B1); PG8_BAR;
;             PG8_LDB(B0, 1, 0); PG8_SCHED; PG8_LDA(At, 1, 0); PG8_STAGE(PG8_SA(0, 1), a2 + hstepA, voffA);
;             PG8_WAIT_L(8); PG8_BAR; PG8_WAIT_L(0); PG8_MMA(0, 0, At, B0); PG8_BAR; PG8_SCHED;
;             PG8_LDB(B1, 1, 1); PG8_STAGE(PG8_SB(1, 0), b3, voffB);
;             PG8_BAR; PG8_WAIT_L(0); PG8_MMA(0, 1, At, B1); PG8_BAR;
	s_waitcnt lgkmcnt(0)
	s_setprio 1
	s_waitcnt lgkmcnt(0)
	v_mfma_f32_16x16x32_bf16 v[124:127], v[206:209], v[174:177], v[124:127]
	v_mfma_f32_16x16x32_bf16 v[120:123], v[214:217], v[174:177], v[120:123]
	v_mfma_f32_16x16x32_bf16 v[116:119], v[206:209], v[182:185], v[116:119]
	v_mfma_f32_16x16x32_bf16 v[112:115], v[214:217], v[182:185], v[112:115]
	v_mfma_f32_16x16x32_bf16 v[108:111], v[206:209], v[190:193], v[108:111]
	v_mfma_f32_16x16x32_bf16 v[104:107], v[214:217], v[190:193], v[104:107]
	v_mfma_f32_16x16x32_bf16 v[100:103], v[206:209], v[198:201], v[100:103]
	v_mfma_f32_16x16x32_bf16 v[96:99], v[214:217], v[198:201], v[96:99]
	v_mfma_f32_16x16x32_bf16 v[124:127], v[210:213], v[178:181], v[124:127]
	v_mfma_f32_16x16x32_bf16 v[120:123], v[218:221], v[178:181], v[120:123]
	v_mfma_f32_16x16x32_bf16 v[116:119], v[210:213], v[186:189], v[116:119]
	v_mfma_f32_16x16x32_bf16 v[112:115], v[218:221], v[186:189], v[112:115]
	v_mfma_f32_16x16x32_bf16 v[108:111], v[210:213], v[194:197], v[108:111]
	v_mfma_f32_16x16x32_bf16 v[104:107], v[218:221], v[194:197], v[104:107]
	v_mfma_f32_16x16x32_bf16 v[100:103], v[210:213], v[202:205], v[100:103]
	v_mfma_f32_16x16x32_bf16 v[96:99], v[218:221], v[202:205], v[96:99]
	s_setprio 0
	s_mov_b32 m0, s30
	v_lshl_add_u64 v[222:223], s[24:25], 0, v[134:135]
	s_barrier
	ds_read_b128 v[174:177], v171 offset:16384
	ds_read_b128 v[178:181], v171 offset:17408
	ds_read_b128 v[182:185], v171 offset:18432
	ds_read_b128 v[186:189], v171 offset:19456
	ds_read_b128 v[190:193], v171 offset:20480
	ds_read_b128 v[194:197], v171 offset:21504
	ds_read_b128 v[198:201], v171 offset:22528
	ds_read_b128 v[202:205], v171 offset:23552
	global_load_lds_dwordx4 v[222:223], off
	v_lshl_add_u64 v[224:225], s[24:25], 0, v[130:131]
	s_mov_b32 m0, s31
	s_nop 0
	global_load_lds_dwordx4 v[224:225], off
	s_barrier
	s_waitcnt lgkmcnt(0)
	s_setprio 1
	s_waitcnt lgkmcnt(0)
	v_mfma_f32_16x16x32_bf16 v[28:31], v[146:149], v[174:177], v[28:31]
	v_mfma_f32_16x16x32_bf16 v[24:27], v[158:161], v[174:177], v[24:27]
	v_mfma_f32_16x16x32_bf16 v[20:23], v[146:149], v[182:185], v[20:23]
	v_mfma_f32_16x16x32_bf16 v[16:19], v[158:161], v[182:185], v[16:19]
	v_mfma_f32_16x16x32_bf16 v[12:15], v[146:149], v[190:193], v[12:15]
	v_mfma_f32_16x16x32_bf16 v[8:11], v[158:161], v[190:193], v[8:11]
	v_mfma_f32_16x16x32_bf16 v[4:7], v[146:149], v[198:201], v[4:7]
	v_mfma_f32_16x16x32_bf16 v[0:3], v[158:161], v[198:201], v[0:3]
	v_mfma_f32_16x16x32_bf16 v[28:31], v[154:157], v[178:181], v[28:31]
	v_mfma_f32_16x16x32_bf16 v[24:27], v[162:165], v[178:181], v[24:27]
	v_mfma_f32_16x16x32_bf16 v[20:23], v[154:157], v[186:189], v[20:23]
	v_mfma_f32_16x16x32_bf16 v[16:19], v[162:165], v[186:189], v[16:19]
	v_mfma_f32_16x16x32_bf16 v[12:15], v[154:157], v[194:197], v[12:15]
	v_mfma_f32_16x16x32_bf16 v[8:11], v[162:165], v[194:197], v[8:11]
	v_mfma_f32_16x16x32_bf16 v[4:7], v[154:157], v[202:205], v[4:7]
	v_mfma_f32_16x16x32_bf16 v[0:3], v[162:165], v[202:205], v[0:3]
	s_setprio 0
	s_barrier
	s_add_u32 s48, s22, 0x40000
	s_addc_u32 s49, s23, 0
	s_add_i32 s50, s40, s27
	v_lshl_add_u64 v[146:147], s[48:49], 0, v[132:133]
	s_mov_b32 m0, s50
	s_nop 0
	global_load_lds_dwordx4 v[146:147], off
	v_lshl_add_u64 v[146:147], s[48:49], 0, v[128:129]
	s_add_i32 m0, s50, 0x2000
	s_nop 0
	global_load_lds_dwordx4 v[146:147], off
	s_waitcnt vmcnt(6)
	s_barrier
	s_setprio 1
	v_mfma_f32_16x16x32_bf16 v[92:95], v[206:209], v[174:177], v[92:95]
	v_mfma_f32_16x16x32_bf16 v[88:91], v[214:217], v[174:177], v[88:91]
	v_mfma_f32_16x16x32_bf16 v[84:87], v[206:209], v[182:185], v[84:87]
	v_mfma_f32_16x16x32_bf16 v[80:83], v[214:217], v[182:185], v[80:83]
	v_mfma_f32_16x16x32_bf16 v[72:75], v[206:209], v[190:193], v[72:75]
	v_mfma_f32_16x16x32_bf16 v[68:71], v[214:217], v[190:193], v[68:71]
	v_mfma_f32_16x16x32_bf16 v[52:55], v[206:209], v[198:201], v[52:55]
	v_mfma_f32_16x16x32_bf16 v[44:47], v[214:217], v[198:201], v[44:47]
	v_mfma_f32_16x16x32_bf16 v[92:95], v[210:213], v[178:181], v[92:95]
	v_mfma_f32_16x16x32_bf16 v[88:91], v[218:221], v[178:181], v[88:91]
	v_mfma_f32_16x16x32_bf16 v[84:87], v[210:213], v[186:189], v[84:87]
	v_mfma_f32_16x16x32_bf16 v[80:83], v[218:221], v[186:189], v[80:83]
	v_mfma_f32_16x16x32_bf16 v[72:75], v[210:213], v[194:197], v[72:75]
	v_mfma_f32_16x16x32_bf16 v[68:71], v[218:221], v[194:197], v[68:71]
	v_mfma_f32_16x16x32_bf16 v[52:55], v[210:213], v[202:205], v[52:55]
	v_mfma_f32_16x16x32_bf16 v[44:47], v[218:221], v[202:205], v[44:47]
	s_setprio 0
	s_add_i32 s48, 0, 0x18000
	v_add_u32_e32 v162, s48, v168
	s_barrier
	ds_read_b128 v[146:149], v162
	ds_read_b128 v[154:157], v162 offset:1024
	ds_read_b128 v[158:161], v162 offset:2048
	ds_read_b128 v[162:165], v162 offset:3072
	s_add_u32 s24, s24, 0x40000
	s_addc_u32 s25, s25, 0
	s_mov_b32 m0, s33
	v_lshl_add_u64 v[206:207], s[24:25], 0, v[134:135]
	ds_read_b128 v[174:177], v171 offset:32768
	ds_read_b128 v[178:181], v171 offset:33792
	ds_read_b128 v[182:185], v171 offset:34816
	ds_read_b128 v[186:189], v171 offset:35840
	ds_read_b128 v[190:193], v171 offset:36864
	ds_read_b128 v[194:197], v171 offset:37888
	ds_read_b128 v[198:201], v171 offset:38912
	ds_read_b128 v[202:205], v171 offset:39936
	global_load_lds_dwordx4 v[206:207], off
	v_lshl_add_u64 v[206:207], s[24:25], 0, v[130:131]
	s_mov_b32 m0, s34
	s_nop 0
	global_load_lds_dwordx4 v[206:207], off
	s_waitcnt lgkmcnt(8)
	s_barrier
; #define PG8_STAGE(bufoff, gbase, voff) do { _Pragma("unroll") for (int _i = 0; _i < 2; ++_i) \
;         __builtin_amdgcn_global_load_lds((const unsigned*)((const char*)(gbase) + (voff)[_i]), (LAS unsigned*)(lds + (bufoff) + ldsw + _i * 8192), 16, 0, 0); } while (0)
; #define PG8_LDA(dst, b, h) do { _Pragma("unroll") for (int m = 0; m < 4; ++m) _Pragma("unroll") for (int k = 0; k < 2; ++k) dst[m][k] = *(const LAS bf16x8*)(lds + PG8_SA(b, h) + aoff + m * 2048 + k * 1024); } while (0)
; #define PG8_MMA(ai, bj, At, Bt) do { __builtin_amdgcn_s_setprio(1); _Pragma("unroll") for (int m = 0; m < 4; ++m) _Pragma("unroll") for (int n = 0; n < 2; ++n) _Pragma("unroll") for (int k = 0; k < 2; ++k) \
;         acc[ai][bj][m][n] = __builtin_amdgcn_mfma_f32_16x16x32_bf16(Bt[n][k], At[m][k], acc[ai][bj][m][n], 0, 0, 0); __builtin_amdgcn_s_setprio(0); } while (0)
; #define PG8_WAIT_V(n) asm volatile("s_waitcnt vmcnt(" #n ")" ::: "memory")
; #define PG8_WAIT_L(n) asm volatile("s_waitcnt lgkmcnt(" #n ")" ::: "memory")
; #define PG8_BAR __builtin_amdgcn_s_barrier()
; #define PG8_SCHED __builtin_amdgcn_sched_barrier(0)
; template <class Epi>
; __device__ __forceinline__ void gemm_phase(LAS unsigned char* lds, const Gemm g, const StaticOrder& S, const Epi& E) {
;     ...
;             PG8_BAR; PG8_WAIT_L(0); PG8_MMA(0, 1, At, B1); PG8_BAR;
;             PG8_LDA(At, 1, 1); PG8_STAGE(PG8_SA(1, 0), a3, voffA);
;             PG8_BAR; PG8_WAIT_L(0); PG8_MMA(1, 0, At, B0); PG8_BAR; PG8_SCHED;
;             PG8_STAGE(PG8_SB(1, 1), b3 + hstepB, voffB);
;             PG8_WAIT_V(6); PG8_BAR; PG8_MMA(1, 1, At, B1); PG8_BAR;
	s_waitcnt lgkmcnt(0)
	s_setprio 1
	s_waitcnt lgkmcnt(0)
	v_mfma_f32_16x16x32_bf16 v[76:79], v[146:149], v[174:177], v[76:79]
	v_mfma_f32_16x16x32_bf16 v[64:67], v[158:161], v[174:177], v[64:67]
	v_mfma_f32_16x16x32_bf16 v[60:63], v[146:149], v[182:185], v[60:63]
	v_mfma_f32_16x16x32_bf16 v[56:59], v[158:161], v[182:185], v[56:59]
	v_mfma_f32_16x16x32_bf16 v[48:51], v[146:149], v[190:193], v[48:51]
	v_mfma_f32_16x16x32_bf16 v[40:43], v[158:161], v[190:193], v[40:43]
	v_mfma_f32_16x16x32_bf16 v[36:39], v[146:149], v[198:201], v[36:39]
	v_mfma_f32_16x16x32_bf16 v[32:35], v[158:161], v[198:201], v[32:35]
	v_mfma_f32_16x16x32_bf16 v[76:79], v[154:157], v[178:181], v[76:79]
	v_mfma_f32_16x16x32_bf16 v[64:67], v[162:165], v[178:181], v[64:67]
	v_mfma_f32_16x16x32_bf16 v[60:63], v[154:157], v[186:189], v[60:63]
	v_mfma_f32_16x16x32_bf16 v[56:59], v[162:165], v[186:189], v[56:59]
	v_mfma_f32_16x16x32_bf16 v[48:51], v[154:157], v[194:197], v[48:51]
	v_mfma_f32_16x16x32_bf16 v[40:43], v[162:165], v[194:197], v[40:43]
	v_mfma_f32_16x16x32_bf16 v[36:39], v[154:157], v[202:205], v[36:39]
	v_mfma_f32_16x16x32_bf16 v[32:35], v[162:165], v[202:205], v[32:35]
	s_setprio 0
	s_barrier
	s_add_i32 s24, 0, 0x1c000
	s_add_i32 s25, s48, s27
	v_add_u32_e32 v218, s24, v168
	v_lshl_add_u64 v[150:151], v[150:151], 0, s[6:7]
	s_mov_b32 m0, s25
	ds_read_b128 v[206:209], v218
	ds_read_b128 v[210:213], v218 offset:1024
	ds_read_b128 v[214:217], v218 offset:2048
	ds_read_b128 v[218:221], v218 offset:3072
	global_load_lds_dwordx4 v[150:151], off
	v_lshl_add_u64 v[150:151], v[166:167], 0, s[6:7]
	s_add_i32 m0, s25, 0x2000
	s_nop 0
	global_load_lds_dwordx4 v[150:151], off
	s_barrier
	s_waitcnt lgkmcnt(0)
	s_setprio 1
	s_waitcnt lgkmcnt(0)
	v_mfma_f32_16x16x32_bf16 v[124:127], v[206:209], v[174:177], v[124:127]
	v_mfma_f32_16x16x32_bf16 v[120:123], v[214:217], v[174:177], v[120:123]
	v_mfma_f32_16x16x32_bf16 v[116:119], v[206:209], v[182:185], v[116:119]
	v_mfma_f32_16x16x32_bf16 v[112:115], v[214:217], v[182:185], v[112:115]
	v_mfma_f32_16x16x32_bf16 v[108:111], v[206:209], v[190:193], v[108:111]
	v_mfma_f32_16x16x32_bf16 v[104:107], v[214:217], v[190:193], v[104:107]
	v_mfma_f32_16x16x32_bf16 v[100:103], v[206:209], v[198:201], v[100:103]
	v_mfma_f32_16x16x32_bf16 v[96:99], v[214:217], v[198:201], v[96:99]
	v_mfma_f32_16x16x32_bf16 v[124:127], v[210:213], v[178:181], v[124:127]
	v_mfma_f32_16x16x32_bf16 v[120:123], v[218:221], v[178:181], v[120:123]
	v_mfma_f32_16x16x32_bf16 v[116:119], v[210:213], v[186:189], v[116:119]
	v_mfma_f32_16x16x32_bf16 v[112:115], v[218:221], v[186:189], v[112:115]
	v_mfma_f32_16x16x32_bf16 v[108:111], v[210:213], v[194:197], v[108:111]
	v_mfma_f32_16x16x32_bf16 v[104:107], v[218:221], v[194:197], v[104:107]
	v_mfma_f32_16x16x32_bf16 v[100:103], v[210:213], v[202:205], v[100:103]
	v_mfma_f32_16x16x32_bf16 v[96:99], v[218:221], v[202:205], v[96:99]
	s_setprio 0
	s_mov_b32 m0, s36
	v_lshl_add_u64 v[150:151], v[222:223], 0, s[6:7]
	s_barrier
	ds_read_b128 v[174:177], v171 offset:49152
	ds_read_b128 v[178:181], v171 offset:50176
	ds_read_b128 v[182:185], v171 offset:51200
	ds_read_b128 v[186:189], v171 offset:52224
	ds_read_b128 v[190:193], v171 offset:53248
	ds_read_b128 v[194:197], v171 offset:54272
	ds_read_b128 v[198:201], v171 offset:55296
	ds_read_b128 v[202:205], v171 offset:56320
	global_load_lds_dwordx4 v[150:151], off
	v_lshl_add_u64 v[150:151], v[224:225], 0, s[6:7]
	s_mov_b32 m0, s37
	s_nop 0
	global_load_lds_dwordx4 v[150:151], off
	s_barrier
	s_waitcnt lgkmcnt(0)
	s_setprio 1
	s_waitcnt lgkmcnt(0)
	v_mfma_f32_16x16x32_bf16 v[28:31], v[146:149], v[174:177], v[28:31]
	v_mfma_f32_16x16x32_bf16 v[24:27], v[158:161], v[174:177], v[24:27]
	v_mfma_f32_16x16x32_bf16 v[20:23], v[146:149], v[182:185], v[20:23]
	v_mfma_f32_16x16x32_bf16 v[16:19], v[158:161], v[182:185], v[16:19]
	v_mfma_f32_16x16x32_bf16 v[12:15], v[146:149], v[190:193], v[12:15]
	v_mfma_f32_16x16x32_bf16 v[8:11], v[158:161], v[190:193], v[8:11]
	v_mfma_f32_16x16x32_bf16 v[4:7], v[146:149], v[198:201], v[4:7]
	v_mfma_f32_16x16x32_bf16 v[0:3], v[158:161], v[198:201], v[0:3]
	v_mfma_f32_16x16x32_bf16 v[28:31], v[154:157], v[178:181], v[28:31]
	v_mfma_f32_16x16x32_bf16 v[24:27], v[162:165], v[178:181], v[24:27]
	v_mfma_f32_16x16x32_bf16 v[20:23], v[154:157], v[186:189], v[20:23]
	v_mfma_f32_16x16x32_bf16 v[16:19], v[162:165], v[186:189], v[16:19]
	v_mfma_f32_16x16x32_bf16 v[12:15], v[154:157], v[194:197], v[12:15]
	v_mfma_f32_16x16x32_bf16 v[8:11], v[162:165], v[194:197], v[8:11]
	v_mfma_f32_16x16x32_bf16 v[4:7], v[154:157], v[202:205], v[4:7]
	v_mfma_f32_16x16x32_bf16 v[0:3], v[162:165], v[202:205], v[0:3]
	s_setprio 0
	s_barrier
	s_add_u32 s22, s22, 0x40080
	s_addc_u32 s23, s23, 0
	s_add_i32 s24, s24, s27
	v_lshl_add_u64 v[146:147], s[22:23], 0, v[132:133]
	s_mov_b32 m0, s24
	s_nop 0
	global_load_lds_dwordx4 v[146:147], off
	v_lshl_add_u64 v[146:147], s[22:23], 0, v[128:129]
	s_add_i32 m0, s24, 0x2000
	s_nop 0
	global_load_lds_dwordx4 v[146:147], off
	s_waitcnt vmcnt(6)
	s_barrier
; __device__ __forceinline__ unsigned pk2(float lo, float hi) { const f32x2 v = (f32x2){lo, hi}; const bf16x2_t b = __builtin_convertvector(v, bf16x2_t); return __builtin_bit_cast(unsigned, b); }
; #define PG8_STAGE(bufoff, gbase, voff) do { _Pragma("unroll") for (int _i = 0; _i < 2; ++_i) \
;         __builtin_amdgcn_global_load_lds((const unsigned*)((const char*)(gbase) + (voff)[_i]), (LAS unsigned*)(lds + (bufoff) + ldsw + _i * 8192), 16, 0, 0); } while (0)
; #define PG8_BAR __builtin_amdgcn_s_barrier()
;     __device__ __forceinline__ void operator()(const f32x4 (&acc)[2][2][4][2], const Unit& u, int wr, int wc, int fr, int fq, const float (&)[8]) const {
;     ...
;         const int col0 = u.pn * BM + wc * 32 + 8 * fq;
; #pragma unroll
;         for (int ai = 0; ai < 2; ++ai)
; #pragma unroll
;             for (int m = 0; m < 4; ++m) { const int row = row0 + ai * HALF + m * 16; const float rs = rsqrtf(ep[ai * 4 + m] * (1.0f / 1024.0f) + EPS);
;                 u16* rowp = O + (size_t)row * ldc + col0;
; #pragma unroll
;                 for (int bj = 0; bj < 2; ++bj) { f32x4 v0 = acc[ai][bj][m][0] * rs, v1 = acc[ai][bj][m][1] * rs;
;                     if (ACT == 1) {
; #pragma unroll
;                         for (int j = 0; j < 4; ++j) { const float a0 = fmaxf(v0[j], 0.f), a1 = fmaxf(v1[j], 0.f); v0[j] = a0 * a0; v1[j] = a1 * a1; } }
;                     u32x4 w; w.x = pk2(v0[0], v0[1]); w.y = pk2(v0[2], v0[3]); w.z = pk2(v1[0], v1[1]); w.w = pk2(v1[2], v1[3]);
;                     *(u32x4*)(rowp + bj * HALF) = w; } }
; template <class Epi>
; __device__ __forceinline__ void gemm_phase(LAS unsigned char* lds, const Gemm g, const StaticOrder& S, const Epi& E) {
;     ...
;             PG8_WAIT_V(6); PG8_BAR; PG8_MMA(1, 1, At, B1); PG8_BAR;
;             PG8_LDB(B0, 1, 0); PG8_SCHED; PG8_LDA(At, 1, 0); PG8_STAGE(PG8_SA(0, 1), a2 + hstepA, voffA);
;             PG8_WAIT_L(8); PG8_BAR; PG8_WAIT_L(0); PG8_MMA(0, 0, At, B0); PG8_BAR; PG8_SCHED;
;             PG8_LDB(B1, 1, 1); PG8_STAGE(PG8_SB(1, 0), b3, voffB);
;             PG8_BAR; PG8_WAIT_L(0); PG8_MMA(0, 1, At, B1); PG8_BAR;
;             PG8_LDA(At, 1, 1); PG8_STAGE(PG8_SA(1, 0), a3, voffA);
;             PG8_BAR; PG8_WAIT_L(0); PG8_MMA(1, 0, At, B0); PG8_BAR; PG8_SCHED;
;             PG8_STAGE(PG8_SB(1, 1), b3 + hstepB, voffB);
;             PG8_WAIT_V(6); PG8_BAR; PG8_MMA(1, 1, At, B1); PG8_BAR;
	s_setprio 1
	v_mfma_f32_16x16x32_bf16 v[92:95], v[206:209], v[174:177], v[92:95]
	v_mfma_f32_16x16x32_bf16 v[88:91], v[214:217], v[174:177], v[88:91]
	v_mfma_f32_16x16x32_bf16 v[84:87], v[206:209], v[182:185], v[84:87]
	v_mfma_f32_16x16x32_bf16 v[80:83], v[214:217], v[182:185], v[80:83]
	v_mfma_f32_16x16x32_bf16 v[72:75], v[206:209], v[190:193], v[72:75]
	v_mfma_f32_16x16x32_bf16 v[68:71], v[214:217], v[190:193], v[68:71]
	v_mfma_f32_16x16x32_bf16 v[52:55], v[206:209], v[198:201], v[52:55]
	v_mfma_f32_16x16x32_bf16 v[44:47], v[214:217], v[198:201], v[44:47]
	v_mfma_f32_16x16x32_bf16 v[92:95], v[210:213], v[178:181], v[92:95]
	v_mfma_f32_16x16x32_bf16 v[88:91], v[218:221], v[178:181], v[88:91]
	v_mfma_f32_16x16x32_bf16 v[84:87], v[210:213], v[186:189], v[84:87]
	v_mfma_f32_16x16x32_bf16 v[80:83], v[218:221], v[186:189], v[80:83]
	v_mfma_f32_16x16x32_bf16 v[72:75], v[210:213], v[194:197], v[72:75]
	v_mfma_f32_16x16x32_bf16 v[68:71], v[218:221], v[194:197], v[68:71]
	v_mfma_f32_16x16x32_bf16 v[52:55], v[210:213], v[202:205], v[52:55]
	v_mfma_f32_16x16x32_bf16 v[44:47], v[218:221], v[202:205], v[44:47]
	s_setprio 0
	s_add_i32 s47, s47, 2
	s_add_u32 s20, s20, 0x100
	s_addc_u32 s21, s21, 0
	s_add_u32 s45, s45, 0x100
	s_addc_u32 s46, s46, 0
	s_cmp_gt_u32 s47, 13
	s_barrier
	s_cbranch_scc0 .LBB0_205
	s_bfe_u32 vcc_lo, s18, 0x20003
	s_lshl_b32 vcc_lo, vcc_lo, 10
	s_add_i32 vcc_lo, vcc_lo, 0x20010
	v_lshl_add_u32 v236, v153, 2, vcc_lo
	ds_read_b32 v228, v236
	ds_read_b32 v229, v236 offset:64
	ds_read_b32 v230, v236 offset:128
	ds_read_b32 v231, v236 offset:192
	ds_read_b32 v232, v236 offset:512
	ds_read_b32 v233, v236 offset:576
	ds_read_b32 v234, v236 offset:640
	ds_read_b32 v235, v236 offset:704
	s_waitcnt lgkmcnt(0)
	s_add_u32 vcc_lo, s19, 0x40080
	s_addc_u32 vcc_hi, s13, 0
	s_add_i32 m0, s30, 0xc000
	v_lshl_add_u64 v[236:237], vcc, 0, v[138:139]
	v_lshl_add_u64 v[238:239], vcc, 0, v[140:141]
	global_load_lds_dwordx4 v[236:237], off
	s_add_i32 m0, s30, 0xe000
	s_nop 0
	global_load_lds_dwordx4 v[238:239], off
	v_lshl_add_u32 v162, s18, 8, v153
	v_ashrrev_i32_e32 v163, 31, v162
	v_or_b32_e32 v160, 16, v162
	v_or_b32_e32 v158, 32, v162
	v_or_b32_e32 v156, 48, v162
	v_ashrrev_i32_e32 v161, 31, v160
	v_ashrrev_i32_e32 v159, 31, v158
	v_ashrrev_i32_e32 v157, 31, v156
	v_add_u32_e32 v154, 0x80, v162
	v_add_u32_e32 v150, 0x90, v162
	v_add_u32_e32 v148, 0xa0, v162
	v_add_u32_e32 v146, 0xb0, v162
	v_ashrrev_i32_e32 v155, 31, v154
	v_ashrrev_i32_e32 v151, 31, v150
	v_ashrrev_i32_e32 v149, 31, v148
	v_ashrrev_i32_e32 v147, 31, v146
	s_cmp_lg_u32 s43, 20
	s_mov_b64 s[18:19], -1
	s_cbranch_scc0 .LBB0_208
	s_waitcnt vmcnt(10)
	v_lshl_or_b32 v166, s43, 8, v169
	v_ashrrev_i32_e32 v167, 31, v166
	v_lshlrev_b64 v[166:167], 1, v[166:167]
	v_mov_b32_e32 v186, v228
	v_mov_b64_e32 v[164:165], s[96:97]
	v_mad_i64_i32 v[182:183], s[18:19], v162, s42, v[164:165]
	v_lshl_add_u64 v[188:189], v[182:183], 0, v[166:167]
	v_pk_mul_f32 v[184:185], v[78:79], v[186:187] op_sel_hi:[1,0]
	v_pk_mul_f32 v[182:183], v[76:77], v[186:187] op_sel_hi:[1,0]
	v_pk_mul_f32 v[190:191], v[66:67], v[186:187] op_sel_hi:[1,0]
	v_pk_mul_f32 v[192:193], v[64:65], v[186:187] op_sel_hi:[1,0]
	v_cvt_pk_bf16_f32 v182, v182, v183
	v_cvt_pk_bf16_f32 v183, v184, v185
	v_cvt_pk_bf16_f32 v184, v192, v193
	v_cvt_pk_bf16_f32 v185, v190, v191
	v_pk_mul_f32 v[124:125], v[124:125], v[186:187] op_sel_hi:[1,0]
	global_store_dwordx4 v[188:189], v[182:185], off
	v_pk_mul_f32 v[126:127], v[126:127], v[186:187] op_sel_hi:[1,0]
	s_nop 0
	v_pk_mul_f32 v[182:183], v[122:123], v[186:187] op_sel_hi:[1,0]
	v_pk_mul_f32 v[122:123], v[120:121], v[186:187] op_sel_hi:[1,0]
	v_cvt_pk_bf16_f32 v120, v124, v125
	v_cvt_pk_bf16_f32 v121, v126, v127
	v_cvt_pk_bf16_f32 v122, v122, v123
	v_cvt_pk_bf16_f32 v123, v182, v183
	global_store_dwordx4 v[188:189], v[120:123], off offset:256
	s_nop 1
	v_mov_b32_e32 v124, v229
	v_mad_i64_i32 v[120:121], s[18:19], v160, s42, v[164:165]
	v_lshl_add_u64 v[126:127], v[120:121], 0, v[166:167]
	v_pk_mul_f32 v[122:123], v[62:63], v[124:125] op_sel_hi:[1,0]
	v_pk_mul_f32 v[120:121], v[60:61], v[124:125] op_sel_hi:[1,0]
	v_pk_mul_f32 v[182:183], v[58:59], v[124:125] op_sel_hi:[1,0]
	v_pk_mul_f32 v[184:185], v[56:57], v[124:125] op_sel_hi:[1,0]
	v_cvt_pk_bf16_f32 v120, v120, v121
	v_cvt_pk_bf16_f32 v121, v122, v123
	v_cvt_pk_bf16_f32 v122, v184, v185
	v_cvt_pk_bf16_f32 v123, v182, v183
	v_pk_mul_f32 v[116:117], v[116:117], v[124:125] op_sel_hi:[1,0]
	global_store_dwordx4 v[126:127], v[120:123], off
	v_pk_mul_f32 v[118:119], v[118:119], v[124:125] op_sel_hi:[1,0]
	s_nop 0
	v_pk_mul_f32 v[120:121], v[114:115], v[124:125] op_sel_hi:[1,0]
	v_pk_mul_f32 v[114:115], v[112:113], v[124:125] op_sel_hi:[1,0]
	v_cvt_pk_bf16_f32 v112, v116, v117
	v_cvt_pk_bf16_f32 v113, v118, v119
	v_cvt_pk_bf16_f32 v114, v114, v115
	v_cvt_pk_bf16_f32 v115, v120, v121
	global_store_dwordx4 v[126:127], v[112:115], off offset:256
	s_nop 1
	v_mov_b32_e32 v116, v230
	v_mad_i64_i32 v[112:113], s[18:19], v158, s42, v[164:165]
	v_lshl_add_u64 v[118:119], v[112:113], 0, v[166:167]
	v_pk_mul_f32 v[114:115], v[50:51], v[116:117] op_sel_hi:[1,0]
	v_pk_mul_f32 v[112:113], v[48:49], v[116:117] op_sel_hi:[1,0]
	v_pk_mul_f32 v[120:121], v[42:43], v[116:117] op_sel_hi:[1,0]
	v_pk_mul_f32 v[122:123], v[40:41], v[116:117] op_sel_hi:[1,0]
	v_cvt_pk_bf16_f32 v112, v112, v113
	v_cvt_pk_bf16_f32 v113, v114, v115
	v_cvt_pk_bf16_f32 v114, v122, v123
	v_cvt_pk_bf16_f32 v115, v120, v121
	v_pk_mul_f32 v[108:109], v[108:109], v[116:117] op_sel_hi:[1,0]
	global_store_dwordx4 v[118:119], v[112:115], off
	v_pk_mul_f32 v[110:111], v[110:111], v[116:117] op_sel_hi:[1,0]
; __device__ __forceinline__ unsigned pk2(float lo, float hi) { const f32x2 v = (f32x2){lo, hi}; const bf16x2_t b = __builtin_convertvector(v, bf16x2_t); return __builtin_bit_cast(unsigned, b); }
;     __device__ __forceinline__ void operator()(const f32x4 (&acc)[2][2][4][2], const Unit& u, int wr, int wc, int fr, int fq, const float (&)[8]) const {
;     ...
;             for (int m = 0; m < 4; ++m) { const int row = row0 + ai * HALF + m * 16; const float rs = rsqrtf(ep[ai * 4 + m] * (1.0f / 1024.0f) + EPS);
;                 u16* rowp = O + (size_t)row * ldc + col0;
; #pragma unroll
;                 for (int bj = 0; bj < 2; ++bj) { f32x4 v0 = acc[ai][bj][m][0] * rs, v1 = acc[ai][bj][m][1] * rs;
;                     if (ACT == 1) {
; #pragma unroll
;                         for (int j = 0; j < 4; ++j) { const float a0 = fmaxf(v0[j], 0.f), a1 = fmaxf(v1[j], 0.f); v0[j] = a0 * a0; v1[j] = a1 * a1; } }
;                     u32x4 w; w.x = pk2(v0[0], v0[1]); w.y = pk2(v0[2], v0[3]); w.z = pk2(v1[0], v1[1]); w.w = pk2(v1[2], v1[3]);
;                     *(u32x4*)(rowp + bj * HALF) = w; } }
	s_nop 0
	v_pk_mul_f32 v[112:113], v[106:107], v[116:117] op_sel_hi:[1,0]
	v_pk_mul_f32 v[106:107], v[104:105], v[116:117] op_sel_hi:[1,0]
	v_cvt_pk_bf16_f32 v104, v108, v109
	v_cvt_pk_bf16_f32 v105, v110, v111
	v_cvt_pk_bf16_f32 v106, v106, v107
	v_cvt_pk_bf16_f32 v107, v112, v113
	global_store_dwordx4 v[118:119], v[104:107], off offset:256
	s_nop 1
	v_mov_b32_e32 v108, v231
	v_mad_i64_i32 v[104:105], s[18:19], v156, s42, v[164:165]
	v_lshl_add_u64 v[110:111], v[104:105], 0, v[166:167]
	v_pk_mul_f32 v[106:107], v[38:39], v[108:109] op_sel_hi:[1,0]
	v_pk_mul_f32 v[104:105], v[36:37], v[108:109] op_sel_hi:[1,0]
	v_pk_mul_f32 v[112:113], v[34:35], v[108:109] op_sel_hi:[1,0]
	v_pk_mul_f32 v[114:115], v[32:33], v[108:109] op_sel_hi:[1,0]
	v_cvt_pk_bf16_f32 v104, v104, v105
	v_cvt_pk_bf16_f32 v105, v106, v107
	v_cvt_pk_bf16_f32 v106, v114, v115
	v_cvt_pk_bf16_f32 v107, v112, v113
	v_pk_mul_f32 v[100:101], v[100:101], v[108:109] op_sel_hi:[1,0]
	global_store_dwordx4 v[110:111], v[104:107], off
	v_pk_mul_f32 v[102:103], v[102:103], v[108:109] op_sel_hi:[1,0]
	s_nop 0
	v_pk_mul_f32 v[104:105], v[98:99], v[108:109] op_sel_hi:[1,0]
	v_pk_mul_f32 v[98:99], v[96:97], v[108:109] op_sel_hi:[1,0]
	v_cvt_pk_bf16_f32 v96, v100, v101
	v_cvt_pk_bf16_f32 v97, v102, v103
	v_cvt_pk_bf16_f32 v98, v98, v99
	v_cvt_pk_bf16_f32 v99, v104, v105
	global_store_dwordx4 v[110:111], v[96:99], off offset:256
	s_nop 1
	v_mov_b32_e32 v100, v232
	v_mad_i64_i32 v[96:97], s[18:19], v154, s42, v[164:165]
	v_lshl_add_u64 v[102:103], v[96:97], 0, v[166:167]
	v_pk_mul_f32 v[98:99], v[30:31], v[100:101] op_sel_hi:[1,0]
	v_pk_mul_f32 v[96:97], v[28:29], v[100:101] op_sel_hi:[1,0]
	v_pk_mul_f32 v[104:105], v[26:27], v[100:101] op_sel_hi:[1,0]
	v_pk_mul_f32 v[106:107], v[24:25], v[100:101] op_sel_hi:[1,0]
	v_cvt_pk_bf16_f32 v96, v96, v97
	v_cvt_pk_bf16_f32 v97, v98, v99
	v_cvt_pk_bf16_f32 v98, v106, v107
	v_cvt_pk_bf16_f32 v99, v104, v105
	v_pk_mul_f32 v[92:93], v[92:93], v[100:101] op_sel_hi:[1,0]
	global_store_dwordx4 v[102:103], v[96:99], off
	v_pk_mul_f32 v[94:95], v[94:95], v[100:101] op_sel_hi:[1,0]
	s_nop 0
	v_pk_mul_f32 v[96:97], v[90:91], v[100:101] op_sel_hi:[1,0]
	v_pk_mul_f32 v[90:91], v[88:89], v[100:101] op_sel_hi:[1,0]
	v_cvt_pk_bf16_f32 v88, v92, v93
	v_cvt_pk_bf16_f32 v89, v94, v95
	v_cvt_pk_bf16_f32 v90, v90, v91
	v_cvt_pk_bf16_f32 v91, v96, v97
	global_store_dwordx4 v[102:103], v[88:91], off offset:256
	s_nop 1
	v_mov_b32_e32 v92, v233
	v_mad_i64_i32 v[88:89], s[18:19], v150, s42, v[164:165]
	v_lshl_add_u64 v[94:95], v[88:89], 0, v[166:167]
	v_pk_mul_f32 v[90:91], v[22:23], v[92:93] op_sel_hi:[1,0]
	v_pk_mul_f32 v[88:89], v[20:21], v[92:93] op_sel_hi:[1,0]
	v_pk_mul_f32 v[96:97], v[18:19], v[92:93] op_sel_hi:[1,0]
	v_pk_mul_f32 v[98:99], v[16:17], v[92:93] op_sel_hi:[1,0]
	v_cvt_pk_bf16_f32 v88, v88, v89
	v_cvt_pk_bf16_f32 v89, v90, v91
	v_cvt_pk_bf16_f32 v90, v98, v99
	v_cvt_pk_bf16_f32 v91, v96, v97
	v_pk_mul_f32 v[84:85], v[84:85], v[92:93] op_sel_hi:[1,0]
	global_store_dwordx4 v[94:95], v[88:91], off
	v_pk_mul_f32 v[86:87], v[86:87], v[92:93] op_sel_hi:[1,0]
	s_nop 0
	v_pk_mul_f32 v[88:89], v[82:83], v[92:93] op_sel_hi:[1,0]
	v_pk_mul_f32 v[82:83], v[80:81], v[92:93] op_sel_hi:[1,0]
	v_cvt_pk_bf16_f32 v80, v84, v85
	v_cvt_pk_bf16_f32 v81, v86, v87
	v_cvt_pk_bf16_f32 v82, v82, v83
	v_cvt_pk_bf16_f32 v83, v88, v89
	global_store_dwordx4 v[94:95], v[80:83], off offset:256
	s_nop 1
	v_mov_b32_e32 v84, v234
	v_mad_i64_i32 v[80:81], s[18:19], v148, s42, v[164:165]
	v_lshl_add_u64 v[86:87], v[80:81], 0, v[166:167]
	v_pk_mul_f32 v[82:83], v[14:15], v[84:85] op_sel_hi:[1,0]
	v_pk_mul_f32 v[80:81], v[12:13], v[84:85] op_sel_hi:[1,0]
	v_pk_mul_f32 v[88:89], v[10:11], v[84:85] op_sel_hi:[1,0]
	v_pk_mul_f32 v[90:91], v[8:9], v[84:85] op_sel_hi:[1,0]
	v_cvt_pk_bf16_f32 v80, v80, v81
	v_cvt_pk_bf16_f32 v81, v82, v83
	v_cvt_pk_bf16_f32 v82, v90, v91
	v_cvt_pk_bf16_f32 v83, v88, v89
	v_pk_mul_f32 v[72:73], v[72:73], v[84:85] op_sel_hi:[1,0]
	global_store_dwordx4 v[86:87], v[80:83], off
	v_pk_mul_f32 v[74:75], v[74:75], v[84:85] op_sel_hi:[1,0]
	s_nop 0
	v_pk_mul_f32 v[80:81], v[70:71], v[84:85] op_sel_hi:[1,0]
	v_pk_mul_f32 v[70:71], v[68:69], v[84:85] op_sel_hi:[1,0]
	v_cvt_pk_bf16_f32 v68, v72, v73
	v_cvt_pk_bf16_f32 v69, v74, v75
	v_cvt_pk_bf16_f32 v70, v70, v71
	v_cvt_pk_bf16_f32 v71, v80, v81
	global_store_dwordx4 v[86:87], v[68:71], off offset:256
	s_nop 1
	v_mov_b32_e32 v72, v235
	v_mad_i64_i32 v[68:69], s[18:19], v146, s42, v[164:165]
	v_lshl_add_u64 v[74:75], v[68:69], 0, v[166:167]
	v_pk_mul_f32 v[70:71], v[6:7], v[72:73] op_sel_hi:[1,0]
	v_pk_mul_f32 v[68:69], v[4:5], v[72:73] op_sel_hi:[1,0]
	v_pk_mul_f32 v[80:81], v[2:3], v[72:73] op_sel_hi:[1,0]
	v_pk_mul_f32 v[82:83], v[0:1], v[72:73] op_sel_hi:[1,0]
	v_cvt_pk_bf16_f32 v68, v68, v69
	v_cvt_pk_bf16_f32 v69, v70, v71
	v_cvt_pk_bf16_f32 v70, v82, v83
	v_cvt_pk_bf16_f32 v71, v80, v81
	global_store_dwordx4 v[74:75], v[68:71], off
	v_pk_mul_f32 v[54:55], v[54:55], v[72:73] op_sel_hi:[1,0]
	v_pk_mul_f32 v[52:53], v[52:53], v[72:73] op_sel_hi:[1,0]
	v_pk_mul_f32 v[68:69], v[46:47], v[72:73] op_sel_hi:[1,0]
	v_pk_mul_f32 v[46:47], v[44:45], v[72:73] op_sel_hi:[1,0]
	v_cvt_pk_bf16_f32 v44, v52, v53
	v_cvt_pk_bf16_f32 v45, v54, v55
	v_cvt_pk_bf16_f32 v46, v46, v47
	v_cvt_pk_bf16_f32 v47, v68, v69
	global_store_dwordx4 v[74:75], v[44:47], off offset:256
	s_mov_b64 s[18:19], 0
;     __device__ __forceinline__ void operator()(const f32x4 (&acc)[2][2][4][2], const Unit& u, int wr, int wc, int fr, int fq, const float (&)[8]) const {
;     ...
;         if (DT && u.pn == 20) {
;             if (wc == 0) {
; #pragma unroll
;                 for (int ai = 0; ai < 2; ++ai)
; #pragma unroll
;                     for (int m = 0; m < 4; ++m) { const int row = row0 + ai * HALF + m * 16; const float rs = rsqrtf(ep[ai * 4 + m] * (1.0f / 1024.0f) + EPS);
;                         *(f32x4*)(dt + (size_t)row * 32 + 8 * fq) = acc[ai][0][m][0] * rs; *(f32x4*)(dt + (size_t)row * 32 + 8 * fq + 4) = acc[ai][0][m][1] * rs; }
;             }
;             return;
.LBB0_208:
	s_andn2_b64 vcc, exec, s[18:19]
	s_cbranch_vccnz .LBB0_201
	s_waitcnt vmcnt(0)
	s_andn2_b64 vcc, exec, s[8:9]
	s_cbranch_vccnz .LBB0_201
	s_waitcnt vmcnt(10)
	v_lshlrev_b64 v[52:53], 7, v[162:163]
	v_lshl_add_u64 v[52:53], v[136:137], 0, v[52:53]
	s_nop 0
	v_mov_b32_e32 v54, v228
	v_pk_mul_f32 v[46:47], v[78:79], v[54:55] op_sel_hi:[1,0]
	v_pk_mul_f32 v[44:45], v[76:77], v[54:55] op_sel_hi:[1,0]
	global_store_dwordx4 v[52:53], v[44:47], off
	s_nop 1
	s_nop 1
	s_nop 0
	v_pk_mul_f32 v[46:47], v[66:67], v[54:55] op_sel_hi:[1,0]
	v_pk_mul_f32 v[44:45], v[64:65], v[54:55] op_sel_hi:[1,0]
	global_store_dwordx4 v[52:53], v[44:47], off offset:16
	s_nop 1
	v_mov_b32_e32 v52, v229
	v_lshlrev_b64 v[54:55], 7, v[160:161]
	v_pk_mul_f32 v[46:47], v[62:63], v[52:53] op_sel_hi:[1,0]
	v_pk_mul_f32 v[44:45], v[60:61], v[52:53] op_sel_hi:[1,0]
	v_lshl_add_u64 v[54:55], v[136:137], 0, v[54:55]
	global_store_dwordx4 v[54:55], v[44:47], off
	s_nop 1
	s_nop 1
	s_nop 0
	v_pk_mul_f32 v[46:47], v[58:59], v[52:53] op_sel_hi:[1,0]
	v_pk_mul_f32 v[44:45], v[56:57], v[52:53] op_sel_hi:[1,0]
	global_store_dwordx4 v[54:55], v[44:47], off offset:16
	s_nop 1
	v_mov_b32_e32 v52, v230
	v_pk_mul_f32 v[44:45], v[48:49], v[52:53] op_sel_hi:[1,0]
	v_lshlrev_b64 v[48:49], 7, v[158:159]
	v_pk_mul_f32 v[46:47], v[50:51], v[52:53] op_sel_hi:[1,0]
	v_lshl_add_u64 v[48:49], v[136:137], 0, v[48:49]
	global_store_dwordx4 v[48:49], v[44:47], off
	v_pk_mul_f32 v[42:43], v[42:43], v[52:53] op_sel_hi:[1,0]
	v_pk_mul_f32 v[40:41], v[40:41], v[52:53] op_sel_hi:[1,0]
	global_store_dwordx4 v[48:49], v[40:43], off offset:16
	s_nop 0
	s_nop 0
	v_lshlrev_b64 v[42:43], 7, v[156:157]
	v_lshl_add_u64 v[42:43], v[136:137], 0, v[42:43]
	v_mov_b32_e32 v40, v231
	v_pk_mul_f32 v[38:39], v[38:39], v[40:41] op_sel_hi:[1,0]
	v_pk_mul_f32 v[36:37], v[36:37], v[40:41] op_sel_hi:[1,0]
	global_store_dwordx4 v[42:43], v[36:39], off
	v_pk_mul_f32 v[34:35], v[34:35], v[40:41] op_sel_hi:[1,0]
	v_pk_mul_f32 v[32:33], v[32:33], v[40:41] op_sel_hi:[1,0]
	global_store_dwordx4 v[42:43], v[32:35], off offset:16
	s_nop 0
	s_nop 0
	v_lshlrev_b64 v[34:35], 7, v[154:155]
	v_lshl_add_u64 v[34:35], v[136:137], 0, v[34:35]
	v_mov_b32_e32 v32, v232
	v_pk_mul_f32 v[30:31], v[30:31], v[32:33] op_sel_hi:[1,0]
	v_pk_mul_f32 v[28:29], v[28:29], v[32:33] op_sel_hi:[1,0]
	global_store_dwordx4 v[34:35], v[28:31], off
	v_pk_mul_f32 v[26:27], v[26:27], v[32:33] op_sel_hi:[1,0]
	v_pk_mul_f32 v[24:25], v[24:25], v[32:33] op_sel_hi:[1,0]
	global_store_dwordx4 v[34:35], v[24:27], off offset:16
	s_nop 0
	s_nop 0
	v_lshlrev_b64 v[26:27], 7, v[150:151]
	v_lshl_add_u64 v[26:27], v[136:137], 0, v[26:27]
	v_mov_b32_e32 v24, v233
	v_pk_mul_f32 v[22:23], v[22:23], v[24:25] op_sel_hi:[1,0]
	v_pk_mul_f32 v[20:21], v[20:21], v[24:25] op_sel_hi:[1,0]
	global_store_dwordx4 v[26:27], v[20:23], off
	v_pk_mul_f32 v[18:19], v[18:19], v[24:25] op_sel_hi:[1,0]
	v_pk_mul_f32 v[16:17], v[16:17], v[24:25] op_sel_hi:[1,0]
	global_store_dwordx4 v[26:27], v[16:19], off offset:16
	s_nop 0
	s_nop 0
	v_lshlrev_b64 v[18:19], 7, v[148:149]
	v_lshl_add_u64 v[18:19], v[136:137], 0, v[18:19]
	v_mov_b32_e32 v16, v234
	v_pk_mul_f32 v[14:15], v[14:15], v[16:17] op_sel_hi:[1,0]
	v_pk_mul_f32 v[12:13], v[12:13], v[16:17] op_sel_hi:[1,0]
	global_store_dwordx4 v[18:19], v[12:15], off
	v_pk_mul_f32 v[10:11], v[10:11], v[16:17] op_sel_hi:[1,0]
	v_pk_mul_f32 v[8:9], v[8:9], v[16:17] op_sel_hi:[1,0]
	global_store_dwordx4 v[18:19], v[8:11], off offset:16
	s_nop 0
	s_nop 0
	v_lshlrev_b64 v[10:11], 7, v[146:147]
	v_lshl_add_u64 v[10:11], v[136:137], 0, v[10:11]
	v_mov_b32_e32 v8, v235
	v_pk_mul_f32 v[6:7], v[6:7], v[8:9] op_sel_hi:[1,0]
	v_pk_mul_f32 v[4:5], v[4:5], v[8:9] op_sel_hi:[1,0]
	v_pk_mul_f32 v[2:3], v[2:3], v[8:9] op_sel_hi:[1,0]
	v_pk_mul_f32 v[0:1], v[0:1], v[8:9] op_sel_hi:[1,0]
	global_store_dwordx4 v[10:11], v[4:7], off
	global_store_dwordx4 v[10:11], v[0:3], off offset:16
	s_branch .LBB0_201

; #define PG8_STAGE(bufoff, gbase, voff) do { _Pragma("unroll") for (int _i = 0; _i < 2; ++_i) \
;         __builtin_amdgcn_global_load_lds((const unsigned*)((const char*)(gbase) + (voff)[_i]), (LAS unsigned*)(lds + (bufoff) + ldsw + _i * 8192), 16, 0, 0); } while (0)
; #define PG8_LDA(dst, b, h) do { _Pragma("unroll") for (int m = 0; m < 4; ++m) _Pragma("unroll") for (int k = 0; k < 2; ++k) dst[m][k] = *(const LAS bf16x8*)(lds + PG8_SA(b, h) + aoff + m * 2048 + k * 1024); } while (0)
; #define PG8_LDB(dst, b, h) do { _Pragma("unroll") for (int n = 0; n < 2; ++n) _Pragma("unroll") for (int k = 0; k < 2; ++k) dst[n][k] = *(const LAS bf16x8*)(lds + PG8_SB(b, h) + boff + n * 2048 + k * 1024); } while (0)
; #define PG8_WAIT_V(n) asm volatile("s_waitcnt vmcnt(" #n ")" ::: "memory")
; #define PG8_BAR __builtin_amdgcn_s_barrier()
; #define PG8_SCHED __builtin_amdgcn_sched_barrier(0)
; template <class Epi>
; __device__ __forceinline__ void gemm_phase(LAS unsigned char* lds, const Gemm g, const StaticOrder& S, const Epi& E) {
;     ...
;     const char* cA = (const char*)g.A + (size_t)cur.pm * tstepA; const char* cB = (const char*)g.Bt + (size_t)cur.pn * tstepB;
;     PG8_STAGE(PG8_SB(0, 0), cB, voffB); PG8_STAGE(PG8_SA(0, 0), cA, voffA); PG8_STAGE(PG8_SB(0, 1), cB + hstepB, voffB); PG8_STAGE(PG8_SA(0, 1), cA + hstepA, voffA);
;     if (wr == 1) PG8_BAR;
;     PG8_WAIT_V(4); PG8_BAR;
;     PG8_STAGE(PG8_SB(1, 0), cB + kstep, voffB); PG8_STAGE(PG8_SA(1, 0), cA + kstep, voffA); PG8_STAGE(PG8_SB(1, 1), cB + hstepB + kstep, voffB);
;     PG8_WAIT_V(6); PG8_BAR;
;     for (;;) {
;         const bool has_next = S.next(ui + 1, nxt);
;         const char* nA = has_next ? (const char*)g.A + (size_t)nxt.pm * tstepA : cA; const char* nB = has_next ? (const char*)g.Bt + (size_t)nxt.pn * tstepB : cB;
;         for (int t = 0; t < nt; t += 2) {
;             const bool last = (t == nt - 2);
;             const char* a1 = cA + (size_t)(t + 1) * kstep;
;             const char* a2 = last ? nA : cA + (size_t)(t + 2) * kstep; const char* b2 = last ? nB : cB + (size_t)(t + 2) * kstep;
;             const char* a3 = a2 + kstep; const char* b3 = b2 + kstep;
;             if (last) E.pre(cur, wr, fr, epre);
;             PG8_LDB(B0, 0, 0); PG8_SCHED; PG8_LDA(At, 0, 0); PG8_STAGE(PG8_SA(1, 1), a1 + hstepA, voffA);
.LBB0_762:
	s_lshl_b32 s4, s4, 5
	s_and_b32 s12, s4, 0x60
	s_mov_b64 s[4:5], 0x80
	s_add_i32 m0, s19, 0x18000
	v_lshl_add_u64 v[6:7], v[6:7], 0, s[4:5]
	s_lshl_b32 s8, s1, 13
	s_lshl_b32 s13, s12, 7
	s_waitcnt vmcnt(4)
	s_barrier
	global_load_lds_dwordx4 v[6:7], off
	v_lshl_add_u64 v[4:5], v[4:5], 0, s[4:5]
	s_add_i32 m0, s19, 0x1a000
	s_add_i32 s35, s19, 0x8000
	s_add_i32 s36, s19, 0xa000
	global_load_lds_dwordx4 v[4:5], off
	v_lshl_add_u64 v[2:3], v[2:3], 0, s[4:5]
	s_mov_b32 m0, s35
	s_add_u32 s10, s22, 0x40080
	global_load_lds_dwordx4 v[2:3], off
	v_lshl_add_u64 v[0:1], v[0:1], 0, s[4:5]
	s_mov_b32 m0, s36
	s_addc_u32 s11, s23, 0
	global_load_lds_dwordx4 v[0:1], off
	s_add_i32 m0, s19, 0x1c000
	v_lshl_add_u64 v[0:1], s[10:11], 0, v[130:131]
	global_load_lds_dwordx4 v[0:1], off
	v_lshl_add_u64 v[0:1], s[10:11], 0, v[134:135]
	s_add_i32 m0, s19, 0x1e000
	v_bfe_u32 v2, v152, 4, 2
	global_load_lds_dwordx4 v[0:1], off
	v_and_b32_e32 v1, 15, v152
	v_lshlrev_b32_e32 v0, 4, v2
	v_lshlrev_b32_e32 v3, 2, v152
	v_lshl_or_b32 v174, s1, 6, v1
	v_lshl_or_b32 v1, v1, 6, v0
	v_and_b32_e32 v3, 32, v3
	s_sext_i32_i8 s40, s0
	v_bitop3_b32 v4, v1, s8, v3 bitop3:0xde
	v_lshlrev_b32_e32 v1, 6, v152
	s_movk_i32 s0, 0x3c0
	v_and_or_b32 v1, v1, s0, v0
	v_bitop3_b32 v175, s13, v1, v3 bitop3:0xf6
	v_mov_b32_e32 v1, v131
	v_lshl_add_u64 v[136:137], s[6:7], 0, v[0:1]
	v_lshlrev_b32_e32 v0, 8, v152
	v_and_b32_e32 v0, 0x38000, v0
	v_lshlrev_b32_e32 v1, 11, v10
	v_or3_b32 v0, v8, v0, v1
	v_add_u32_e32 v138, v0, v9
	v_lshlrev_b32_e32 v0, 4, v11
	v_and_b32_e32 v0, 0x78000, v0
	s_waitcnt vmcnt(6)
	v_or3_b32 v0, v8, v0, v1
	v_add_u32_e32 v140, v0, v9
	s_add_i32 s7, 0, 0x10000
	s_add_i32 s38, 0, 0x14000
	v_mbcnt_lo_u32_b32 v0, -1, 0
	s_ashr_i32 s37, s92, 31
	v_lshl_or_b32 v176, v2, 3, s12
	v_mov_b32_e32 v139, v131
	v_mov_b32_e32 v141, v131
	v_mov_b64_e32 v[142:143], 0x1000
	v_mov_b64_e32 v[144:145], 0xfff
	v_add_u32_e32 v177, s7, v175
	v_add_u32_e32 v178, 0, v4
	v_add_u32_e32 v179, s38, v175
	v_mbcnt_hi_u32_b32 v180, -1, v0
	s_mov_b32 s6, 0x3a800000
	s_mov_b32 s8, 0x358637bd
	s_mov_b32 s39, 0x800000
	s_add_u32 vcc_lo, s20, 0x40080
	s_addc_u32 vcc_hi, s21, 0
	s_add_i32 m0, s19, 0xc000
	v_lshl_add_u64 v[236:237], vcc, 0, v[138:139]
	v_lshl_add_u64 v[238:239], vcc, 0, v[140:141]
	global_load_lds_dwordx4 v[236:237], off
	s_add_i32 m0, s19, 0xe000
	s_nop 0
	global_load_lds_dwordx4 v[238:239], off
	s_waitcnt vmcnt(0)
	s_barrier

; #define PG8_STAGE(bufoff, gbase, voff) do { _Pragma("unroll") for (int _i = 0; _i < 2; ++_i) \
;         __builtin_amdgcn_global_load_lds((const unsigned*)((const char*)(gbase) + (voff)[_i]), (LAS unsigned*)(lds + (bufoff) + ldsw + _i * 8192), 16, 0, 0); } while (0)
; #define PG8_LDA(dst, b, h) do { _Pragma("unroll") for (int m = 0; m < 4; ++m) _Pragma("unroll") for (int k = 0; k < 2; ++k) dst[m][k] = *(const LAS bf16x8*)(lds + PG8_SA(b, h) + aoff + m * 2048 + k * 1024); } while (0)
; #define PG8_LDB(dst, b, h) do { _Pragma("unroll") for (int n = 0; n < 2; ++n) _Pragma("unroll") for (int k = 0; k < 2; ++k) dst[n][k] = *(const LAS bf16x8*)(lds + PG8_SB(b, h) + boff + n * 2048 + k * 1024); } while (0)
; #define PG8_WAIT_V(n) asm volatile("s_waitcnt vmcnt(" #n ")" ::: "memory")
; #define PG8_WAIT_L(n) asm volatile("s_waitcnt lgkmcnt(" #n ")" ::: "memory")
; #define PG8_BAR __builtin_amdgcn_s_barrier()
; #define PG8_SCHED __builtin_amdgcn_sched_barrier(0)
; template <class Epi>
; __device__ __forceinline__ void gemm_phase(LAS unsigned char* lds, const Gemm g, const StaticOrder& S, const Epi& E) {
;     ...
;         const bool has_next = S.next(ui + 1, nxt);
;         const char* nA = has_next ? (const char*)g.A + (size_t)nxt.pm * tstepA : cA; const char* nB = has_next ? (const char*)g.Bt + (size_t)nxt.pn * tstepB : cB;
;         for (int t = 0; t < nt; t += 2) {
;             const bool last = (t == nt - 2);
;             const char* a1 = cA + (size_t)(t + 1) * kstep;
;             const char* a2 = last ? nA : cA + (size_t)(t + 2) * kstep; const char* b2 = last ? nB : cB + (size_t)(t + 2) * kstep;
;             const char* a3 = a2 + kstep; const char* b3 = b2 + kstep;
;             if (last) E.pre(cur, wr, fr, epre);
;             PG8_LDB(B0, 0, 0); PG8_SCHED; PG8_LDA(At, 0, 0); PG8_STAGE(PG8_SA(1, 1), a1 + hstepA, voffA);
;             PG8_WAIT_L(8); PG8_BAR; PG8_WAIT_L(0); PG8_MMA(0, 0, At, B0); PG8_BAR; PG8_SCHED;
;             PG8_LDB(B1, 0, 1); PG8_STAGE(PG8_SB(0, 0), b2, voffB);
;             PG8_BAR; PG8_WAIT_L(0); PG8_MMA(0, 1, At, B1); PG8_BAR;
;             PG8_LDA(At, 0, 1); PG8_STAGE(PG8_SA(0, 0), a2, voffA);
;             PG8_BAR; PG8_WAIT_L(0); PG8_MMA(1, 0, At, B0); PG8_BAR; PG8_SCHED;
;             PG8_STAGE(PG8_SB(0, 1), b2 + hstepB, voffB);
;             PG8_WAIT_V(6); PG8_BAR; PG8_MMA(1, 1, At, B1); PG8_BAR;
.LBB0_769:
	s_ashr_i32 s13, s12, 31
	v_cmp_lt_i64_e32 vcc, s[14:15], v[142:143]
	s_lshl_b64 s[14:15], s[12:13], 19
	s_add_u32 s14, s76, s14
	s_addc_u32 s15, s77, s15
	s_and_b64 s[16:17], vcc, exec
	s_cselect_b32 s13, s15, s21
	s_cselect_b32 s41, s14, s20
	s_ashr_i32 s11, s10, 31
	s_lshl_b64 s[16:17], s[10:11], 19
	s_add_u32 s16, s27, s16
	s_addc_u32 s17, s28, s17
	s_and_b64 s[24:25], vcc, exec
	s_cselect_b32 s11, s17, s23
	s_cselect_b32 s42, s16, s22
	s_add_u32 s20, s20, 0x40080
	s_addc_u32 s21, s21, 0
	s_add_u32 s43, s22, 0x100
	s_addc_u32 s44, s23, 0
	s_mov_b32 s45, -2
	ds_read_b128 v[146:149], v177
	ds_read_b128 v[154:157], v177 offset:1024
	ds_read_b128 v[158:161], v177 offset:2048
	ds_read_b128 v[162:165], v177 offset:3072
	s_add_u32 s22, s20, 0xfffc0080
	s_addc_u32 s23, s21, -1
	s_cmp_eq_u32 s45, 12
	s_cselect_b32 s25, s13, s23
	s_cselect_b32 s24, s41, s22
	s_cselect_b32 s23, s11, s44
	s_cselect_b32 s22, s42, s43
	ds_read_b128 v[166:169], v178
	ds_read_b128 v[170:173], v178 offset:1024
	ds_read_b128 v[182:185], v178 offset:2048
	ds_read_b128 v[186:189], v178 offset:3072
	ds_read_b128 v[190:193], v178 offset:4096
	ds_read_b128 v[194:197], v178 offset:5120
	ds_read_b128 v[198:201], v178 offset:6144
	ds_read_b128 v[202:205], v178 offset:7168
	s_waitcnt lgkmcnt(8)
	s_barrier
	s_waitcnt lgkmcnt(0)
	s_setprio 1
	s_waitcnt lgkmcnt(0)
	v_mfma_f32_16x16x32_bf16 v[124:127], v[146:149], v[166:169], 0
	v_mfma_f32_16x16x32_bf16 v[120:123], v[158:161], v[166:169], 0
	v_mfma_f32_16x16x32_bf16 v[108:111], v[146:149], v[182:185], 0
	v_mfma_f32_16x16x32_bf16 v[104:107], v[158:161], v[182:185], 0
	v_mfma_f32_16x16x32_bf16 v[92:95], v[146:149], v[190:193], 0
	v_mfma_f32_16x16x32_bf16 v[88:91], v[158:161], v[190:193], 0
	v_mfma_f32_16x16x32_bf16 v[76:79], v[146:149], v[198:201], 0
	v_mfma_f32_16x16x32_bf16 v[72:75], v[158:161], v[198:201], 0
	v_mfma_f32_16x16x32_bf16 v[124:127], v[154:157], v[170:173], v[124:127]
	v_mfma_f32_16x16x32_bf16 v[120:123], v[162:165], v[170:173], v[120:123]
	v_mfma_f32_16x16x32_bf16 v[108:111], v[154:157], v[186:189], v[108:111]
	v_mfma_f32_16x16x32_bf16 v[104:107], v[162:165], v[186:189], v[104:107]
	v_mfma_f32_16x16x32_bf16 v[92:95], v[154:157], v[194:197], v[92:95]
	v_mfma_f32_16x16x32_bf16 v[88:91], v[162:165], v[194:197], v[88:91]
	v_mfma_f32_16x16x32_bf16 v[76:79], v[154:157], v[202:205], v[76:79]
	v_mfma_f32_16x16x32_bf16 v[72:75], v[162:165], v[202:205], v[72:75]
	s_setprio 0
	s_barrier
	s_add_i32 s46, s7, s29
	v_lshl_add_u64 v[150:151], s[22:23], 0, v[130:131]
	s_mov_b32 m0, s46
	ds_read_b128 v[206:209], v179
	ds_read_b128 v[210:213], v179 offset:1024
	ds_read_b128 v[214:217], v179 offset:2048
	ds_read_b128 v[218:221], v179 offset:3072
	global_load_lds_dwordx4 v[150:151], off
	v_lshl_add_u64 v[222:223], s[22:23], 0, v[134:135]
	s_add_i32 m0, s46, 0x2000
	s_nop 0
	global_load_lds_dwordx4 v[222:223], off
	s_barrier
	s_waitcnt lgkmcnt(0)
	s_setprio 1
	s_waitcnt lgkmcnt(0)
	v_mfma_f32_16x16x32_bf16 v[116:119], v[206:209], v[166:169], 0
	v_mfma_f32_16x16x32_bf16 v[112:115], v[214:217], v[166:169], 0
	v_mfma_f32_16x16x32_bf16 v[100:103], v[206:209], v[182:185], 0
	v_mfma_f32_16x16x32_bf16 v[96:99], v[214:217], v[182:185], 0
	v_mfma_f32_16x16x32_bf16 v[84:87], v[206:209], v[190:193], 0
	v_mfma_f32_16x16x32_bf16 v[80:83], v[214:217], v[190:193], 0
	v_mfma_f32_16x16x32_bf16 v[68:71], v[206:209], v[198:201], 0
	v_mfma_f32_16x16x32_bf16 v[64:67], v[214:217], v[198:201], 0
	v_mfma_f32_16x16x32_bf16 v[116:119], v[210:213], v[170:173], v[116:119]
	v_mfma_f32_16x16x32_bf16 v[112:115], v[218:221], v[170:173], v[112:115]
	v_mfma_f32_16x16x32_bf16 v[100:103], v[210:213], v[186:189], v[100:103]
	v_mfma_f32_16x16x32_bf16 v[96:99], v[218:221], v[186:189], v[96:99]
	v_mfma_f32_16x16x32_bf16 v[84:87], v[210:213], v[194:197], v[84:87]
	v_mfma_f32_16x16x32_bf16 v[80:83], v[218:221], v[194:197], v[80:83]
	v_mfma_f32_16x16x32_bf16 v[68:71], v[210:213], v[202:205], v[68:71]
	v_mfma_f32_16x16x32_bf16 v[64:67], v[218:221], v[202:205], v[64:67]
	s_setprio 0
	s_mov_b32 m0, s19
	v_lshl_add_u64 v[224:225], s[24:25], 0, v[128:129]
	s_barrier
	ds_read_b128 v[166:169], v178 offset:16384
	ds_read_b128 v[170:173], v178 offset:17408
	ds_read_b128 v[182:185], v178 offset:18432
	ds_read_b128 v[186:189], v178 offset:19456
	ds_read_b128 v[190:193], v178 offset:20480
	ds_read_b128 v[194:197], v178 offset:21504
	ds_read_b128 v[198:201], v178 offset:22528
	ds_read_b128 v[202:205], v178 offset:23552
	global_load_lds_dwordx4 v[224:225], off
	v_lshl_add_u64 v[226:227], s[24:25], 0, v[132:133]
	s_mov_b32 m0, s30
	s_nop 0
	global_load_lds_dwordx4 v[226:227], off
	s_barrier
	s_waitcnt lgkmcnt(0)
	s_setprio 1
	s_waitcnt lgkmcnt(0)
	v_mfma_f32_16x16x32_bf16 v[60:63], v[146:149], v[166:169], 0
	v_mfma_f32_16x16x32_bf16 v[56:59], v[158:161], v[166:169], 0
	v_mfma_f32_16x16x32_bf16 v[44:47], v[146:149], v[182:185], 0
	v_mfma_f32_16x16x32_bf16 v[40:43], v[158:161], v[182:185], 0
	v_mfma_f32_16x16x32_bf16 v[28:31], v[146:149], v[190:193], 0
	v_mfma_f32_16x16x32_bf16 v[24:27], v[158:161], v[190:193], 0
	v_mfma_f32_16x16x32_bf16 v[12:15], v[146:149], v[198:201], 0
	v_mfma_f32_16x16x32_bf16 v[8:11], v[158:161], v[198:201], 0
	v_mfma_f32_16x16x32_bf16 v[60:63], v[154:157], v[170:173], v[60:63]
	v_mfma_f32_16x16x32_bf16 v[56:59], v[162:165], v[170:173], v[56:59]
	v_mfma_f32_16x16x32_bf16 v[44:47], v[154:157], v[186:189], v[44:47]
	v_mfma_f32_16x16x32_bf16 v[40:43], v[162:165], v[186:189], v[40:43]
	v_mfma_f32_16x16x32_bf16 v[28:31], v[154:157], v[194:197], v[28:31]
	v_mfma_f32_16x16x32_bf16 v[24:27], v[162:165], v[194:197], v[24:27]
	v_mfma_f32_16x16x32_bf16 v[12:15], v[154:157], v[202:205], v[12:15]
	v_mfma_f32_16x16x32_bf16 v[8:11], v[162:165], v[202:205], v[8:11]
	s_setprio 0
	s_barrier
; #define PG8_STAGE(bufoff, gbase, voff) do { _Pragma("unroll") for (int _i = 0; _i < 2; ++_i) \
;         __builtin_amdgcn_global_load_lds((const unsigned*)((const char*)(gbase) + (voff)[_i]), (LAS unsigned*)(lds + (bufoff) + ldsw + _i * 8192), 16, 0, 0); } while (0)
; #define PG8_LDA(dst, b, h) do { _Pragma("unroll") for (int m = 0; m < 4; ++m) _Pragma("unroll") for (int k = 0; k < 2; ++k) dst[m][k] = *(const LAS bf16x8*)(lds + PG8_SA(b, h) + aoff + m * 2048 + k * 1024); } while (0)
; #define PG8_LDB(dst, b, h) do { _Pragma("unroll") for (int n = 0; n < 2; ++n) _Pragma("unroll") for (int k = 0; k < 2; ++k) dst[n][k] = *(const LAS bf16x8*)(lds + PG8_SB(b, h) + boff + n * 2048 + k * 1024); } while (0)
; #define PG8_MMA(ai, bj, At, Bt) do { __builtin_amdgcn_s_setprio(1); _Pragma("unroll") for (int m = 0; m < 4; ++m) _Pragma("unroll") for (int n = 0; n < 2; ++n) _Pragma("unroll") for (int k = 0; k < 2; ++k) \
;         acc[ai][bj][m][n] = __builtin_amdgcn_mfma_f32_16x16x32_bf16(Bt[n][k], At[m][k], acc[ai][bj][m][n], 0, 0, 0); __builtin_amdgcn_s_setprio(0); } while (0)
; #define PG8_WAIT_V(n) asm volatile("s_waitcnt vmcnt(" #n ")" ::: "memory")
; #define PG8_WAIT_L(n) asm volatile("s_waitcnt lgkmcnt(" #n ")" ::: "memory")
; #define PG8_BAR __builtin_amdgcn_s_barrier()
; #define PG8_SCHED __builtin_amdgcn_sched_barrier(0)
; template <class Epi>
; __device__ __forceinline__ void gemm_phase(LAS unsigned char* lds, const Gemm g, const StaticOrder& S, const Epi& E) {
;     ...
;             PG8_WAIT_V(6); PG8_BAR; PG8_MMA(1, 1, At, B1); PG8_BAR;
;             PG8_LDB(B0, 1, 0); PG8_SCHED; PG8_LDA(At, 1, 0); PG8_STAGE(PG8_SA(0, 1), a2 + hstepA, voffA);
;             PG8_WAIT_L(8); PG8_BAR; PG8_WAIT_L(0); PG8_MMA(0, 0, At, B0); PG8_BAR; PG8_SCHED;
;             PG8_LDB(B1, 1, 1); PG8_STAGE(PG8_SB(1, 0), b3, voffB);
;             PG8_BAR; PG8_WAIT_L(0); PG8_MMA(0, 1, At, B1); PG8_BAR;
;             PG8_LDA(At, 1, 1); PG8_STAGE(PG8_SA(1, 0), a3, voffA);
;             PG8_BAR; PG8_WAIT_L(0); PG8_MMA(1, 0, At, B0); PG8_BAR; PG8_SCHED;
;             PG8_STAGE(PG8_SB(1, 1), b3 + hstepB, voffB);
;             PG8_WAIT_V(6); PG8_BAR; PG8_MMA(1, 1, At, B1); PG8_BAR;
	s_add_u32 s46, s22, 0x40000
	s_addc_u32 s47, s23, 0
	s_add_i32 s48, s38, s29
	v_lshl_add_u64 v[146:147], s[46:47], 0, v[130:131]
	s_mov_b32 m0, s48
	s_nop 0
	global_load_lds_dwordx4 v[146:147], off
	v_lshl_add_u64 v[146:147], s[46:47], 0, v[134:135]
	s_add_i32 m0, s48, 0x2000
	s_nop 0
	global_load_lds_dwordx4 v[146:147], off
	s_waitcnt vmcnt(22)
	s_barrier
	s_setprio 1
	v_mfma_f32_16x16x32_bf16 v[52:55], v[206:209], v[166:169], 0
	v_mfma_f32_16x16x32_bf16 v[48:51], v[214:217], v[166:169], 0
	v_mfma_f32_16x16x32_bf16 v[36:39], v[206:209], v[182:185], 0
	v_mfma_f32_16x16x32_bf16 v[32:35], v[214:217], v[182:185], 0
	v_mfma_f32_16x16x32_bf16 v[20:23], v[206:209], v[190:193], 0
	v_mfma_f32_16x16x32_bf16 v[16:19], v[214:217], v[190:193], 0
	v_mfma_f32_16x16x32_bf16 v[4:7], v[206:209], v[198:201], 0
	v_mfma_f32_16x16x32_bf16 v[0:3], v[214:217], v[198:201], 0
	v_mfma_f32_16x16x32_bf16 v[52:55], v[210:213], v[170:173], v[52:55]
	v_mfma_f32_16x16x32_bf16 v[48:51], v[218:221], v[170:173], v[48:51]
	v_mfma_f32_16x16x32_bf16 v[36:39], v[210:213], v[186:189], v[36:39]
	v_mfma_f32_16x16x32_bf16 v[32:35], v[218:221], v[186:189], v[32:35]
	v_mfma_f32_16x16x32_bf16 v[20:23], v[210:213], v[194:197], v[20:23]
	v_mfma_f32_16x16x32_bf16 v[16:19], v[218:221], v[194:197], v[16:19]
	v_mfma_f32_16x16x32_bf16 v[4:7], v[210:213], v[202:205], v[4:7]
	v_mfma_f32_16x16x32_bf16 v[0:3], v[218:221], v[202:205], v[0:3]
	s_setprio 0
	s_add_i32 s46, 0, 0x18000
	v_add_u32_e32 v162, s46, v175
	s_barrier
	ds_read_b128 v[146:149], v162
	ds_read_b128 v[154:157], v162 offset:1024
	ds_read_b128 v[158:161], v162 offset:2048
	ds_read_b128 v[162:165], v162 offset:3072
	s_add_u32 s24, s24, 0x40000
	s_addc_u32 s25, s25, 0
	s_mov_b32 m0, s31
	v_lshl_add_u64 v[206:207], s[24:25], 0, v[128:129]
	ds_read_b128 v[166:169], v178 offset:32768
	ds_read_b128 v[170:173], v178 offset:33792
	ds_read_b128 v[182:185], v178 offset:34816
	ds_read_b128 v[186:189], v178 offset:35840
	ds_read_b128 v[190:193], v178 offset:36864
	ds_read_b128 v[194:197], v178 offset:37888
	ds_read_b128 v[198:201], v178 offset:38912
	ds_read_b128 v[202:205], v178 offset:39936
	global_load_lds_dwordx4 v[206:207], off
	v_lshl_add_u64 v[206:207], s[24:25], 0, v[132:133]
	s_mov_b32 m0, s33
	s_nop 0
	global_load_lds_dwordx4 v[206:207], off
	s_waitcnt lgkmcnt(8)
	s_barrier
	s_waitcnt lgkmcnt(0)
	s_setprio 1
	s_waitcnt lgkmcnt(0)
	v_mfma_f32_16x16x32_bf16 v[124:127], v[146:149], v[166:169], v[124:127]
	v_mfma_f32_16x16x32_bf16 v[120:123], v[158:161], v[166:169], v[120:123]
	v_mfma_f32_16x16x32_bf16 v[108:111], v[146:149], v[182:185], v[108:111]
	v_mfma_f32_16x16x32_bf16 v[104:107], v[158:161], v[182:185], v[104:107]
	v_mfma_f32_16x16x32_bf16 v[92:95], v[146:149], v[190:193], v[92:95]
	v_mfma_f32_16x16x32_bf16 v[88:91], v[158:161], v[190:193], v[88:91]
	v_mfma_f32_16x16x32_bf16 v[76:79], v[146:149], v[198:201], v[76:79]
	v_mfma_f32_16x16x32_bf16 v[72:75], v[158:161], v[198:201], v[72:75]
	v_mfma_f32_16x16x32_bf16 v[124:127], v[154:157], v[170:173], v[124:127]
	v_mfma_f32_16x16x32_bf16 v[120:123], v[162:165], v[170:173], v[120:123]
	v_mfma_f32_16x16x32_bf16 v[108:111], v[154:157], v[186:189], v[108:111]
	v_mfma_f32_16x16x32_bf16 v[104:107], v[162:165], v[186:189], v[104:107]
	v_mfma_f32_16x16x32_bf16 v[92:95], v[154:157], v[194:197], v[92:95]
	v_mfma_f32_16x16x32_bf16 v[88:91], v[162:165], v[194:197], v[88:91]
	v_mfma_f32_16x16x32_bf16 v[76:79], v[154:157], v[202:205], v[76:79]
	v_mfma_f32_16x16x32_bf16 v[72:75], v[162:165], v[202:205], v[72:75]
	s_setprio 0
	s_barrier
	s_add_i32 s24, 0, 0x1c000
	s_add_i32 s25, s46, s29
	v_add_u32_e32 v181, s24, v175
	v_lshl_add_u64 v[150:151], v[150:151], 0, s[4:5]
	s_mov_b32 m0, s25
	ds_read_b128 v[206:209], v181
	ds_read_b128 v[210:213], v181 offset:1024
	ds_read_b128 v[214:217], v181 offset:2048
	ds_read_b128 v[218:221], v181 offset:3072
	global_load_lds_dwordx4 v[150:151], off
	v_lshl_add_u64 v[150:151], v[222:223], 0, s[4:5]
	s_add_i32 m0, s25, 0x2000
	s_nop 0
	global_load_lds_dwordx4 v[150:151], off
	s_barrier
	s_waitcnt lgkmcnt(0)
	s_setprio 1
	s_waitcnt lgkmcnt(0)
	v_mfma_f32_16x16x32_bf16 v[116:119], v[206:209], v[166:169], v[116:119]
	v_mfma_f32_16x16x32_bf16 v[112:115], v[214:217], v[166:169], v[112:115]
	v_mfma_f32_16x16x32_bf16 v[100:103], v[206:209], v[182:185], v[100:103]
	v_mfma_f32_16x16x32_bf16 v[96:99], v[214:217], v[182:185], v[96:99]
	v_mfma_f32_16x16x32_bf16 v[84:87], v[206:209], v[190:193], v[84:87]
	v_mfma_f32_16x16x32_bf16 v[80:83], v[214:217], v[190:193], v[80:83]
	v_mfma_f32_16x16x32_bf16 v[68:71], v[206:209], v[198:201], v[68:71]
	v_mfma_f32_16x16x32_bf16 v[64:67], v[214:217], v[198:201], v[64:67]
	v_mfma_f32_16x16x32_bf16 v[116:119], v[210:213], v[170:173], v[116:119]
	v_mfma_f32_16x16x32_bf16 v[112:115], v[218:221], v[170:173], v[112:115]
	v_mfma_f32_16x16x32_bf16 v[100:103], v[210:213], v[186:189], v[100:103]
	v_mfma_f32_16x16x32_bf16 v[96:99], v[218:221], v[186:189], v[96:99]
	v_mfma_f32_16x16x32_bf16 v[84:87], v[210:213], v[194:197], v[84:87]
	v_mfma_f32_16x16x32_bf16 v[80:83], v[218:221], v[194:197], v[80:83]
	v_mfma_f32_16x16x32_bf16 v[68:71], v[210:213], v[202:205], v[68:71]
	v_mfma_f32_16x16x32_bf16 v[64:67], v[218:221], v[202:205], v[64:67]
	s_setprio 0
	s_mov_b32 m0, s35
	v_lshl_add_u64 v[150:151], v[224:225], 0, s[4:5]
	s_barrier
	ds_read_b128 v[166:169], v178 offset:49152
	ds_read_b128 v[170:173], v178 offset:50176
	ds_read_b128 v[182:185], v178 offset:51200
	ds_read_b128 v[186:189], v178 offset:52224
	ds_read_b128 v[190:193], v178 offset:53248
	ds_read_b128 v[194:197], v178 offset:54272
	ds_read_b128 v[198:201], v178 offset:55296
	ds_read_b128 v[202:205], v178 offset:56320
	global_load_lds_dwordx4 v[150:151], off
	v_lshl_add_u64 v[150:151], v[226:227], 0, s[4:5]
	s_mov_b32 m0, s36
	s_nop 0
	global_load_lds_dwordx4 v[150:151], off
	s_barrier
; #define PG8_STAGE(bufoff, gbase, voff) do { _Pragma("unroll") for (int _i = 0; _i < 2; ++_i) \
;         __builtin_amdgcn_global_load_lds((const unsigned*)((const char*)(gbase) + (voff)[_i]), (LAS unsigned*)(lds + (bufoff) + ldsw + _i * 8192), 16, 0, 0); } while (0)
; #define PG8_LDA(dst, b, h) do { _Pragma("unroll") for (int m = 0; m < 4; ++m) _Pragma("unroll") for (int k = 0; k < 2; ++k) dst[m][k] = *(const LAS bf16x8*)(lds + PG8_SA(b, h) + aoff + m * 2048 + k * 1024); } while (0)
; #define PG8_LDB(dst, b, h) do { _Pragma("unroll") for (int n = 0; n < 2; ++n) _Pragma("unroll") for (int k = 0; k < 2; ++k) dst[n][k] = *(const LAS bf16x8*)(lds + PG8_SB(b, h) + boff + n * 2048 + k * 1024); } while (0)
; #define PG8_MMA(ai, bj, At, Bt) do { __builtin_amdgcn_s_setprio(1); _Pragma("unroll") for (int m = 0; m < 4; ++m) _Pragma("unroll") for (int n = 0; n < 2; ++n) _Pragma("unroll") for (int k = 0; k < 2; ++k) \
;         acc[ai][bj][m][n] = __builtin_amdgcn_mfma_f32_16x16x32_bf16(Bt[n][k], At[m][k], acc[ai][bj][m][n], 0, 0, 0); __builtin_amdgcn_s_setprio(0); } while (0)
; #define PG8_WAIT_V(n) asm volatile("s_waitcnt vmcnt(" #n ")" ::: "memory")
; #define PG8_WAIT_L(n) asm volatile("s_waitcnt lgkmcnt(" #n ")" ::: "memory")
; #define PG8_BAR __builtin_amdgcn_s_barrier()
; #define PG8_SCHED __builtin_amdgcn_sched_barrier(0)
; template <class Epi>
; __device__ __forceinline__ void gemm_phase(LAS unsigned char* lds, const Gemm g, const StaticOrder& S, const Epi& E) {
;     ...
;             PG8_LDB(B0, 0, 0); PG8_SCHED; PG8_LDA(At, 0, 0); PG8_STAGE(PG8_SA(1, 1), a1 + hstepA, voffA);
;             PG8_WAIT_L(8); PG8_BAR; PG8_WAIT_L(0); PG8_MMA(0, 0, At, B0); PG8_BAR; PG8_SCHED;
;             PG8_LDB(B1, 0, 1); PG8_STAGE(PG8_SB(0, 0), b2, voffB);
;     ...
;             PG8_BAR; PG8_WAIT_L(0); PG8_MMA(1, 0, At, B0); PG8_BAR; PG8_SCHED;
;             PG8_STAGE(PG8_SB(1, 1), b3 + hstepB, voffB);
;             PG8_WAIT_V(6); PG8_BAR; PG8_MMA(1, 1, At, B1); PG8_BAR;
	s_waitcnt lgkmcnt(0)
	s_setprio 1
	s_waitcnt lgkmcnt(0)
	v_mfma_f32_16x16x32_bf16 v[60:63], v[146:149], v[166:169], v[60:63]
	v_mfma_f32_16x16x32_bf16 v[56:59], v[158:161], v[166:169], v[56:59]
	v_mfma_f32_16x16x32_bf16 v[44:47], v[146:149], v[182:185], v[44:47]
	v_mfma_f32_16x16x32_bf16 v[40:43], v[158:161], v[182:185], v[40:43]
	v_mfma_f32_16x16x32_bf16 v[28:31], v[146:149], v[190:193], v[28:31]
	v_mfma_f32_16x16x32_bf16 v[24:27], v[158:161], v[190:193], v[24:27]
	v_mfma_f32_16x16x32_bf16 v[12:15], v[146:149], v[198:201], v[12:15]
	v_mfma_f32_16x16x32_bf16 v[8:11], v[158:161], v[198:201], v[8:11]
	v_mfma_f32_16x16x32_bf16 v[60:63], v[154:157], v[170:173], v[60:63]
	v_mfma_f32_16x16x32_bf16 v[56:59], v[162:165], v[170:173], v[56:59]
	v_mfma_f32_16x16x32_bf16 v[44:47], v[154:157], v[186:189], v[44:47]
	v_mfma_f32_16x16x32_bf16 v[40:43], v[162:165], v[186:189], v[40:43]
	v_mfma_f32_16x16x32_bf16 v[28:31], v[154:157], v[194:197], v[28:31]
	v_mfma_f32_16x16x32_bf16 v[24:27], v[162:165], v[194:197], v[24:27]
	v_mfma_f32_16x16x32_bf16 v[12:15], v[154:157], v[202:205], v[12:15]
	v_mfma_f32_16x16x32_bf16 v[8:11], v[162:165], v[202:205], v[8:11]
	s_setprio 0
	s_barrier
	s_add_u32 s22, s22, 0x40080
	s_addc_u32 s23, s23, 0
	s_add_i32 s24, s24, s29
	v_lshl_add_u64 v[146:147], s[22:23], 0, v[130:131]
	s_mov_b32 m0, s24
	s_nop 0
	global_load_lds_dwordx4 v[146:147], off
	v_lshl_add_u64 v[146:147], s[22:23], 0, v[134:135]
	s_add_i32 m0, s24, 0x2000
	s_nop 0
	global_load_lds_dwordx4 v[146:147], off
	s_waitcnt vmcnt(6)
	s_barrier
	s_setprio 1
	v_mfma_f32_16x16x32_bf16 v[52:55], v[206:209], v[166:169], v[52:55]
	v_mfma_f32_16x16x32_bf16 v[48:51], v[214:217], v[166:169], v[48:51]
	v_mfma_f32_16x16x32_bf16 v[36:39], v[206:209], v[182:185], v[36:39]
	v_mfma_f32_16x16x32_bf16 v[32:35], v[214:217], v[182:185], v[32:35]
	v_mfma_f32_16x16x32_bf16 v[20:23], v[206:209], v[190:193], v[20:23]
	v_mfma_f32_16x16x32_bf16 v[16:19], v[214:217], v[190:193], v[16:19]
	v_mfma_f32_16x16x32_bf16 v[4:7], v[206:209], v[198:201], v[4:7]
	v_mfma_f32_16x16x32_bf16 v[0:3], v[214:217], v[198:201], v[0:3]
	v_mfma_f32_16x16x32_bf16 v[52:55], v[210:213], v[170:173], v[52:55]
	v_mfma_f32_16x16x32_bf16 v[48:51], v[218:221], v[170:173], v[48:51]
	v_mfma_f32_16x16x32_bf16 v[36:39], v[210:213], v[186:189], v[36:39]
	v_mfma_f32_16x16x32_bf16 v[32:35], v[218:221], v[186:189], v[32:35]
	v_mfma_f32_16x16x32_bf16 v[20:23], v[210:213], v[194:197], v[20:23]
	v_mfma_f32_16x16x32_bf16 v[16:19], v[218:221], v[194:197], v[16:19]
	v_mfma_f32_16x16x32_bf16 v[4:7], v[210:213], v[202:205], v[4:7]
	v_mfma_f32_16x16x32_bf16 v[0:3], v[218:221], v[202:205], v[0:3]
	s_setprio 0
	s_add_i32 s45, s45, 2
	s_add_u32 s20, s20, 0x100
	s_addc_u32 s21, s21, 0
	s_add_u32 s43, s43, 0x100
	s_addc_u32 s44, s44, 0
	s_cmp_gt_u32 s45, 13
	s_barrier
.LBB0_770:
	ds_read_b128 v[146:149], v177
	ds_read_b128 v[154:157], v177 offset:1024
	ds_read_b128 v[158:161], v177 offset:2048
	ds_read_b128 v[162:165], v177 offset:3072
	s_add_u32 s22, s20, 0xfffc0080
	s_addc_u32 s23, s21, -1
	s_cmp_eq_u32 s45, 12
	s_cselect_b32 s25, s13, s23
	s_cselect_b32 s24, s41, s22
	s_cselect_b32 s23, s11, s44
	s_cselect_b32 s22, s42, s43
	v_lshl_add_u64 v[150:151], s[20:21], 0, v[138:139]
	s_add_i32 m0, s19, 0xc000
	ds_read_b128 v[166:169], v178
	ds_read_b128 v[170:173], v178 offset:1024
	ds_read_b128 v[182:185], v178 offset:2048
	ds_read_b128 v[186:189], v178 offset:3072
	ds_read_b128 v[190:193], v178 offset:4096
	ds_read_b128 v[194:197], v178 offset:5120
	ds_read_b128 v[198:201], v178 offset:6144
	ds_read_b128 v[202:205], v178 offset:7168
	global_load_lds_dwordx4 v[150:151], off
	v_lshl_add_u64 v[150:151], s[20:21], 0, v[140:141]
	s_add_i32 m0, s19, 0xe000
	s_nop 0
	global_load_lds_dwordx4 v[150:151], off
	s_waitcnt lgkmcnt(8)
	s_barrier
	s_waitcnt lgkmcnt(0)
	s_setprio 1
	s_waitcnt lgkmcnt(0)
	v_mfma_f32_16x16x32_bf16 v[124:127], v[146:149], v[166:169], v[124:127]
	v_mfma_f32_16x16x32_bf16 v[120:123], v[158:161], v[166:169], v[120:123]
	v_mfma_f32_16x16x32_bf16 v[108:111], v[146:149], v[182:185], v[108:111]
	v_mfma_f32_16x16x32_bf16 v[104:107], v[158:161], v[182:185], v[104:107]
	v_mfma_f32_16x16x32_bf16 v[92:95], v[146:149], v[190:193], v[92:95]
	v_mfma_f32_16x16x32_bf16 v[88:91], v[158:161], v[190:193], v[88:91]
	v_mfma_f32_16x16x32_bf16 v[76:79], v[146:149], v[198:201], v[76:79]
	v_mfma_f32_16x16x32_bf16 v[72:75], v[158:161], v[198:201], v[72:75]
	v_mfma_f32_16x16x32_bf16 v[124:127], v[154:157], v[170:173], v[124:127]
	v_mfma_f32_16x16x32_bf16 v[120:123], v[162:165], v[170:173], v[120:123]
	v_mfma_f32_16x16x32_bf16 v[108:111], v[154:157], v[186:189], v[108:111]
	v_mfma_f32_16x16x32_bf16 v[104:107], v[162:165], v[186:189], v[104:107]
	v_mfma_f32_16x16x32_bf16 v[92:95], v[154:157], v[194:197], v[92:95]
	v_mfma_f32_16x16x32_bf16 v[88:91], v[162:165], v[194:197], v[88:91]
	v_mfma_f32_16x16x32_bf16 v[76:79], v[154:157], v[202:205], v[76:79]
	v_mfma_f32_16x16x32_bf16 v[72:75], v[162:165], v[202:205], v[72:75]
	s_setprio 0
	s_barrier
	s_add_i32 s46, s7, s29
	v_lshl_add_u64 v[150:151], s[22:23], 0, v[130:131]
	s_mov_b32 m0, s46
	ds_read_b128 v[206:209], v179
	ds_read_b128 v[210:213], v179 offset:1024
	ds_read_b128 v[214:217], v179 offset:2048
	ds_read_b128 v[218:221], v179 offset:3072
	global_load_lds_dwordx4 v[150:151], off
	v_lshl_add_u64 v[222:223], s[22:23], 0, v[134:135]
	s_add_i32 m0, s46, 0x2000
	s_nop 0
	global_load_lds_dwordx4 v[222:223], off
	s_barrier
; #define PG8_STAGE(bufoff, gbase, voff) do { _Pragma("unroll") for (int _i = 0; _i < 2; ++_i) \
;         __builtin_amdgcn_global_load_lds((const unsigned*)((const char*)(gbase) + (voff)[_i]), (LAS unsigned*)(lds + (bufoff) + ldsw + _i * 8192), 16, 0, 0); } while (0)
; #define PG8_LDA(dst, b, h) do { _Pragma("unroll") for (int m = 0; m < 4; ++m) _Pragma("unroll") for (int k = 0; k < 2; ++k) dst[m][k] = *(const LAS bf16x8*)(lds + PG8_SA(b, h) + aoff + m * 2048 + k * 1024); } while (0)
; #define PG8_LDB(dst, b, h) do { _Pragma("unroll") for (int n = 0; n < 2; ++n) _Pragma("unroll") for (int k = 0; k < 2; ++k) dst[n][k] = *(const LAS bf16x8*)(lds + PG8_SB(b, h) + boff + n * 2048 + k * 1024); } while (0)
; #define PG8_MMA(ai, bj, At, Bt) do { __builtin_amdgcn_s_setprio(1); _Pragma("unroll") for (int m = 0; m < 4; ++m) _Pragma("unroll") for (int n = 0; n < 2; ++n) _Pragma("unroll") for (int k = 0; k < 2; ++k) \
;         acc[ai][bj][m][n] = __builtin_amdgcn_mfma_f32_16x16x32_bf16(Bt[n][k], At[m][k], acc[ai][bj][m][n], 0, 0, 0); __builtin_amdgcn_s_setprio(0); } while (0)
; #define PG8_WAIT_V(n) asm volatile("s_waitcnt vmcnt(" #n ")" ::: "memory")
; #define PG8_WAIT_L(n) asm volatile("s_waitcnt lgkmcnt(" #n ")" ::: "memory")
; #define PG8_BAR __builtin_amdgcn_s_barrier()
; #define PG8_SCHED __builtin_amdgcn_sched_barrier(0)
; template <class Epi>
; __device__ __forceinline__ void gemm_phase(LAS unsigned char* lds, const Gemm g, const StaticOrder& S, const Epi& E) {
;     ...
;             PG8_BAR; PG8_WAIT_L(0); PG8_MMA(0, 1, At, B1); PG8_BAR;
;             PG8_LDA(At, 0, 1); PG8_STAGE(PG8_SA(0, 0), a2, voffA);
;             PG8_BAR; PG8_WAIT_L(0); PG8_MMA(1, 0, At, B0); PG8_BAR; PG8_SCHED;
;             PG8_STAGE(PG8_SB(0, 1), b2 + hstepB, voffB);
;             PG8_WAIT_V(6); PG8_BAR; PG8_MMA(1, 1, At, B1); PG8_BAR;
;             PG8_LDB(B0, 1, 0); PG8_SCHED; PG8_LDA(At, 1, 0); PG8_STAGE(PG8_SA(0, 1), a2 + hstepA, voffA);
	s_waitcnt lgkmcnt(0)
	s_setprio 1
	s_waitcnt lgkmcnt(0)
	v_mfma_f32_16x16x32_bf16 v[116:119], v[206:209], v[166:169], v[116:119]
	v_mfma_f32_16x16x32_bf16 v[112:115], v[214:217], v[166:169], v[112:115]
	v_mfma_f32_16x16x32_bf16 v[100:103], v[206:209], v[182:185], v[100:103]
	v_mfma_f32_16x16x32_bf16 v[96:99], v[214:217], v[182:185], v[96:99]
	v_mfma_f32_16x16x32_bf16 v[84:87], v[206:209], v[190:193], v[84:87]
	v_mfma_f32_16x16x32_bf16 v[80:83], v[214:217], v[190:193], v[80:83]
	v_mfma_f32_16x16x32_bf16 v[68:71], v[206:209], v[198:201], v[68:71]
	v_mfma_f32_16x16x32_bf16 v[64:67], v[214:217], v[198:201], v[64:67]
	v_mfma_f32_16x16x32_bf16 v[116:119], v[210:213], v[170:173], v[116:119]
	v_mfma_f32_16x16x32_bf16 v[112:115], v[218:221], v[170:173], v[112:115]
	v_mfma_f32_16x16x32_bf16 v[100:103], v[210:213], v[186:189], v[100:103]
	v_mfma_f32_16x16x32_bf16 v[96:99], v[218:221], v[186:189], v[96:99]
	v_mfma_f32_16x16x32_bf16 v[84:87], v[210:213], v[194:197], v[84:87]
	v_mfma_f32_16x16x32_bf16 v[80:83], v[218:221], v[194:197], v[80:83]
	v_mfma_f32_16x16x32_bf16 v[68:71], v[210:213], v[202:205], v[68:71]
	v_mfma_f32_16x16x32_bf16 v[64:67], v[218:221], v[202:205], v[64:67]
	s_setprio 0
	s_mov_b32 m0, s19
	v_lshl_add_u64 v[224:225], s[24:25], 0, v[128:129]
	s_barrier
	ds_read_b128 v[166:169], v178 offset:16384
	ds_read_b128 v[170:173], v178 offset:17408
	ds_read_b128 v[182:185], v178 offset:18432
	ds_read_b128 v[186:189], v178 offset:19456
	ds_read_b128 v[190:193], v178 offset:20480
	ds_read_b128 v[194:197], v178 offset:21504
	ds_read_b128 v[198:201], v178 offset:22528
	ds_read_b128 v[202:205], v178 offset:23552
	global_load_lds_dwordx4 v[224:225], off
	v_lshl_add_u64 v[226:227], s[24:25], 0, v[132:133]
	s_mov_b32 m0, s30
	s_nop 0
	global_load_lds_dwordx4 v[226:227], off
	s_barrier
	s_waitcnt lgkmcnt(0)
	s_setprio 1
	s_waitcnt lgkmcnt(0)
	v_mfma_f32_16x16x32_bf16 v[60:63], v[146:149], v[166:169], v[60:63]
	v_mfma_f32_16x16x32_bf16 v[56:59], v[158:161], v[166:169], v[56:59]
	v_mfma_f32_16x16x32_bf16 v[44:47], v[146:149], v[182:185], v[44:47]
	v_mfma_f32_16x16x32_bf16 v[40:43], v[158:161], v[182:185], v[40:43]
	v_mfma_f32_16x16x32_bf16 v[28:31], v[146:149], v[190:193], v[28:31]
	v_mfma_f32_16x16x32_bf16 v[24:27], v[158:161], v[190:193], v[24:27]
	v_mfma_f32_16x16x32_bf16 v[12:15], v[146:149], v[198:201], v[12:15]
	v_mfma_f32_16x16x32_bf16 v[8:11], v[158:161], v[198:201], v[8:11]
	v_mfma_f32_16x16x32_bf16 v[60:63], v[154:157], v[170:173], v[60:63]
	v_mfma_f32_16x16x32_bf16 v[56:59], v[162:165], v[170:173], v[56:59]
	v_mfma_f32_16x16x32_bf16 v[44:47], v[154:157], v[186:189], v[44:47]
	v_mfma_f32_16x16x32_bf16 v[40:43], v[162:165], v[186:189], v[40:43]
	v_mfma_f32_16x16x32_bf16 v[28:31], v[154:157], v[194:197], v[28:31]
	v_mfma_f32_16x16x32_bf16 v[24:27], v[162:165], v[194:197], v[24:27]
	v_mfma_f32_16x16x32_bf16 v[12:15], v[154:157], v[202:205], v[12:15]
	v_mfma_f32_16x16x32_bf16 v[8:11], v[162:165], v[202:205], v[8:11]
	s_setprio 0
	s_barrier
	s_add_u32 s46, s22, 0x40000
	s_addc_u32 s47, s23, 0
	s_add_i32 s48, s38, s29
	v_lshl_add_u64 v[146:147], s[46:47], 0, v[130:131]
	s_mov_b32 m0, s48
	s_nop 0
	global_load_lds_dwordx4 v[146:147], off
	v_lshl_add_u64 v[146:147], s[46:47], 0, v[134:135]
	s_add_i32 m0, s48, 0x2000
	s_nop 0
	global_load_lds_dwordx4 v[146:147], off
	s_waitcnt vmcnt(6)
	s_barrier
	s_setprio 1
	v_mfma_f32_16x16x32_bf16 v[52:55], v[206:209], v[166:169], v[52:55]
	v_mfma_f32_16x16x32_bf16 v[48:51], v[214:217], v[166:169], v[48:51]
	v_mfma_f32_16x16x32_bf16 v[36:39], v[206:209], v[182:185], v[36:39]
	v_mfma_f32_16x16x32_bf16 v[32:35], v[214:217], v[182:185], v[32:35]
	v_mfma_f32_16x16x32_bf16 v[20:23], v[206:209], v[190:193], v[20:23]
	v_mfma_f32_16x16x32_bf16 v[16:19], v[214:217], v[190:193], v[16:19]
	v_mfma_f32_16x16x32_bf16 v[4:7], v[206:209], v[198:201], v[4:7]
	v_mfma_f32_16x16x32_bf16 v[0:3], v[214:217], v[198:201], v[0:3]
	v_mfma_f32_16x16x32_bf16 v[52:55], v[210:213], v[170:173], v[52:55]
	v_mfma_f32_16x16x32_bf16 v[48:51], v[218:221], v[170:173], v[48:51]
	v_mfma_f32_16x16x32_bf16 v[36:39], v[210:213], v[186:189], v[36:39]
	v_mfma_f32_16x16x32_bf16 v[32:35], v[218:221], v[186:189], v[32:35]
	v_mfma_f32_16x16x32_bf16 v[20:23], v[210:213], v[194:197], v[20:23]
	v_mfma_f32_16x16x32_bf16 v[16:19], v[218:221], v[194:197], v[16:19]
	v_mfma_f32_16x16x32_bf16 v[4:7], v[210:213], v[202:205], v[4:7]
	v_mfma_f32_16x16x32_bf16 v[0:3], v[218:221], v[202:205], v[0:3]
	s_setprio 0
	s_add_i32 s46, 0, 0x18000
	v_add_u32_e32 v162, s46, v175
	s_barrier
	ds_read_b128 v[146:149], v162
	ds_read_b128 v[154:157], v162 offset:1024
	ds_read_b128 v[158:161], v162 offset:2048
	ds_read_b128 v[162:165], v162 offset:3072
	s_add_u32 s24, s24, 0x40000
	s_addc_u32 s25, s25, 0
	s_mov_b32 m0, s31
	v_lshl_add_u64 v[206:207], s[24:25], 0, v[128:129]
	ds_read_b128 v[166:169], v178 offset:32768
	ds_read_b128 v[170:173], v178 offset:33792
	ds_read_b128 v[182:185], v178 offset:34816
	ds_read_b128 v[186:189], v178 offset:35840
	ds_read_b128 v[190:193], v178 offset:36864
	ds_read_b128 v[194:197], v178 offset:37888
	ds_read_b128 v[198:201], v178 offset:38912
	ds_read_b128 v[202:205], v178 offset:39936
	global_load_lds_dwordx4 v[206:207], off
	v_lshl_add_u64 v[206:207], s[24:25], 0, v[132:133]
	s_mov_b32 m0, s33
	s_nop 0
	global_load_lds_dwordx4 v[206:207], off
	s_waitcnt lgkmcnt(8)
	s_barrier
; #define PG8_STAGE(bufoff, gbase, voff) do { _Pragma("unroll") for (int _i = 0; _i < 2; ++_i) \
;         __builtin_amdgcn_global_load_lds((const unsigned*)((const char*)(gbase) + (voff)[_i]), (LAS unsigned*)(lds + (bufoff) + ldsw + _i * 8192), 16, 0, 0); } while (0)
; #define PG8_LDA(dst, b, h) do { _Pragma("unroll") for (int m = 0; m < 4; ++m) _Pragma("unroll") for (int k = 0; k < 2; ++k) dst[m][k] = *(const LAS bf16x8*)(lds + PG8_SA(b, h) + aoff + m * 2048 + k * 1024); } while (0)
; #define PG8_LDB(dst, b, h) do { _Pragma("unroll") for (int n = 0; n < 2; ++n) _Pragma("unroll") for (int k = 0; k < 2; ++k) dst[n][k] = *(const LAS bf16x8*)(lds + PG8_SB(b, h) + boff + n * 2048 + k * 1024); } while (0)
; #define PG8_MMA(ai, bj, At, Bt) do { __builtin_amdgcn_s_setprio(1); _Pragma("unroll") for (int m = 0; m < 4; ++m) _Pragma("unroll") for (int n = 0; n < 2; ++n) _Pragma("unroll") for (int k = 0; k < 2; ++k) \
;         acc[ai][bj][m][n] = __builtin_amdgcn_mfma_f32_16x16x32_bf16(Bt[n][k], At[m][k], acc[ai][bj][m][n], 0, 0, 0); __builtin_amdgcn_s_setprio(0); } while (0)
; #define PG8_WAIT_L(n) asm volatile("s_waitcnt lgkmcnt(" #n ")" ::: "memory")
; #define PG8_BAR __builtin_amdgcn_s_barrier()
; #define PG8_SCHED __builtin_amdgcn_sched_barrier(0)
; template <class Epi>
; __device__ __forceinline__ void gemm_phase(LAS unsigned char* lds, const Gemm g, const StaticOrder& S, const Epi& E) {
;     ...
;             PG8_WAIT_L(8); PG8_BAR; PG8_WAIT_L(0); PG8_MMA(0, 0, At, B0); PG8_BAR; PG8_SCHED;
;             PG8_LDB(B1, 1, 1); PG8_STAGE(PG8_SB(1, 0), b3, voffB);
;             PG8_BAR; PG8_WAIT_L(0); PG8_MMA(0, 1, At, B1); PG8_BAR;
;             PG8_LDA(At, 1, 1); PG8_STAGE(PG8_SA(1, 0), a3, voffA);
;             PG8_BAR; PG8_WAIT_L(0); PG8_MMA(1, 0, At, B0); PG8_BAR; PG8_SCHED;
;             PG8_STAGE(PG8_SB(1, 1), b3 + hstepB, voffB);
	s_waitcnt lgkmcnt(0)
	s_setprio 1
	s_waitcnt lgkmcnt(0)
	v_mfma_f32_16x16x32_bf16 v[124:127], v[146:149], v[166:169], v[124:127]
	v_mfma_f32_16x16x32_bf16 v[120:123], v[158:161], v[166:169], v[120:123]
	v_mfma_f32_16x16x32_bf16 v[108:111], v[146:149], v[182:185], v[108:111]
	v_mfma_f32_16x16x32_bf16 v[104:107], v[158:161], v[182:185], v[104:107]
	v_mfma_f32_16x16x32_bf16 v[92:95], v[146:149], v[190:193], v[92:95]
	v_mfma_f32_16x16x32_bf16 v[88:91], v[158:161], v[190:193], v[88:91]
	v_mfma_f32_16x16x32_bf16 v[76:79], v[146:149], v[198:201], v[76:79]
	v_mfma_f32_16x16x32_bf16 v[72:75], v[158:161], v[198:201], v[72:75]
	v_mfma_f32_16x16x32_bf16 v[124:127], v[154:157], v[170:173], v[124:127]
	v_mfma_f32_16x16x32_bf16 v[120:123], v[162:165], v[170:173], v[120:123]
	v_mfma_f32_16x16x32_bf16 v[108:111], v[154:157], v[186:189], v[108:111]
	v_mfma_f32_16x16x32_bf16 v[104:107], v[162:165], v[186:189], v[104:107]
	v_mfma_f32_16x16x32_bf16 v[92:95], v[154:157], v[194:197], v[92:95]
	v_mfma_f32_16x16x32_bf16 v[88:91], v[162:165], v[194:197], v[88:91]
	v_mfma_f32_16x16x32_bf16 v[76:79], v[154:157], v[202:205], v[76:79]
	v_mfma_f32_16x16x32_bf16 v[72:75], v[162:165], v[202:205], v[72:75]
	s_setprio 0
	s_barrier
	s_add_i32 s24, 0, 0x1c000
	s_add_i32 s25, s46, s29
	v_add_u32_e32 v181, s24, v175
	v_lshl_add_u64 v[150:151], v[150:151], 0, s[4:5]
	s_mov_b32 m0, s25
	ds_read_b128 v[206:209], v181
	ds_read_b128 v[210:213], v181 offset:1024
	ds_read_b128 v[214:217], v181 offset:2048
	ds_read_b128 v[218:221], v181 offset:3072
	global_load_lds_dwordx4 v[150:151], off
	v_lshl_add_u64 v[150:151], v[222:223], 0, s[4:5]
	s_add_i32 m0, s25, 0x2000
	s_nop 0
	global_load_lds_dwordx4 v[150:151], off
	s_barrier
	s_waitcnt lgkmcnt(0)
	s_setprio 1
	s_waitcnt lgkmcnt(0)
	v_mfma_f32_16x16x32_bf16 v[116:119], v[206:209], v[166:169], v[116:119]
	v_mfma_f32_16x16x32_bf16 v[112:115], v[214:217], v[166:169], v[112:115]
	v_mfma_f32_16x16x32_bf16 v[100:103], v[206:209], v[182:185], v[100:103]
	v_mfma_f32_16x16x32_bf16 v[96:99], v[214:217], v[182:185], v[96:99]
	v_mfma_f32_16x16x32_bf16 v[84:87], v[206:209], v[190:193], v[84:87]
	v_mfma_f32_16x16x32_bf16 v[80:83], v[214:217], v[190:193], v[80:83]
	v_mfma_f32_16x16x32_bf16 v[68:71], v[206:209], v[198:201], v[68:71]
	v_mfma_f32_16x16x32_bf16 v[64:67], v[214:217], v[198:201], v[64:67]
	v_mfma_f32_16x16x32_bf16 v[116:119], v[210:213], v[170:173], v[116:119]
	v_mfma_f32_16x16x32_bf16 v[112:115], v[218:221], v[170:173], v[112:115]
	v_mfma_f32_16x16x32_bf16 v[100:103], v[210:213], v[186:189], v[100:103]
	v_mfma_f32_16x16x32_bf16 v[96:99], v[218:221], v[186:189], v[96:99]
	v_mfma_f32_16x16x32_bf16 v[84:87], v[210:213], v[194:197], v[84:87]
	v_mfma_f32_16x16x32_bf16 v[80:83], v[218:221], v[194:197], v[80:83]
	v_mfma_f32_16x16x32_bf16 v[68:71], v[210:213], v[202:205], v[68:71]
	v_mfma_f32_16x16x32_bf16 v[64:67], v[218:221], v[202:205], v[64:67]
	s_setprio 0
	s_mov_b32 m0, s35
	v_lshl_add_u64 v[150:151], v[224:225], 0, s[4:5]
	s_barrier
	ds_read_b128 v[166:169], v178 offset:49152
	ds_read_b128 v[170:173], v178 offset:50176
	ds_read_b128 v[182:185], v178 offset:51200
	ds_read_b128 v[186:189], v178 offset:52224
	ds_read_b128 v[190:193], v178 offset:53248
	ds_read_b128 v[194:197], v178 offset:54272
	ds_read_b128 v[198:201], v178 offset:55296
	ds_read_b128 v[202:205], v178 offset:56320
	global_load_lds_dwordx4 v[150:151], off
	v_lshl_add_u64 v[150:151], v[226:227], 0, s[4:5]
	s_mov_b32 m0, s36
	s_nop 0
	global_load_lds_dwordx4 v[150:151], off
	s_barrier
	s_waitcnt lgkmcnt(0)
	s_setprio 1
	s_waitcnt lgkmcnt(0)
	v_mfma_f32_16x16x32_bf16 v[60:63], v[146:149], v[166:169], v[60:63]
	v_mfma_f32_16x16x32_bf16 v[56:59], v[158:161], v[166:169], v[56:59]
	v_mfma_f32_16x16x32_bf16 v[44:47], v[146:149], v[182:185], v[44:47]
	v_mfma_f32_16x16x32_bf16 v[40:43], v[158:161], v[182:185], v[40:43]
	v_mfma_f32_16x16x32_bf16 v[28:31], v[146:149], v[190:193], v[28:31]
	v_mfma_f32_16x16x32_bf16 v[24:27], v[158:161], v[190:193], v[24:27]
	v_mfma_f32_16x16x32_bf16 v[12:15], v[146:149], v[198:201], v[12:15]
	v_mfma_f32_16x16x32_bf16 v[8:11], v[158:161], v[198:201], v[8:11]
	v_mfma_f32_16x16x32_bf16 v[60:63], v[154:157], v[170:173], v[60:63]
	v_mfma_f32_16x16x32_bf16 v[56:59], v[162:165], v[170:173], v[56:59]
	v_mfma_f32_16x16x32_bf16 v[44:47], v[154:157], v[186:189], v[44:47]
	v_mfma_f32_16x16x32_bf16 v[40:43], v[162:165], v[186:189], v[40:43]
	v_mfma_f32_16x16x32_bf16 v[28:31], v[154:157], v[194:197], v[28:31]
	v_mfma_f32_16x16x32_bf16 v[24:27], v[162:165], v[194:197], v[24:27]
	v_mfma_f32_16x16x32_bf16 v[12:15], v[154:157], v[202:205], v[12:15]
	v_mfma_f32_16x16x32_bf16 v[8:11], v[162:165], v[202:205], v[8:11]
	s_setprio 0
	s_barrier
	s_add_u32 s22, s22, 0x40080
	s_addc_u32 s23, s23, 0
	s_add_i32 s24, s24, s29
	v_lshl_add_u64 v[146:147], s[22:23], 0, v[130:131]
	s_mov_b32 m0, s24
	s_nop 0
	global_load_lds_dwordx4 v[146:147], off
	v_lshl_add_u64 v[146:147], s[22:23], 0, v[134:135]
	s_add_i32 m0, s24, 0x2000
	s_nop 0
	global_load_lds_dwordx4 v[146:147], off
	s_waitcnt vmcnt(6)
	s_barrier
; __device__ __forceinline__ unsigned pk2(float lo, float hi) { const f32x2 v = (f32x2){lo, hi}; const bf16x2_t b = __builtin_convertvector(v, bf16x2_t); return __builtin_bit_cast(unsigned, b); }
; #define PG8_MMA(ai, bj, At, Bt) do { __builtin_amdgcn_s_setprio(1); _Pragma("unroll") for (int m = 0; m < 4; ++m) _Pragma("unroll") for (int n = 0; n < 2; ++n) _Pragma("unroll") for (int k = 0; k < 2; ++k) \
;         acc[ai][bj][m][n] = __builtin_amdgcn_mfma_f32_16x16x32_bf16(Bt[n][k], At[m][k], acc[ai][bj][m][n], 0, 0, 0); __builtin_amdgcn_s_setprio(0); } while (0)
; #define PG8_WAIT_V(n) asm volatile("s_waitcnt vmcnt(" #n ")" ::: "memory")
; #define PG8_BAR __builtin_amdgcn_s_barrier()
;     __device__ __forceinline__ void operator()(const f32x4 (&acc)[2][2][4][2], const Unit& u, int wr, int wc, int fr, int fq, const float (&)[8]) const {
;     ...
;         const int col0 = u.pn * BM + wc * 32 + 8 * fq;
; #pragma unroll
;         for (int ai = 0; ai < 2; ++ai)
; #pragma unroll
;             for (int m = 0; m < 4; ++m) { const int row = row0 + ai * HALF + m * 16; const float rs = rsqrtf(ep[ai * 4 + m] * (1.0f / 1024.0f) + EPS);
;                 u16* rowp = O + (size_t)row * ldc + col0;
; #pragma unroll
;                 for (int bj = 0; bj < 2; ++bj) { f32x4 v0 = acc[ai][bj][m][0] * rs, v1 = acc[ai][bj][m][1] * rs;
;                     if (ACT == 1) {
; #pragma unroll
;                         for (int j = 0; j < 4; ++j) { const float a0 = fmaxf(v0[j], 0.f), a1 = fmaxf(v1[j], 0.f); v0[j] = a0 * a0; v1[j] = a1 * a1; } }
;                     u32x4 w; w.x = pk2(v0[0], v0[1]); w.y = pk2(v0[2], v0[3]); w.z = pk2(v1[0], v1[1]); w.w = pk2(v1[2], v1[3]);
;                     *(u32x4*)(rowp + bj * HALF) = w; } }
; template <class Epi>
; __device__ __forceinline__ void gemm_phase(LAS unsigned char* lds, const Gemm g, const StaticOrder& S, const Epi& E) {
;     ...
;             PG8_WAIT_V(6); PG8_BAR; PG8_MMA(1, 1, At, B1); PG8_BAR;
;         }
;         E(acc, cur, wr, wc, fr, fq, epre);
	s_setprio 1
	v_mfma_f32_16x16x32_bf16 v[52:55], v[206:209], v[166:169], v[52:55]
	v_mfma_f32_16x16x32_bf16 v[48:51], v[214:217], v[166:169], v[48:51]
	v_mfma_f32_16x16x32_bf16 v[36:39], v[206:209], v[182:185], v[36:39]
	v_mfma_f32_16x16x32_bf16 v[32:35], v[214:217], v[182:185], v[32:35]
	v_mfma_f32_16x16x32_bf16 v[20:23], v[206:209], v[190:193], v[20:23]
	v_mfma_f32_16x16x32_bf16 v[16:19], v[214:217], v[190:193], v[16:19]
	v_mfma_f32_16x16x32_bf16 v[4:7], v[206:209], v[198:201], v[4:7]
	v_mfma_f32_16x16x32_bf16 v[0:3], v[214:217], v[198:201], v[0:3]
	v_mfma_f32_16x16x32_bf16 v[52:55], v[210:213], v[170:173], v[52:55]
	v_mfma_f32_16x16x32_bf16 v[48:51], v[218:221], v[170:173], v[48:51]
	v_mfma_f32_16x16x32_bf16 v[36:39], v[210:213], v[186:189], v[36:39]
	v_mfma_f32_16x16x32_bf16 v[32:35], v[218:221], v[186:189], v[32:35]
	v_mfma_f32_16x16x32_bf16 v[20:23], v[210:213], v[194:197], v[20:23]
	v_mfma_f32_16x16x32_bf16 v[16:19], v[218:221], v[194:197], v[16:19]
	v_mfma_f32_16x16x32_bf16 v[4:7], v[210:213], v[202:205], v[4:7]
	v_mfma_f32_16x16x32_bf16 v[0:3], v[218:221], v[202:205], v[0:3]
	s_setprio 0
	s_add_i32 s45, s45, 2
	s_add_u32 s20, s20, 0x100
	s_addc_u32 s21, s21, 0
	s_add_u32 s43, s43, 0x100
	s_addc_u32 s44, s44, 0
	s_cmp_gt_u32 s45, 13
	s_barrier
	s_cbranch_scc0 .LBB0_770
	s_bfe_u32 vcc_lo, s18, 0x20003
	s_lshl_b32 vcc_lo, vcc_lo, 10
	s_add_i32 vcc_lo, vcc_lo, 0x20010
	v_lshl_add_u32 v236, v174, 2, vcc_lo
	ds_read_b32 v228, v236
	ds_read_b32 v229, v236 offset:64
	ds_read_b32 v230, v236 offset:128
	ds_read_b32 v231, v236 offset:192
	ds_read_b32 v232, v236 offset:512
	ds_read_b32 v233, v236 offset:576
	ds_read_b32 v234, v236 offset:640
	ds_read_b32 v235, v236 offset:704
	s_waitcnt lgkmcnt(0)
	s_add_u32 vcc_lo, s41, 0x40080
	s_addc_u32 vcc_hi, s13, 0
	s_add_i32 m0, s19, 0xc000
	v_lshl_add_u64 v[236:237], vcc, 0, v[138:139]
	v_lshl_add_u64 v[238:239], vcc, 0, v[140:141]
	global_load_lds_dwordx4 v[236:237], off
	s_add_i32 m0, s19, 0xe000
	s_nop 0
	global_load_lds_dwordx4 v[238:239], off
	v_lshl_add_u32 v148, s18, 8, v174
	v_ashrrev_i32_e32 v149, 31, v148
	v_or_b32_e32 v172, 16, v148
	v_ashrrev_i32_e32 v173, 31, v172
	v_or_b32_e32 v168, 32, v148
	v_or_b32_e32 v164, 48, v148
	v_ashrrev_i32_e32 v169, 31, v168
	v_ashrrev_i32_e32 v165, 31, v164
	v_add_u32_e32 v162, 0x80, v148
	v_add_u32_e32 v156, 0x90, v148
	v_ashrrev_i32_e32 v163, 31, v162
	v_ashrrev_i32_e32 v157, 31, v156
	v_add_u32_e32 v150, 0xa0, v148
	v_ashrrev_i32_e32 v151, 31, v150
	v_add_u32_e32 v146, 0xb0, v148
	v_ashrrev_i32_e32 v147, 31, v146
	v_lshl_or_b32 v166, s40, 8, v176
	v_ashrrev_i32_e32 v167, 31, v166
	v_lshlrev_b64 v[170:171], 13, v[148:149]
	v_lshlrev_b64 v[148:149], 1, v[166:167]
	v_lshl_add_u64 v[166:167], s[96:97], 0, v[170:171]
	v_lshl_add_u64 v[212:213], v[166:167], 0, v[148:149]
	s_mov_b32 s40, s10
	s_mov_b32 s18, s12
	s_mov_b64 s[22:23], s[16:17]
	s_mov_b64 s[20:21], s[14:15]
	s_waitcnt vmcnt(10)
	s_waitcnt lgkmcnt(0)
	s_waitcnt lgkmcnt(0)
	v_mov_b32_e32 v184, v228
	v_pk_mul_f32 v[120:121], v[120:121], v[184:185] op_sel_hi:[1,0]
	v_pk_mul_f32 v[126:127], v[126:127], v[184:185] op_sel_hi:[1,0]
	v_pk_mul_f32 v[124:125], v[124:125], v[184:185] op_sel_hi:[1,0]
	v_pk_mul_f32 v[122:123], v[122:123], v[184:185] op_sel_hi:[1,0]
	v_max_f32_e32 v120, 0, v120
	v_max_f32_e32 v121, 0, v121
	v_max_f32_e32 v124, 0, v124
	v_max_f32_e32 v125, 0, v125
	v_pk_mul_f32 v[190:191], v[120:121], v[120:121]
	v_max_f32_e32 v120, 0, v126
	v_max_f32_e32 v122, 0, v122
	v_max_f32_e32 v121, 0, v127
	v_max_f32_e32 v123, 0, v123
	v_pk_mul_f32 v[124:125], v[124:125], v[124:125]
	v_pk_mul_f32 v[126:127], v[120:121], v[120:121]
	v_pk_mul_f32 v[194:195], v[122:123], v[122:123]
	v_pk_mul_f32 v[114:115], v[114:115], v[184:185] op_sel_hi:[1,0]
	v_cvt_pk_bf16_f32 v120, v124, v125
	v_cvt_pk_bf16_f32 v121, v126, v127
	v_cvt_pk_bf16_f32 v122, v190, v191
	v_cvt_pk_bf16_f32 v123, v194, v195
	v_pk_mul_f32 v[116:117], v[116:117], v[184:185] op_sel_hi:[1,0]
	v_pk_mul_f32 v[112:113], v[112:113], v[184:185] op_sel_hi:[1,0]
	v_max_f32_e32 v114, 0, v114
	v_max_f32_e32 v115, 0, v115
	global_store_dwordx4 v[212:213], v[120:123], off
	v_pk_mul_f32 v[118:119], v[118:119], v[184:185] op_sel_hi:[1,0]
	v_max_f32_e32 v116, 0, v116
	v_max_f32_e32 v112, 0, v112
	v_max_f32_e32 v117, 0, v117
	v_max_f32_e32 v113, 0, v113
	v_pk_mul_f32 v[122:123], v[114:115], v[114:115]
	v_pk_mul_f32 v[116:117], v[116:117], v[116:117]
	v_pk_mul_f32 v[120:121], v[112:113], v[112:113]
	v_max_f32_e32 v112, 0, v118
	v_max_f32_e32 v113, 0, v119
	v_pk_mul_f32 v[118:119], v[112:113], v[112:113]
	v_cvt_pk_bf16_f32 v112, v116, v117
	v_cvt_pk_bf16_f32 v113, v118, v119
	v_cvt_pk_bf16_f32 v114, v120, v121
	v_cvt_pk_bf16_f32 v115, v122, v123
	global_store_dwordx4 v[212:213], v[112:115], off offset:256
	s_nop 1
	v_mov_b32_e32 v112, v229
	v_pk_mul_f32 v[104:105], v[104:105], v[112:113] op_sel_hi:[1,0]
	v_pk_mul_f32 v[110:111], v[110:111], v[112:113] op_sel_hi:[1,0]
	v_pk_mul_f32 v[108:109], v[108:109], v[112:113] op_sel_hi:[1,0]
	v_pk_mul_f32 v[106:107], v[106:107], v[112:113] op_sel_hi:[1,0]
	v_max_f32_e32 v104, 0, v104
	v_max_f32_e32 v105, 0, v105
	v_lshlrev_b64 v[114:115], 13, v[172:173]
	v_max_f32_e32 v108, 0, v108
	v_max_f32_e32 v109, 0, v109
	v_pk_mul_f32 v[116:117], v[104:105], v[104:105]
	v_max_f32_e32 v104, 0, v110
	v_max_f32_e32 v106, 0, v106
	v_max_f32_e32 v105, 0, v111
	v_max_f32_e32 v107, 0, v107
	v_lshl_add_u64 v[114:115], s[96:97], 0, v[114:115]
	v_pk_mul_f32 v[108:109], v[108:109], v[108:109]
	v_pk_mul_f32 v[110:111], v[104:105], v[104:105]
	v_pk_mul_f32 v[118:119], v[106:107], v[106:107]
	v_pk_mul_f32 v[96:97], v[96:97], v[112:113] op_sel_hi:[1,0]
	v_lshl_add_u64 v[114:115], v[114:115], 0, v[148:149]
	v_cvt_pk_bf16_f32 v104, v108, v109
	v_cvt_pk_bf16_f32 v105, v110, v111
	v_cvt_pk_bf16_f32 v106, v116, v117
	v_cvt_pk_bf16_f32 v107, v118, v119
	v_pk_mul_f32 v[102:103], v[102:103], v[112:113] op_sel_hi:[1,0]
	v_max_f32_e32 v96, 0, v96
	v_max_f32_e32 v97, 0, v97
	global_store_dwordx4 v[114:115], v[104:107], off
	v_pk_mul_f32 v[100:101], v[100:101], v[112:113] op_sel_hi:[1,0]
	v_pk_mul_f32 v[98:99], v[98:99], v[112:113] op_sel_hi:[1,0]
	v_pk_mul_f32 v[104:105], v[96:97], v[96:97]
	v_max_f32_e32 v96, 0, v102
	v_max_f32_e32 v97, 0, v103
	v_max_f32_e32 v100, 0, v100
	v_max_f32_e32 v101, 0, v101
	v_pk_mul_f32 v[100:101], v[100:101], v[100:101]
	v_pk_mul_f32 v[108:109], v[96:97], v[96:97]
	v_cvt_pk_bf16_f32 v96, v100, v101
	s_waitcnt lgkmcnt(0)
; __device__ __forceinline__ unsigned pk2(float lo, float hi) { const f32x2 v = (f32x2){lo, hi}; const bf16x2_t b = __builtin_convertvector(v, bf16x2_t); return __builtin_bit_cast(unsigned, b); }
;     __device__ __forceinline__ void operator()(const f32x4 (&acc)[2][2][4][2], const Unit& u, int wr, int wc, int fr, int fq, const float (&)[8]) const {
;     ...
;             for (int m = 0; m < 4; ++m) { const int row = row0 + ai * HALF + m * 16; const float rs = rsqrtf(ep[ai * 4 + m] * (1.0f / 1024.0f) + EPS);
;                 u16* rowp = O + (size_t)row * ldc + col0;
; #pragma unroll
;                 for (int bj = 0; bj < 2; ++bj) { f32x4 v0 = acc[ai][bj][m][0] * rs, v1 = acc[ai][bj][m][1] * rs;
;                     if (ACT == 1) {
; #pragma unroll
;                         for (int j = 0; j < 4; ++j) { const float a0 = fmaxf(v0[j], 0.f), a1 = fmaxf(v1[j], 0.f); v0[j] = a0 * a0; v1[j] = a1 * a1; } }
;                     u32x4 w; w.x = pk2(v0[0], v0[1]); w.y = pk2(v0[2], v0[3]); w.z = pk2(v1[0], v1[1]); w.w = pk2(v1[2], v1[3]);
;                     *(u32x4*)(rowp + bj * HALF) = w; } }
	v_max_f32_e32 v98, 0, v98
	v_max_f32_e32 v99, 0, v99
	v_pk_mul_f32 v[110:111], v[98:99], v[98:99]
	v_cvt_pk_bf16_f32 v97, v108, v109
	v_cvt_pk_bf16_f32 v98, v104, v105
	v_cvt_pk_bf16_f32 v99, v110, v111
	global_store_dwordx4 v[114:115], v[96:99], off offset:256
	s_waitcnt lgkmcnt(0)
	s_nop 0
	s_nop 0
	s_nop 0
	s_nop 1
	v_lshlrev_b64 v[98:99], 13, v[168:169]
	v_lshl_add_u64 v[98:99], s[96:97], 0, v[98:99]
	v_lshl_add_u64 v[98:99], v[98:99], 0, v[148:149]
	v_mov_b32_e32 v100, v230
	v_pk_mul_f32 v[88:89], v[88:89], v[100:101] op_sel_hi:[1,0]
	v_pk_mul_f32 v[94:95], v[94:95], v[100:101] op_sel_hi:[1,0]
	v_pk_mul_f32 v[92:93], v[92:93], v[100:101] op_sel_hi:[1,0]
	v_pk_mul_f32 v[90:91], v[90:91], v[100:101] op_sel_hi:[1,0]
	v_max_f32_e32 v88, 0, v88
	v_max_f32_e32 v89, 0, v89
	v_max_f32_e32 v92, 0, v92
	v_max_f32_e32 v93, 0, v93
	v_pk_mul_f32 v[102:103], v[88:89], v[88:89]
	v_max_f32_e32 v88, 0, v94
	v_max_f32_e32 v90, 0, v90
	v_max_f32_e32 v89, 0, v95
	v_max_f32_e32 v91, 0, v91
	v_pk_mul_f32 v[92:93], v[92:93], v[92:93]
	v_pk_mul_f32 v[94:95], v[88:89], v[88:89]
	v_pk_mul_f32 v[104:105], v[90:91], v[90:91]
	v_pk_mul_f32 v[82:83], v[82:83], v[100:101] op_sel_hi:[1,0]
	v_cvt_pk_bf16_f32 v88, v92, v93
	v_cvt_pk_bf16_f32 v89, v94, v95
	v_cvt_pk_bf16_f32 v90, v102, v103
	v_cvt_pk_bf16_f32 v91, v104, v105
	v_pk_mul_f32 v[84:85], v[84:85], v[100:101] op_sel_hi:[1,0]
	v_pk_mul_f32 v[80:81], v[80:81], v[100:101] op_sel_hi:[1,0]
	v_max_f32_e32 v82, 0, v82
	v_max_f32_e32 v83, 0, v83
	global_store_dwordx4 v[98:99], v[88:91], off
	v_pk_mul_f32 v[86:87], v[86:87], v[100:101] op_sel_hi:[1,0]
	v_max_f32_e32 v84, 0, v84
	v_max_f32_e32 v80, 0, v80
	v_max_f32_e32 v85, 0, v85
	v_max_f32_e32 v81, 0, v81
	v_pk_mul_f32 v[90:91], v[82:83], v[82:83]
	v_pk_mul_f32 v[84:85], v[84:85], v[84:85]
	v_pk_mul_f32 v[88:89], v[80:81], v[80:81]
	v_max_f32_e32 v80, 0, v86
	v_max_f32_e32 v81, 0, v87
	v_pk_mul_f32 v[86:87], v[80:81], v[80:81]
	v_cvt_pk_bf16_f32 v80, v84, v85
	v_cvt_pk_bf16_f32 v81, v86, v87
	v_cvt_pk_bf16_f32 v82, v88, v89
	v_cvt_pk_bf16_f32 v83, v90, v91
	global_store_dwordx4 v[98:99], v[80:83], off offset:256
	s_nop 1
	v_mov_b32_e32 v80, v231
	v_pk_mul_f32 v[72:73], v[72:73], v[80:81] op_sel_hi:[1,0]
	v_pk_mul_f32 v[78:79], v[78:79], v[80:81] op_sel_hi:[1,0]
	v_pk_mul_f32 v[76:77], v[76:77], v[80:81] op_sel_hi:[1,0]
	v_pk_mul_f32 v[74:75], v[74:75], v[80:81] op_sel_hi:[1,0]
	v_max_f32_e32 v72, 0, v72
	v_max_f32_e32 v73, 0, v73
	v_lshlrev_b64 v[82:83], 13, v[164:165]
	v_max_f32_e32 v76, 0, v76
	v_max_f32_e32 v77, 0, v77
	v_pk_mul_f32 v[84:85], v[72:73], v[72:73]
	v_max_f32_e32 v72, 0, v78
	v_max_f32_e32 v74, 0, v74
	v_max_f32_e32 v73, 0, v79
	v_max_f32_e32 v75, 0, v75
	v_lshl_add_u64 v[82:83], s[96:97], 0, v[82:83]
	v_pk_mul_f32 v[76:77], v[76:77], v[76:77]
	v_pk_mul_f32 v[78:79], v[72:73], v[72:73]
	v_pk_mul_f32 v[86:87], v[74:75], v[74:75]
	v_pk_mul_f32 v[64:65], v[64:65], v[80:81] op_sel_hi:[1,0]
	v_lshl_add_u64 v[82:83], v[82:83], 0, v[148:149]
	v_cvt_pk_bf16_f32 v72, v76, v77
	v_cvt_pk_bf16_f32 v73, v78, v79
	v_cvt_pk_bf16_f32 v74, v84, v85
	v_cvt_pk_bf16_f32 v75, v86, v87
	v_pk_mul_f32 v[70:71], v[70:71], v[80:81] op_sel_hi:[1,0]
	v_max_f32_e32 v64, 0, v64
	v_max_f32_e32 v65, 0, v65
	global_store_dwordx4 v[82:83], v[72:75], off
	v_pk_mul_f32 v[68:69], v[68:69], v[80:81] op_sel_hi:[1,0]
	v_pk_mul_f32 v[66:67], v[66:67], v[80:81] op_sel_hi:[1,0]
	v_pk_mul_f32 v[72:73], v[64:65], v[64:65]
	v_max_f32_e32 v64, 0, v70
	v_max_f32_e32 v65, 0, v71
	v_max_f32_e32 v68, 0, v68
	v_max_f32_e32 v69, 0, v69
	v_pk_mul_f32 v[68:69], v[68:69], v[68:69]
	v_pk_mul_f32 v[76:77], v[64:65], v[64:65]
	v_cvt_pk_bf16_f32 v64, v68, v69
	s_waitcnt lgkmcnt(0)
	v_max_f32_e32 v66, 0, v66
	v_max_f32_e32 v67, 0, v67
	v_pk_mul_f32 v[78:79], v[66:67], v[66:67]
	v_cvt_pk_bf16_f32 v65, v76, v77
	v_cvt_pk_bf16_f32 v66, v72, v73
	v_cvt_pk_bf16_f32 v67, v78, v79
	global_store_dwordx4 v[82:83], v[64:67], off offset:256
	s_waitcnt lgkmcnt(0)
	s_nop 0
	s_nop 0
	s_nop 0
	s_nop 1
	v_lshlrev_b64 v[66:67], 13, v[162:163]
	v_lshl_add_u64 v[66:67], s[96:97], 0, v[66:67]
	v_lshl_add_u64 v[66:67], v[66:67], 0, v[148:149]
	v_mov_b32_e32 v68, v232
	v_pk_mul_f32 v[56:57], v[56:57], v[68:69] op_sel_hi:[1,0]
	v_pk_mul_f32 v[62:63], v[62:63], v[68:69] op_sel_hi:[1,0]
	v_pk_mul_f32 v[60:61], v[60:61], v[68:69] op_sel_hi:[1,0]
	v_pk_mul_f32 v[58:59], v[58:59], v[68:69] op_sel_hi:[1,0]
	v_max_f32_e32 v56, 0, v56
	v_max_f32_e32 v57, 0, v57
	v_max_f32_e32 v60, 0, v60
	v_max_f32_e32 v61, 0, v61
	v_pk_mul_f32 v[70:71], v[56:57], v[56:57]
	v_max_f32_e32 v56, 0, v62
	v_max_f32_e32 v58, 0, v58
	v_max_f32_e32 v57, 0, v63
	v_max_f32_e32 v59, 0, v59
	v_pk_mul_f32 v[60:61], v[60:61], v[60:61]
	v_pk_mul_f32 v[62:63], v[56:57], v[56:57]
	v_pk_mul_f32 v[72:73], v[58:59], v[58:59]
	v_pk_mul_f32 v[50:51], v[50:51], v[68:69] op_sel_hi:[1,0]
	v_cvt_pk_bf16_f32 v56, v60, v61
	v_cvt_pk_bf16_f32 v57, v62, v63
	v_cvt_pk_bf16_f32 v58, v70, v71
	v_cvt_pk_bf16_f32 v59, v72, v73
	v_pk_mul_f32 v[52:53], v[52:53], v[68:69] op_sel_hi:[1,0]
	v_pk_mul_f32 v[48:49], v[48:49], v[68:69] op_sel_hi:[1,0]
	v_max_f32_e32 v50, 0, v50
	v_max_f32_e32 v51, 0, v51
	global_store_dwordx4 v[66:67], v[56:59], off
	v_pk_mul_f32 v[54:55], v[54:55], v[68:69] op_sel_hi:[1,0]
	v_max_f32_e32 v52, 0, v52
	v_max_f32_e32 v48, 0, v48
	v_max_f32_e32 v53, 0, v53
	v_max_f32_e32 v49, 0, v49
	v_pk_mul_f32 v[58:59], v[50:51], v[50:51]
	v_pk_mul_f32 v[52:53], v[52:53], v[52:53]
	v_pk_mul_f32 v[56:57], v[48:49], v[48:49]
	v_max_f32_e32 v48, 0, v54
	v_max_f32_e32 v49, 0, v55
	v_pk_mul_f32 v[54:55], v[48:49], v[48:49]
	v_cvt_pk_bf16_f32 v48, v52, v53
; __device__ __forceinline__ unsigned pk2(float lo, float hi) { const f32x2 v = (f32x2){lo, hi}; const bf16x2_t b = __builtin_convertvector(v, bf16x2_t); return __builtin_bit_cast(unsigned, b); }
;     __device__ __forceinline__ void operator()(const f32x4 (&acc)[2][2][4][2], const Unit& u, int wr, int wc, int fr, int fq, const float (&)[8]) const {
;     ...
;             for (int m = 0; m < 4; ++m) { const int row = row0 + ai * HALF + m * 16; const float rs = rsqrtf(ep[ai * 4 + m] * (1.0f / 1024.0f) + EPS);
;                 u16* rowp = O + (size_t)row * ldc + col0;
; #pragma unroll
;                 for (int bj = 0; bj < 2; ++bj) { f32x4 v0 = acc[ai][bj][m][0] * rs, v1 = acc[ai][bj][m][1] * rs;
;                     if (ACT == 1) {
; #pragma unroll
;                         for (int j = 0; j < 4; ++j) { const float a0 = fmaxf(v0[j], 0.f), a1 = fmaxf(v1[j], 0.f); v0[j] = a0 * a0; v1[j] = a1 * a1; } }
;                     u32x4 w; w.x = pk2(v0[0], v0[1]); w.y = pk2(v0[2], v0[3]); w.z = pk2(v1[0], v1[1]); w.w = pk2(v1[2], v1[3]);
;                     *(u32x4*)(rowp + bj * HALF) = w; } }
	v_cvt_pk_bf16_f32 v49, v54, v55
	v_cvt_pk_bf16_f32 v50, v56, v57
	v_cvt_pk_bf16_f32 v51, v58, v59
	global_store_dwordx4 v[66:67], v[48:51], off offset:256
	s_nop 1
	v_mov_b32_e32 v48, v233
	v_pk_mul_f32 v[40:41], v[40:41], v[48:49] op_sel_hi:[1,0]
	v_pk_mul_f32 v[46:47], v[46:47], v[48:49] op_sel_hi:[1,0]
	v_pk_mul_f32 v[44:45], v[44:45], v[48:49] op_sel_hi:[1,0]
	v_pk_mul_f32 v[42:43], v[42:43], v[48:49] op_sel_hi:[1,0]
	v_max_f32_e32 v40, 0, v40
	v_max_f32_e32 v41, 0, v41
	v_lshlrev_b64 v[50:51], 13, v[156:157]
	v_max_f32_e32 v44, 0, v44
	v_max_f32_e32 v45, 0, v45
	v_pk_mul_f32 v[52:53], v[40:41], v[40:41]
	v_max_f32_e32 v40, 0, v46
	v_max_f32_e32 v42, 0, v42
	v_max_f32_e32 v41, 0, v47
	v_max_f32_e32 v43, 0, v43
	v_lshl_add_u64 v[50:51], s[96:97], 0, v[50:51]
	v_pk_mul_f32 v[44:45], v[44:45], v[44:45]
	v_pk_mul_f32 v[46:47], v[40:41], v[40:41]
	v_pk_mul_f32 v[54:55], v[42:43], v[42:43]
	v_pk_mul_f32 v[32:33], v[32:33], v[48:49] op_sel_hi:[1,0]
	v_lshl_add_u64 v[50:51], v[50:51], 0, v[148:149]
	v_cvt_pk_bf16_f32 v40, v44, v45
	v_cvt_pk_bf16_f32 v41, v46, v47
	v_cvt_pk_bf16_f32 v42, v52, v53
	v_cvt_pk_bf16_f32 v43, v54, v55
	v_pk_mul_f32 v[38:39], v[38:39], v[48:49] op_sel_hi:[1,0]
	v_max_f32_e32 v32, 0, v32
	v_max_f32_e32 v33, 0, v33
	global_store_dwordx4 v[50:51], v[40:43], off
	v_pk_mul_f32 v[36:37], v[36:37], v[48:49] op_sel_hi:[1,0]
	v_pk_mul_f32 v[34:35], v[34:35], v[48:49] op_sel_hi:[1,0]
	v_pk_mul_f32 v[40:41], v[32:33], v[32:33]
	v_max_f32_e32 v32, 0, v38
	v_max_f32_e32 v33, 0, v39
	v_max_f32_e32 v36, 0, v36
	v_max_f32_e32 v37, 0, v37
	v_pk_mul_f32 v[36:37], v[36:37], v[36:37]
	v_pk_mul_f32 v[44:45], v[32:33], v[32:33]
	v_cvt_pk_bf16_f32 v32, v36, v37
	s_waitcnt lgkmcnt(0)
	v_max_f32_e32 v34, 0, v34
	v_max_f32_e32 v35, 0, v35
	v_pk_mul_f32 v[46:47], v[34:35], v[34:35]
	v_cvt_pk_bf16_f32 v33, v44, v45
	v_cvt_pk_bf16_f32 v34, v40, v41
	v_cvt_pk_bf16_f32 v35, v46, v47
	global_store_dwordx4 v[50:51], v[32:35], off offset:256
	s_waitcnt lgkmcnt(0)
	s_nop 0
	s_nop 0
	s_nop 0
	s_nop 1
	v_lshlrev_b64 v[34:35], 13, v[150:151]
	v_lshl_add_u64 v[34:35], s[96:97], 0, v[34:35]
	v_lshl_add_u64 v[34:35], v[34:35], 0, v[148:149]
	v_mov_b32_e32 v36, v234
	v_pk_mul_f32 v[24:25], v[24:25], v[36:37] op_sel_hi:[1,0]
	v_pk_mul_f32 v[30:31], v[30:31], v[36:37] op_sel_hi:[1,0]
	v_pk_mul_f32 v[28:29], v[28:29], v[36:37] op_sel_hi:[1,0]
	v_pk_mul_f32 v[26:27], v[26:27], v[36:37] op_sel_hi:[1,0]
	v_max_f32_e32 v24, 0, v24
	v_max_f32_e32 v25, 0, v25
	v_max_f32_e32 v28, 0, v28
	v_max_f32_e32 v29, 0, v29
	v_pk_mul_f32 v[38:39], v[24:25], v[24:25]
	v_max_f32_e32 v24, 0, v30
	v_max_f32_e32 v26, 0, v26
	v_max_f32_e32 v25, 0, v31
	v_max_f32_e32 v27, 0, v27
	v_pk_mul_f32 v[28:29], v[28:29], v[28:29]
	v_pk_mul_f32 v[30:31], v[24:25], v[24:25]
	v_pk_mul_f32 v[40:41], v[26:27], v[26:27]
	v_pk_mul_f32 v[18:19], v[18:19], v[36:37] op_sel_hi:[1,0]
	v_cvt_pk_bf16_f32 v24, v28, v29
	v_cvt_pk_bf16_f32 v25, v30, v31
	v_cvt_pk_bf16_f32 v26, v38, v39
	v_cvt_pk_bf16_f32 v27, v40, v41
	v_pk_mul_f32 v[20:21], v[20:21], v[36:37] op_sel_hi:[1,0]
	v_pk_mul_f32 v[16:17], v[16:17], v[36:37] op_sel_hi:[1,0]
	v_max_f32_e32 v18, 0, v18
	v_max_f32_e32 v19, 0, v19
	global_store_dwordx4 v[34:35], v[24:27], off
	v_pk_mul_f32 v[22:23], v[22:23], v[36:37] op_sel_hi:[1,0]
	v_max_f32_e32 v20, 0, v20
	v_max_f32_e32 v16, 0, v16
	v_max_f32_e32 v21, 0, v21
	v_max_f32_e32 v17, 0, v17
	v_pk_mul_f32 v[26:27], v[18:19], v[18:19]
	v_pk_mul_f32 v[20:21], v[20:21], v[20:21]
	v_pk_mul_f32 v[24:25], v[16:17], v[16:17]
	v_max_f32_e32 v16, 0, v22
	v_max_f32_e32 v17, 0, v23
	v_pk_mul_f32 v[22:23], v[16:17], v[16:17]
	v_cvt_pk_bf16_f32 v16, v20, v21
	v_cvt_pk_bf16_f32 v17, v22, v23
	v_cvt_pk_bf16_f32 v18, v24, v25
	v_cvt_pk_bf16_f32 v19, v26, v27
	global_store_dwordx4 v[34:35], v[16:19], off offset:256
	s_nop 1
	v_mov_b32_e32 v16, v235
	v_pk_mul_f32 v[8:9], v[8:9], v[16:17] op_sel_hi:[1,0]
	v_pk_mul_f32 v[14:15], v[14:15], v[16:17] op_sel_hi:[1,0]
	v_pk_mul_f32 v[12:13], v[12:13], v[16:17] op_sel_hi:[1,0]
	v_pk_mul_f32 v[10:11], v[10:11], v[16:17] op_sel_hi:[1,0]
	v_max_f32_e32 v8, 0, v8
	v_max_f32_e32 v9, 0, v9
	v_lshlrev_b64 v[18:19], 13, v[146:147]
	v_max_f32_e32 v12, 0, v12
	v_max_f32_e32 v13, 0, v13
	v_pk_mul_f32 v[20:21], v[8:9], v[8:9]
	v_max_f32_e32 v8, 0, v14
	v_max_f32_e32 v10, 0, v10
	v_max_f32_e32 v9, 0, v15
	v_max_f32_e32 v11, 0, v11
	v_lshl_add_u64 v[18:19], s[96:97], 0, v[18:19]
	v_pk_mul_f32 v[12:13], v[12:13], v[12:13]
	v_pk_mul_f32 v[14:15], v[8:9], v[8:9]
	v_pk_mul_f32 v[22:23], v[10:11], v[10:11]
	v_pk_mul_f32 v[0:1], v[0:1], v[16:17] op_sel_hi:[1,0]
	v_lshl_add_u64 v[18:19], v[18:19], 0, v[148:149]
	v_cvt_pk_bf16_f32 v8, v12, v13
	v_cvt_pk_bf16_f32 v9, v14, v15
	v_cvt_pk_bf16_f32 v10, v20, v21
	v_cvt_pk_bf16_f32 v11, v22, v23
	v_pk_mul_f32 v[6:7], v[6:7], v[16:17] op_sel_hi:[1,0]
	v_pk_mul_f32 v[4:5], v[4:5], v[16:17] op_sel_hi:[1,0]
	v_pk_mul_f32 v[2:3], v[2:3], v[16:17] op_sel_hi:[1,0]
	v_max_f32_e32 v0, 0, v0
	v_max_f32_e32 v1, 0, v1
	global_store_dwordx4 v[18:19], v[8:11], off
	v_max_f32_e32 v4, 0, v4
	v_max_f32_e32 v5, 0, v5
	v_pk_mul_f32 v[8:9], v[0:1], v[0:1]
	v_max_f32_e32 v0, 0, v6
	v_max_f32_e32 v2, 0, v2
	v_max_f32_e32 v1, 0, v7
	v_max_f32_e32 v3, 0, v3
	v_pk_mul_f32 v[4:5], v[4:5], v[4:5]
	v_pk_mul_f32 v[6:7], v[0:1], v[0:1]
	v_pk_mul_f32 v[10:11], v[2:3], v[2:3]
	v_cvt_pk_bf16_f32 v0, v4, v5
	v_cvt_pk_bf16_f32 v1, v6, v7
	v_cvt_pk_bf16_f32 v2, v8, v9
	v_cvt_pk_bf16_f32 v3, v10, v11
	s_and_b64 vcc, exec, s[0:1]
	global_store_dwordx4 v[18:19], v[0:3], off offset:256
	s_cbranch_vccz .LBB0_763
	s_waitcnt vmcnt(0)
	s_cmpk_gt_u32 s9, 0xff
	s_cbranch_scc1 .LBB0_774
	s_barrier

; #define PG8_STAGE(bufoff, gbase, voff) do { _Pragma("unroll") for (int _i = 0; _i < 2; ++_i) \
;         __builtin_amdgcn_global_load_lds((const unsigned*)((const char*)(gbase) + (voff)[_i]), (LAS unsigned*)(lds + (bufoff) + ldsw + _i * 8192), 16, 0, 0); } while (0)
; #define PG8_LDA(dst, b, h) do { _Pragma("unroll") for (int m = 0; m < 4; ++m) _Pragma("unroll") for (int k = 0; k < 2; ++k) dst[m][k] = *(const LAS bf16x8*)(lds + PG8_SA(b, h) + aoff + m * 2048 + k * 1024); } while (0)
; #define PG8_LDB(dst, b, h) do { _Pragma("unroll") for (int n = 0; n < 2; ++n) _Pragma("unroll") for (int k = 0; k < 2; ++k) dst[n][k] = *(const LAS bf16x8*)(lds + PG8_SB(b, h) + boff + n * 2048 + k * 1024); } while (0)
; #define PG8_WAIT_V(n) asm volatile("s_waitcnt vmcnt(" #n ")" ::: "memory")
; #define PG8_BAR __builtin_amdgcn_s_barrier()
; #define PG8_SCHED __builtin_amdgcn_sched_barrier(0)
; template <class Epi>
; __device__ __forceinline__ void gemm_phase(LAS unsigned char* lds, const Gemm g, const StaticOrder& S, const Epi& E) {
;     ...
;     const char* cA = (const char*)g.A + (size_t)cur.pm * tstepA; const char* cB = (const char*)g.Bt + (size_t)cur.pn * tstepB;
;     PG8_STAGE(PG8_SB(0, 0), cB, voffB); PG8_STAGE(PG8_SA(0, 0), cA, voffA); PG8_STAGE(PG8_SB(0, 1), cB + hstepB, voffB); PG8_STAGE(PG8_SA(0, 1), cA + hstepA, voffA);
;     if (wr == 1) PG8_BAR;
;     PG8_WAIT_V(4); PG8_BAR;
;     PG8_STAGE(PG8_SB(1, 0), cB + kstep, voffB); PG8_STAGE(PG8_SA(1, 0), cA + kstep, voffA); PG8_STAGE(PG8_SB(1, 1), cB + hstepB + kstep, voffB);
;     PG8_WAIT_V(6); PG8_BAR;
;     for (;;) {
;         const bool has_next = S.next(ui + 1, nxt);
;         const char* nA = has_next ? (const char*)g.A + (size_t)nxt.pm * tstepA : cA; const char* nB = has_next ? (const char*)g.Bt + (size_t)nxt.pn * tstepB : cB;
;         for (int t = 0; t < nt; t += 2) {
;             const bool last = (t == nt - 2);
;             const char* a1 = cA + (size_t)(t + 1) * kstep;
;             const char* a2 = last ? nA : cA + (size_t)(t + 2) * kstep; const char* b2 = last ? nB : cB + (size_t)(t + 2) * kstep;
;             const char* a3 = a2 + kstep; const char* b3 = b2 + kstep;
;             if (last) E.pre(cur, wr, fr, epre);
;             PG8_LDB(B0, 0, 0); PG8_SCHED; PG8_LDA(At, 0, 0); PG8_STAGE(PG8_SA(1, 1), a1 + hstepA, voffA);
.LBB0_918:
	s_lshl_b32 s4, s4, 5
	s_and_b32 s8, s4, 0x60
	s_mov_b64 s[4:5], 0x80
	s_add_i32 m0, s19, 0x18000
	v_lshl_add_u64 v[6:7], v[6:7], 0, s[4:5]
	s_lshl_b32 s6, s1, 13
	s_lshl_b32 s12, s8, 7
	s_waitcnt vmcnt(4)
	s_barrier
	global_load_lds_dwordx4 v[6:7], off
	v_lshl_add_u64 v[4:5], v[4:5], 0, s[4:5]
	s_add_i32 m0, s19, 0x1a000
	s_add_i32 s35, s19, 0x8000
	s_add_i32 s36, s19, 0xa000
	global_load_lds_dwordx4 v[4:5], off
	v_lshl_add_u64 v[2:3], v[2:3], 0, s[4:5]
	s_mov_b32 m0, s35
	s_add_u32 s10, s22, 0x40080
	global_load_lds_dwordx4 v[2:3], off
	v_lshl_add_u64 v[0:1], v[0:1], 0, s[4:5]
	s_mov_b32 m0, s36
	s_addc_u32 s11, s23, 0
	global_load_lds_dwordx4 v[0:1], off
	s_add_i32 m0, s19, 0x1c000
	v_lshl_add_u64 v[0:1], s[10:11], 0, v[132:133]
	global_load_lds_dwordx4 v[0:1], off
	v_lshl_add_u64 v[0:1], s[10:11], 0, v[128:129]
	s_add_i32 m0, s19, 0x1e000
	v_bfe_u32 v2, v152, 4, 2
	global_load_lds_dwordx4 v[0:1], off
	v_and_b32_e32 v1, 15, v152
	v_lshlrev_b32_e32 v0, 4, v2
	v_lshlrev_b32_e32 v3, 2, v152
	v_lshl_or_b32 v170, s1, 6, v1
	v_lshl_or_b32 v1, v1, 6, v0
	v_and_b32_e32 v3, 32, v3
	s_sext_i32_i16 s42, s0
	v_bitop3_b32 v4, v1, s6, v3 bitop3:0xde
	v_lshlrev_b32_e32 v1, 6, v152
	s_movk_i32 s0, 0x3c0
	v_and_or_b32 v1, v1, s0, v0
	v_bitop3_b32 v171, s12, v1, v3 bitop3:0xf6
	v_mov_b32_e32 v1, v133
	v_lshl_add_u64 v[0:1], s[74:75], 0, v[0:1]
	s_mov_b64 s[0:1], 0x3c7c4000
	v_lshl_add_u64 v[136:137], v[0:1], 0, s[0:1]
	v_lshlrev_b32_e32 v0, 8, v152
	v_and_b32_e32 v0, 0x38000, v0
	v_lshlrev_b32_e32 v1, 11, v11
	v_or3_b32 v0, v9, v0, v1
	v_add_u32_e32 v138, v0, v10
	v_lshlrev_b32_e32 v0, 4, v8
	v_and_b32_e32 v0, 0x78000, v0
	s_waitcnt vmcnt(6)
	v_or3_b32 v0, v9, v0, v1
	v_add_u32_e32 v140, v0, v10
	s_add_i32 s38, 0, 0x10000
	s_add_i32 s39, 0, 0x14000
	v_mbcnt_lo_u32_b32 v0, -1, 0
	s_ashr_i32 s37, s92, 31
	v_lshl_or_b32 v172, v2, 3, s8
	v_mov_b32_e32 v139, v133
	v_mov_b32_e32 v141, v133
	v_mov_b64_e32 v[142:143], 0x1400
	v_mov_b64_e32 v[144:145], 0x13ff
	v_add_u32_e32 v173, s38, v171
	v_add_u32_e32 v174, 0, v4
	v_add_u32_e32 v175, s39, v171
	v_mbcnt_hi_u32_b32 v176, -1, v0
	s_movk_i32 s40, 0x2800
	s_mov_b32 s6, 0x3a800000
	s_mov_b32 s8, 0x358637bd
	s_mov_b32 s41, 0x800000
	s_add_u32 vcc_lo, s20, 0x40080
	s_addc_u32 vcc_hi, s21, 0
	s_add_i32 m0, s19, 0xc000
	v_lshl_add_u64 v[236:237], vcc, 0, v[138:139]
	v_lshl_add_u64 v[238:239], vcc, 0, v[140:141]
	global_load_lds_dwordx4 v[236:237], off
	s_add_i32 m0, s19, 0xe000
	s_nop 0
	global_load_lds_dwordx4 v[238:239], off
	s_waitcnt vmcnt(0)
	s_barrier

; #define PG8_STAGE(bufoff, gbase, voff) do { _Pragma("unroll") for (int _i = 0; _i < 2; ++_i) \
;         __builtin_amdgcn_global_load_lds((const unsigned*)((const char*)(gbase) + (voff)[_i]), (LAS unsigned*)(lds + (bufoff) + ldsw + _i * 8192), 16, 0, 0); } while (0)
; #define PG8_LDA(dst, b, h) do { _Pragma("unroll") for (int m = 0; m < 4; ++m) _Pragma("unroll") for (int k = 0; k < 2; ++k) dst[m][k] = *(const LAS bf16x8*)(lds + PG8_SA(b, h) + aoff + m * 2048 + k * 1024); } while (0)
; #define PG8_LDB(dst, b, h) do { _Pragma("unroll") for (int n = 0; n < 2; ++n) _Pragma("unroll") for (int k = 0; k < 2; ++k) dst[n][k] = *(const LAS bf16x8*)(lds + PG8_SB(b, h) + boff + n * 2048 + k * 1024); } while (0)
; #define PG8_WAIT_V(n) asm volatile("s_waitcnt vmcnt(" #n ")" ::: "memory")
; #define PG8_WAIT_L(n) asm volatile("s_waitcnt lgkmcnt(" #n ")" ::: "memory")
; #define PG8_BAR __builtin_amdgcn_s_barrier()
; #define PG8_SCHED __builtin_amdgcn_sched_barrier(0)
; template <class Epi>
; __device__ __forceinline__ void gemm_phase(LAS unsigned char* lds, const Gemm g, const StaticOrder& S, const Epi& E) {
;     ...
;         const bool has_next = S.next(ui + 1, nxt);
;         const char* nA = has_next ? (const char*)g.A + (size_t)nxt.pm * tstepA : cA; const char* nB = has_next ? (const char*)g.Bt + (size_t)nxt.pn * tstepB : cB;
;         for (int t = 0; t < nt; t += 2) {
;             const bool last = (t == nt - 2);
;             const char* a1 = cA + (size_t)(t + 1) * kstep;
;             const char* a2 = last ? nA : cA + (size_t)(t + 2) * kstep; const char* b2 = last ? nB : cB + (size_t)(t + 2) * kstep;
;             const char* a3 = a2 + kstep; const char* b3 = b2 + kstep;
;             if (last) E.pre(cur, wr, fr, epre);
;             PG8_LDB(B0, 0, 0); PG8_SCHED; PG8_LDA(At, 0, 0); PG8_STAGE(PG8_SA(1, 1), a1 + hstepA, voffA);
;             PG8_WAIT_L(8); PG8_BAR; PG8_WAIT_L(0); PG8_MMA(0, 0, At, B0); PG8_BAR; PG8_SCHED;
;             PG8_LDB(B1, 0, 1); PG8_STAGE(PG8_SB(0, 0), b2, voffB);
;             PG8_BAR; PG8_WAIT_L(0); PG8_MMA(0, 1, At, B1); PG8_BAR;
;             PG8_LDA(At, 0, 1); PG8_STAGE(PG8_SA(0, 0), a2, voffA);
;             PG8_BAR; PG8_WAIT_L(0); PG8_MMA(1, 0, At, B0); PG8_BAR; PG8_SCHED;
;             PG8_STAGE(PG8_SB(0, 1), b2 + hstepB, voffB);
;             PG8_WAIT_V(6); PG8_BAR; PG8_MMA(1, 1, At, B1); PG8_BAR;
.LBB0_921:
	s_ashr_i32 s13, s12, 31
	v_cmp_lt_i64_e32 vcc, s[14:15], v[142:143]
	s_lshl_b64 s[14:15], s[12:13], 19
	s_add_u32 s14, s76, s14
	s_addc_u32 s15, s77, s15
	s_and_b64 s[16:17], vcc, exec
	s_cselect_b32 s13, s15, s21
	s_cselect_b32 s43, s14, s20
	s_ashr_i32 s11, s10, 31
	s_lshl_b64 s[16:17], s[10:11], 19
	s_add_u32 s16, s9, s16
	s_addc_u32 s17, s26, s17
	s_and_b64 s[24:25], vcc, exec
	s_cselect_b32 s11, s17, s23
	s_cselect_b32 s44, s16, s22
	s_add_u32 s20, s20, 0x40080
	s_addc_u32 s21, s21, 0
	s_add_u32 s45, s22, 0x100
	s_addc_u32 s46, s23, 0
	s_mov_b32 s47, -2
	ds_read_b128 v[146:149], v173
	ds_read_b128 v[154:157], v173 offset:1024
	ds_read_b128 v[158:161], v173 offset:2048
	ds_read_b128 v[162:165], v173 offset:3072
	s_add_u32 s22, s20, 0xfffc0080
	s_addc_u32 s23, s21, -1
	s_cmp_eq_u32 s47, 12
	s_cselect_b32 s25, s13, s23
	s_cselect_b32 s24, s43, s22
	s_cselect_b32 s23, s11, s46
	s_cselect_b32 s22, s44, s45
	ds_read_b128 v[166:169], v174
	ds_read_b128 v[178:181], v174 offset:1024
	ds_read_b128 v[182:185], v174 offset:2048
	ds_read_b128 v[186:189], v174 offset:3072
	ds_read_b128 v[190:193], v174 offset:4096
	ds_read_b128 v[194:197], v174 offset:5120
	ds_read_b128 v[198:201], v174 offset:6144
	ds_read_b128 v[202:205], v174 offset:7168
	s_waitcnt lgkmcnt(8)
	s_barrier
	s_waitcnt lgkmcnt(0)
	s_setprio 1
	s_waitcnt lgkmcnt(0)
	v_mfma_f32_16x16x32_bf16 v[124:127], v[146:149], v[166:169], 0
	v_mfma_f32_16x16x32_bf16 v[120:123], v[158:161], v[166:169], 0
	v_mfma_f32_16x16x32_bf16 v[112:115], v[146:149], v[182:185], 0
	v_mfma_f32_16x16x32_bf16 v[104:107], v[158:161], v[182:185], 0
	v_mfma_f32_16x16x32_bf16 v[92:95], v[146:149], v[190:193], 0
	v_mfma_f32_16x16x32_bf16 v[88:91], v[158:161], v[190:193], 0
	v_mfma_f32_16x16x32_bf16 v[80:83], v[146:149], v[198:201], 0
	v_mfma_f32_16x16x32_bf16 v[72:75], v[158:161], v[198:201], 0
	v_mfma_f32_16x16x32_bf16 v[124:127], v[154:157], v[178:181], v[124:127]
	v_mfma_f32_16x16x32_bf16 v[120:123], v[162:165], v[178:181], v[120:123]
	v_mfma_f32_16x16x32_bf16 v[112:115], v[154:157], v[186:189], v[112:115]
	v_mfma_f32_16x16x32_bf16 v[104:107], v[162:165], v[186:189], v[104:107]
	v_mfma_f32_16x16x32_bf16 v[92:95], v[154:157], v[194:197], v[92:95]
	v_mfma_f32_16x16x32_bf16 v[88:91], v[162:165], v[194:197], v[88:91]
	v_mfma_f32_16x16x32_bf16 v[80:83], v[154:157], v[202:205], v[80:83]
	v_mfma_f32_16x16x32_bf16 v[72:75], v[162:165], v[202:205], v[72:75]
	s_setprio 0
	s_barrier
	s_add_i32 s48, s38, s27
	v_lshl_add_u64 v[150:151], s[22:23], 0, v[132:133]
	s_mov_b32 m0, s48
	ds_read_b128 v[206:209], v175
	ds_read_b128 v[210:213], v175 offset:1024
	ds_read_b128 v[214:217], v175 offset:2048
	ds_read_b128 v[218:221], v175 offset:3072
	global_load_lds_dwordx4 v[150:151], off
	v_lshl_add_u64 v[222:223], s[22:23], 0, v[128:129]
	s_add_i32 m0, s48, 0x2000
	s_nop 0
	global_load_lds_dwordx4 v[222:223], off
	s_barrier
	s_waitcnt lgkmcnt(0)
	s_setprio 1
	s_waitcnt lgkmcnt(0)
	v_mfma_f32_16x16x32_bf16 v[116:119], v[206:209], v[166:169], 0
	v_mfma_f32_16x16x32_bf16 v[108:111], v[214:217], v[166:169], 0
	v_mfma_f32_16x16x32_bf16 v[100:103], v[206:209], v[182:185], 0
	v_mfma_f32_16x16x32_bf16 v[96:99], v[214:217], v[182:185], 0
	v_mfma_f32_16x16x32_bf16 v[84:87], v[206:209], v[190:193], 0
	v_mfma_f32_16x16x32_bf16 v[76:79], v[214:217], v[190:193], 0
	v_mfma_f32_16x16x32_bf16 v[68:71], v[206:209], v[198:201], 0
	v_mfma_f32_16x16x32_bf16 v[64:67], v[214:217], v[198:201], 0
	v_mfma_f32_16x16x32_bf16 v[116:119], v[210:213], v[178:181], v[116:119]
	v_mfma_f32_16x16x32_bf16 v[108:111], v[218:221], v[178:181], v[108:111]
	v_mfma_f32_16x16x32_bf16 v[100:103], v[210:213], v[186:189], v[100:103]
	v_mfma_f32_16x16x32_bf16 v[96:99], v[218:221], v[186:189], v[96:99]
	v_mfma_f32_16x16x32_bf16 v[84:87], v[210:213], v[194:197], v[84:87]
	v_mfma_f32_16x16x32_bf16 v[76:79], v[218:221], v[194:197], v[76:79]
	v_mfma_f32_16x16x32_bf16 v[68:71], v[210:213], v[202:205], v[68:71]
	v_mfma_f32_16x16x32_bf16 v[64:67], v[218:221], v[202:205], v[64:67]
	s_setprio 0
	s_mov_b32 m0, s19
	v_lshl_add_u64 v[224:225], s[24:25], 0, v[134:135]
	s_barrier
	ds_read_b128 v[166:169], v174 offset:16384
	ds_read_b128 v[178:181], v174 offset:17408
	ds_read_b128 v[182:185], v174 offset:18432
	ds_read_b128 v[186:189], v174 offset:19456
	ds_read_b128 v[190:193], v174 offset:20480
	ds_read_b128 v[194:197], v174 offset:21504
	ds_read_b128 v[198:201], v174 offset:22528
	ds_read_b128 v[202:205], v174 offset:23552
	global_load_lds_dwordx4 v[224:225], off
	v_lshl_add_u64 v[226:227], s[24:25], 0, v[130:131]
	s_mov_b32 m0, s30
	s_nop 0
	global_load_lds_dwordx4 v[226:227], off
	s_barrier
	s_waitcnt lgkmcnt(0)
	s_setprio 1
	s_waitcnt lgkmcnt(0)
	v_mfma_f32_16x16x32_bf16 v[60:63], v[146:149], v[166:169], 0
	v_mfma_f32_16x16x32_bf16 v[56:59], v[158:161], v[166:169], 0
	v_mfma_f32_16x16x32_bf16 v[48:51], v[146:149], v[182:185], 0
	v_mfma_f32_16x16x32_bf16 v[40:43], v[158:161], v[182:185], 0
	v_mfma_f32_16x16x32_bf16 v[32:35], v[146:149], v[190:193], 0
	v_mfma_f32_16x16x32_bf16 v[24:27], v[158:161], v[190:193], 0
	v_mfma_f32_16x16x32_bf16 v[16:19], v[146:149], v[198:201], 0
	v_mfma_f32_16x16x32_bf16 v[8:11], v[158:161], v[198:201], 0
	v_mfma_f32_16x16x32_bf16 v[60:63], v[154:157], v[178:181], v[60:63]
	v_mfma_f32_16x16x32_bf16 v[56:59], v[162:165], v[178:181], v[56:59]
	v_mfma_f32_16x16x32_bf16 v[48:51], v[154:157], v[186:189], v[48:51]
	v_mfma_f32_16x16x32_bf16 v[40:43], v[162:165], v[186:189], v[40:43]
	v_mfma_f32_16x16x32_bf16 v[32:35], v[154:157], v[194:197], v[32:35]
	v_mfma_f32_16x16x32_bf16 v[24:27], v[162:165], v[194:197], v[24:27]
	v_mfma_f32_16x16x32_bf16 v[16:19], v[154:157], v[202:205], v[16:19]
	v_mfma_f32_16x16x32_bf16 v[8:11], v[162:165], v[202:205], v[8:11]
	s_setprio 0
	s_barrier
; #define PG8_STAGE(bufoff, gbase, voff) do { _Pragma("unroll") for (int _i = 0; _i < 2; ++_i) \
;         __builtin_amdgcn_global_load_lds((const unsigned*)((const char*)(gbase) + (voff)[_i]), (LAS unsigned*)(lds + (bufoff) + ldsw + _i * 8192), 16, 0, 0); } while (0)
; #define PG8_LDA(dst, b, h) do { _Pragma("unroll") for (int m = 0; m < 4; ++m) _Pragma("unroll") for (int k = 0; k < 2; ++k) dst[m][k] = *(const LAS bf16x8*)(lds + PG8_SA(b, h) + aoff + m * 2048 + k * 1024); } while (0)
; #define PG8_LDB(dst, b, h) do { _Pragma("unroll") for (int n = 0; n < 2; ++n) _Pragma("unroll") for (int k = 0; k < 2; ++k) dst[n][k] = *(const LAS bf16x8*)(lds + PG8_SB(b, h) + boff + n * 2048 + k * 1024); } while (0)
; #define PG8_MMA(ai, bj, At, Bt) do { __builtin_amdgcn_s_setprio(1); _Pragma("unroll") for (int m = 0; m < 4; ++m) _Pragma("unroll") for (int n = 0; n < 2; ++n) _Pragma("unroll") for (int k = 0; k < 2; ++k) \
;         acc[ai][bj][m][n] = __builtin_amdgcn_mfma_f32_16x16x32_bf16(Bt[n][k], At[m][k], acc[ai][bj][m][n], 0, 0, 0); __builtin_amdgcn_s_setprio(0); } while (0)
; #define PG8_WAIT_V(n) asm volatile("s_waitcnt vmcnt(" #n ")" ::: "memory")
; #define PG8_WAIT_L(n) asm volatile("s_waitcnt lgkmcnt(" #n ")" ::: "memory")
; #define PG8_BAR __builtin_amdgcn_s_barrier()
; #define PG8_SCHED __builtin_amdgcn_sched_barrier(0)
; template <class Epi>
; __device__ __forceinline__ void gemm_phase(LAS unsigned char* lds, const Gemm g, const StaticOrder& S, const Epi& E) {
;     ...
;             PG8_WAIT_V(6); PG8_BAR; PG8_MMA(1, 1, At, B1); PG8_BAR;
;             PG8_LDB(B0, 1, 0); PG8_SCHED; PG8_LDA(At, 1, 0); PG8_STAGE(PG8_SA(0, 1), a2 + hstepA, voffA);
;             PG8_WAIT_L(8); PG8_BAR; PG8_WAIT_L(0); PG8_MMA(0, 0, At, B0); PG8_BAR; PG8_SCHED;
;             PG8_LDB(B1, 1, 1); PG8_STAGE(PG8_SB(1, 0), b3, voffB);
;             PG8_BAR; PG8_WAIT_L(0); PG8_MMA(0, 1, At, B1); PG8_BAR;
;             PG8_LDA(At, 1, 1); PG8_STAGE(PG8_SA(1, 0), a3, voffA);
	s_add_u32 s48, s22, 0x40000
	s_addc_u32 s49, s23, 0
	s_add_i32 s50, s39, s27
	v_lshl_add_u64 v[146:147], s[48:49], 0, v[132:133]
	s_mov_b32 m0, s50
	s_nop 0
	global_load_lds_dwordx4 v[146:147], off
	v_lshl_add_u64 v[146:147], s[48:49], 0, v[128:129]
	s_add_i32 m0, s50, 0x2000
	s_nop 0
	global_load_lds_dwordx4 v[146:147], off
	s_waitcnt vmcnt(22)
	s_barrier
	s_setprio 1
	v_mfma_f32_16x16x32_bf16 v[52:55], v[206:209], v[166:169], 0
	v_mfma_f32_16x16x32_bf16 v[44:47], v[214:217], v[166:169], 0
	v_mfma_f32_16x16x32_bf16 v[36:39], v[206:209], v[182:185], 0
	v_mfma_f32_16x16x32_bf16 v[28:31], v[214:217], v[182:185], 0
	v_mfma_f32_16x16x32_bf16 v[20:23], v[206:209], v[190:193], 0
	v_mfma_f32_16x16x32_bf16 v[12:15], v[214:217], v[190:193], 0
	v_mfma_f32_16x16x32_bf16 v[4:7], v[206:209], v[198:201], 0
	v_mfma_f32_16x16x32_bf16 v[0:3], v[214:217], v[198:201], 0
	v_mfma_f32_16x16x32_bf16 v[52:55], v[210:213], v[178:181], v[52:55]
	v_mfma_f32_16x16x32_bf16 v[44:47], v[218:221], v[178:181], v[44:47]
	v_mfma_f32_16x16x32_bf16 v[36:39], v[210:213], v[186:189], v[36:39]
	v_mfma_f32_16x16x32_bf16 v[28:31], v[218:221], v[186:189], v[28:31]
	v_mfma_f32_16x16x32_bf16 v[20:23], v[210:213], v[194:197], v[20:23]
	v_mfma_f32_16x16x32_bf16 v[12:15], v[218:221], v[194:197], v[12:15]
	v_mfma_f32_16x16x32_bf16 v[4:7], v[210:213], v[202:205], v[4:7]
	v_mfma_f32_16x16x32_bf16 v[0:3], v[218:221], v[202:205], v[0:3]
	s_setprio 0
	s_add_i32 s48, 0, 0x18000
	v_add_u32_e32 v162, s48, v171
	s_barrier
	ds_read_b128 v[146:149], v162
	ds_read_b128 v[154:157], v162 offset:1024
	ds_read_b128 v[158:161], v162 offset:2048
	ds_read_b128 v[162:165], v162 offset:3072
	s_add_u32 s24, s24, 0x40000
	s_addc_u32 s25, s25, 0
	s_mov_b32 m0, s31
	v_lshl_add_u64 v[206:207], s[24:25], 0, v[134:135]
	ds_read_b128 v[166:169], v174 offset:32768
	ds_read_b128 v[178:181], v174 offset:33792
	ds_read_b128 v[182:185], v174 offset:34816
	ds_read_b128 v[186:189], v174 offset:35840
	ds_read_b128 v[190:193], v174 offset:36864
	ds_read_b128 v[194:197], v174 offset:37888
	ds_read_b128 v[198:201], v174 offset:38912
	ds_read_b128 v[202:205], v174 offset:39936
	global_load_lds_dwordx4 v[206:207], off
	v_lshl_add_u64 v[206:207], s[24:25], 0, v[130:131]
	s_mov_b32 m0, s33
	s_nop 0
	global_load_lds_dwordx4 v[206:207], off
	s_waitcnt lgkmcnt(8)
	s_barrier
	s_waitcnt lgkmcnt(0)
	s_setprio 1
	s_waitcnt lgkmcnt(0)
	v_mfma_f32_16x16x32_bf16 v[124:127], v[146:149], v[166:169], v[124:127]
	v_mfma_f32_16x16x32_bf16 v[120:123], v[158:161], v[166:169], v[120:123]
	v_mfma_f32_16x16x32_bf16 v[112:115], v[146:149], v[182:185], v[112:115]
	v_mfma_f32_16x16x32_bf16 v[104:107], v[158:161], v[182:185], v[104:107]
	v_mfma_f32_16x16x32_bf16 v[92:95], v[146:149], v[190:193], v[92:95]
	v_mfma_f32_16x16x32_bf16 v[88:91], v[158:161], v[190:193], v[88:91]
	v_mfma_f32_16x16x32_bf16 v[80:83], v[146:149], v[198:201], v[80:83]
	v_mfma_f32_16x16x32_bf16 v[72:75], v[158:161], v[198:201], v[72:75]
	v_mfma_f32_16x16x32_bf16 v[124:127], v[154:157], v[178:181], v[124:127]
	v_mfma_f32_16x16x32_bf16 v[120:123], v[162:165], v[178:181], v[120:123]
	v_mfma_f32_16x16x32_bf16 v[112:115], v[154:157], v[186:189], v[112:115]
	v_mfma_f32_16x16x32_bf16 v[104:107], v[162:165], v[186:189], v[104:107]
	v_mfma_f32_16x16x32_bf16 v[92:95], v[154:157], v[194:197], v[92:95]
	v_mfma_f32_16x16x32_bf16 v[88:91], v[162:165], v[194:197], v[88:91]
	v_mfma_f32_16x16x32_bf16 v[80:83], v[154:157], v[202:205], v[80:83]
	v_mfma_f32_16x16x32_bf16 v[72:75], v[162:165], v[202:205], v[72:75]
	s_setprio 0
	s_barrier
	s_add_i32 s24, 0, 0x1c000
	s_add_i32 s25, s48, s27
	v_add_u32_e32 v177, s24, v171
	v_lshl_add_u64 v[150:151], v[150:151], 0, s[4:5]
	s_mov_b32 m0, s25
	ds_read_b128 v[206:209], v177
	ds_read_b128 v[210:213], v177 offset:1024
	ds_read_b128 v[214:217], v177 offset:2048
	ds_read_b128 v[218:221], v177 offset:3072
	global_load_lds_dwordx4 v[150:151], off
	v_lshl_add_u64 v[150:151], v[222:223], 0, s[4:5]
	s_add_i32 m0, s25, 0x2000
	s_nop 0
	global_load_lds_dwordx4 v[150:151], off
	s_barrier
	s_waitcnt lgkmcnt(0)
	s_setprio 1
	s_waitcnt lgkmcnt(0)
	v_mfma_f32_16x16x32_bf16 v[116:119], v[206:209], v[166:169], v[116:119]
	v_mfma_f32_16x16x32_bf16 v[108:111], v[214:217], v[166:169], v[108:111]
	v_mfma_f32_16x16x32_bf16 v[100:103], v[206:209], v[182:185], v[100:103]
	v_mfma_f32_16x16x32_bf16 v[96:99], v[214:217], v[182:185], v[96:99]
	v_mfma_f32_16x16x32_bf16 v[84:87], v[206:209], v[190:193], v[84:87]
	v_mfma_f32_16x16x32_bf16 v[76:79], v[214:217], v[190:193], v[76:79]
	v_mfma_f32_16x16x32_bf16 v[68:71], v[206:209], v[198:201], v[68:71]
	v_mfma_f32_16x16x32_bf16 v[64:67], v[214:217], v[198:201], v[64:67]
	v_mfma_f32_16x16x32_bf16 v[116:119], v[210:213], v[178:181], v[116:119]
	v_mfma_f32_16x16x32_bf16 v[108:111], v[218:221], v[178:181], v[108:111]
	v_mfma_f32_16x16x32_bf16 v[100:103], v[210:213], v[186:189], v[100:103]
	v_mfma_f32_16x16x32_bf16 v[96:99], v[218:221], v[186:189], v[96:99]
	v_mfma_f32_16x16x32_bf16 v[84:87], v[210:213], v[194:197], v[84:87]
	v_mfma_f32_16x16x32_bf16 v[76:79], v[218:221], v[194:197], v[76:79]
	v_mfma_f32_16x16x32_bf16 v[68:71], v[210:213], v[202:205], v[68:71]
	v_mfma_f32_16x16x32_bf16 v[64:67], v[218:221], v[202:205], v[64:67]
	s_setprio 0
	s_mov_b32 m0, s35
	v_lshl_add_u64 v[150:151], v[224:225], 0, s[4:5]
	s_barrier
	ds_read_b128 v[166:169], v174 offset:49152
	ds_read_b128 v[178:181], v174 offset:50176
	ds_read_b128 v[182:185], v174 offset:51200
	ds_read_b128 v[186:189], v174 offset:52224
	ds_read_b128 v[190:193], v174 offset:53248
	ds_read_b128 v[194:197], v174 offset:54272
	ds_read_b128 v[198:201], v174 offset:55296
	ds_read_b128 v[202:205], v174 offset:56320
	global_load_lds_dwordx4 v[150:151], off
	v_lshl_add_u64 v[150:151], v[226:227], 0, s[4:5]
	s_mov_b32 m0, s36
	s_nop 0
	global_load_lds_dwordx4 v[150:151], off
	s_barrier
; #define PG8_STAGE(bufoff, gbase, voff) do { _Pragma("unroll") for (int _i = 0; _i < 2; ++_i) \
;         __builtin_amdgcn_global_load_lds((const unsigned*)((const char*)(gbase) + (voff)[_i]), (LAS unsigned*)(lds + (bufoff) + ldsw + _i * 8192), 16, 0, 0); } while (0)
; #define PG8_LDA(dst, b, h) do { _Pragma("unroll") for (int m = 0; m < 4; ++m) _Pragma("unroll") for (int k = 0; k < 2; ++k) dst[m][k] = *(const LAS bf16x8*)(lds + PG8_SA(b, h) + aoff + m * 2048 + k * 1024); } while (0)
; #define PG8_LDB(dst, b, h) do { _Pragma("unroll") for (int n = 0; n < 2; ++n) _Pragma("unroll") for (int k = 0; k < 2; ++k) dst[n][k] = *(const LAS bf16x8*)(lds + PG8_SB(b, h) + boff + n * 2048 + k * 1024); } while (0)
; #define PG8_MMA(ai, bj, At, Bt) do { __builtin_amdgcn_s_setprio(1); _Pragma("unroll") for (int m = 0; m < 4; ++m) _Pragma("unroll") for (int n = 0; n < 2; ++n) _Pragma("unroll") for (int k = 0; k < 2; ++k) \
;         acc[ai][bj][m][n] = __builtin_amdgcn_mfma_f32_16x16x32_bf16(Bt[n][k], At[m][k], acc[ai][bj][m][n], 0, 0, 0); __builtin_amdgcn_s_setprio(0); } while (0)
; #define PG8_WAIT_V(n) asm volatile("s_waitcnt vmcnt(" #n ")" ::: "memory")
; #define PG8_WAIT_L(n) asm volatile("s_waitcnt lgkmcnt(" #n ")" ::: "memory")
; #define PG8_BAR __builtin_amdgcn_s_barrier()
; #define PG8_SCHED __builtin_amdgcn_sched_barrier(0)
; template <class Epi>
; __device__ __forceinline__ void gemm_phase(LAS unsigned char* lds, const Gemm g, const StaticOrder& S, const Epi& E) {
;     ...
;             PG8_LDB(B0, 0, 0); PG8_SCHED; PG8_LDA(At, 0, 0); PG8_STAGE(PG8_SA(1, 1), a1 + hstepA, voffA);
;             PG8_WAIT_L(8); PG8_BAR; PG8_WAIT_L(0); PG8_MMA(0, 0, At, B0); PG8_BAR; PG8_SCHED;
;             PG8_LDB(B1, 0, 1); PG8_STAGE(PG8_SB(0, 0), b2, voffB);
;     ...
;             PG8_BAR; PG8_WAIT_L(0); PG8_MMA(1, 0, At, B0); PG8_BAR; PG8_SCHED;
;             PG8_STAGE(PG8_SB(1, 1), b3 + hstepB, voffB);
;             PG8_WAIT_V(6); PG8_BAR; PG8_MMA(1, 1, At, B1); PG8_BAR;
	s_waitcnt lgkmcnt(0)
	s_setprio 1
	s_waitcnt lgkmcnt(0)
	v_mfma_f32_16x16x32_bf16 v[60:63], v[146:149], v[166:169], v[60:63]
	v_mfma_f32_16x16x32_bf16 v[56:59], v[158:161], v[166:169], v[56:59]
	v_mfma_f32_16x16x32_bf16 v[48:51], v[146:149], v[182:185], v[48:51]
	v_mfma_f32_16x16x32_bf16 v[40:43], v[158:161], v[182:185], v[40:43]
	v_mfma_f32_16x16x32_bf16 v[32:35], v[146:149], v[190:193], v[32:35]
	v_mfma_f32_16x16x32_bf16 v[24:27], v[158:161], v[190:193], v[24:27]
	v_mfma_f32_16x16x32_bf16 v[16:19], v[146:149], v[198:201], v[16:19]
	v_mfma_f32_16x16x32_bf16 v[8:11], v[158:161], v[198:201], v[8:11]
	v_mfma_f32_16x16x32_bf16 v[60:63], v[154:157], v[178:181], v[60:63]
	v_mfma_f32_16x16x32_bf16 v[56:59], v[162:165], v[178:181], v[56:59]
	v_mfma_f32_16x16x32_bf16 v[48:51], v[154:157], v[186:189], v[48:51]
	v_mfma_f32_16x16x32_bf16 v[40:43], v[162:165], v[186:189], v[40:43]
	v_mfma_f32_16x16x32_bf16 v[32:35], v[154:157], v[194:197], v[32:35]
	v_mfma_f32_16x16x32_bf16 v[24:27], v[162:165], v[194:197], v[24:27]
	v_mfma_f32_16x16x32_bf16 v[16:19], v[154:157], v[202:205], v[16:19]
	v_mfma_f32_16x16x32_bf16 v[8:11], v[162:165], v[202:205], v[8:11]
	s_setprio 0
	s_barrier
	s_add_u32 s22, s22, 0x40080
	s_addc_u32 s23, s23, 0
	s_add_i32 s24, s24, s27
	v_lshl_add_u64 v[146:147], s[22:23], 0, v[132:133]
	s_mov_b32 m0, s24
	s_nop 0
	global_load_lds_dwordx4 v[146:147], off
	v_lshl_add_u64 v[146:147], s[22:23], 0, v[128:129]
	s_add_i32 m0, s24, 0x2000
	s_nop 0
	global_load_lds_dwordx4 v[146:147], off
	s_waitcnt vmcnt(6)
	s_barrier
	s_setprio 1
	v_mfma_f32_16x16x32_bf16 v[52:55], v[206:209], v[166:169], v[52:55]
	v_mfma_f32_16x16x32_bf16 v[44:47], v[214:217], v[166:169], v[44:47]
	v_mfma_f32_16x16x32_bf16 v[36:39], v[206:209], v[182:185], v[36:39]
	v_mfma_f32_16x16x32_bf16 v[28:31], v[214:217], v[182:185], v[28:31]
	v_mfma_f32_16x16x32_bf16 v[20:23], v[206:209], v[190:193], v[20:23]
	v_mfma_f32_16x16x32_bf16 v[12:15], v[214:217], v[190:193], v[12:15]
	v_mfma_f32_16x16x32_bf16 v[4:7], v[206:209], v[198:201], v[4:7]
	v_mfma_f32_16x16x32_bf16 v[0:3], v[214:217], v[198:201], v[0:3]
	v_mfma_f32_16x16x32_bf16 v[52:55], v[210:213], v[178:181], v[52:55]
	v_mfma_f32_16x16x32_bf16 v[44:47], v[218:221], v[178:181], v[44:47]
	v_mfma_f32_16x16x32_bf16 v[36:39], v[210:213], v[186:189], v[36:39]
	v_mfma_f32_16x16x32_bf16 v[28:31], v[218:221], v[186:189], v[28:31]
	v_mfma_f32_16x16x32_bf16 v[20:23], v[210:213], v[194:197], v[20:23]
	v_mfma_f32_16x16x32_bf16 v[12:15], v[218:221], v[194:197], v[12:15]
	v_mfma_f32_16x16x32_bf16 v[4:7], v[210:213], v[202:205], v[4:7]
	v_mfma_f32_16x16x32_bf16 v[0:3], v[218:221], v[202:205], v[0:3]
	s_setprio 0
	s_add_i32 s47, s47, 2
	s_add_u32 s20, s20, 0x100
	s_addc_u32 s21, s21, 0
	s_add_u32 s45, s45, 0x100
	s_addc_u32 s46, s46, 0
	s_cmp_gt_u32 s47, 13
	s_barrier
.LBB0_922:
	ds_read_b128 v[146:149], v173
	ds_read_b128 v[154:157], v173 offset:1024
	ds_read_b128 v[158:161], v173 offset:2048
	ds_read_b128 v[162:165], v173 offset:3072
	s_add_u32 s22, s20, 0xfffc0080
	s_addc_u32 s23, s21, -1
	s_cmp_eq_u32 s47, 12
	s_cselect_b32 s25, s13, s23
	s_cselect_b32 s24, s43, s22
	s_cselect_b32 s23, s11, s46
	s_cselect_b32 s22, s44, s45
	v_lshl_add_u64 v[150:151], s[20:21], 0, v[138:139]
	s_add_i32 m0, s19, 0xc000
	ds_read_b128 v[166:169], v174
	ds_read_b128 v[178:181], v174 offset:1024
	ds_read_b128 v[182:185], v174 offset:2048
	ds_read_b128 v[186:189], v174 offset:3072
	ds_read_b128 v[190:193], v174 offset:4096
	ds_read_b128 v[194:197], v174 offset:5120
	ds_read_b128 v[198:201], v174 offset:6144
	ds_read_b128 v[202:205], v174 offset:7168
	global_load_lds_dwordx4 v[150:151], off
	v_lshl_add_u64 v[150:151], s[20:21], 0, v[140:141]
	s_add_i32 m0, s19, 0xe000
	s_nop 0
	global_load_lds_dwordx4 v[150:151], off
	s_waitcnt lgkmcnt(8)
	s_barrier
	s_waitcnt lgkmcnt(0)
	s_setprio 1
	s_waitcnt lgkmcnt(0)
	v_mfma_f32_16x16x32_bf16 v[124:127], v[146:149], v[166:169], v[124:127]
	v_mfma_f32_16x16x32_bf16 v[120:123], v[158:161], v[166:169], v[120:123]
	v_mfma_f32_16x16x32_bf16 v[112:115], v[146:149], v[182:185], v[112:115]
	v_mfma_f32_16x16x32_bf16 v[104:107], v[158:161], v[182:185], v[104:107]
	v_mfma_f32_16x16x32_bf16 v[92:95], v[146:149], v[190:193], v[92:95]
	v_mfma_f32_16x16x32_bf16 v[88:91], v[158:161], v[190:193], v[88:91]
	v_mfma_f32_16x16x32_bf16 v[80:83], v[146:149], v[198:201], v[80:83]
	v_mfma_f32_16x16x32_bf16 v[72:75], v[158:161], v[198:201], v[72:75]
	v_mfma_f32_16x16x32_bf16 v[124:127], v[154:157], v[178:181], v[124:127]
	v_mfma_f32_16x16x32_bf16 v[120:123], v[162:165], v[178:181], v[120:123]
	v_mfma_f32_16x16x32_bf16 v[112:115], v[154:157], v[186:189], v[112:115]
	v_mfma_f32_16x16x32_bf16 v[104:107], v[162:165], v[186:189], v[104:107]
	v_mfma_f32_16x16x32_bf16 v[92:95], v[154:157], v[194:197], v[92:95]
	v_mfma_f32_16x16x32_bf16 v[88:91], v[162:165], v[194:197], v[88:91]
	v_mfma_f32_16x16x32_bf16 v[80:83], v[154:157], v[202:205], v[80:83]
	v_mfma_f32_16x16x32_bf16 v[72:75], v[162:165], v[202:205], v[72:75]
	s_setprio 0
	s_barrier
	s_add_i32 s48, s38, s27
	v_lshl_add_u64 v[150:151], s[22:23], 0, v[132:133]
	s_mov_b32 m0, s48
	ds_read_b128 v[206:209], v175
	ds_read_b128 v[210:213], v175 offset:1024
	ds_read_b128 v[214:217], v175 offset:2048
	ds_read_b128 v[218:221], v175 offset:3072
	global_load_lds_dwordx4 v[150:151], off
	v_lshl_add_u64 v[222:223], s[22:23], 0, v[128:129]
	s_add_i32 m0, s48, 0x2000
	s_nop 0
	global_load_lds_dwordx4 v[222:223], off
	s_barrier
; #define PG8_STAGE(bufoff, gbase, voff) do { _Pragma("unroll") for (int _i = 0; _i < 2; ++_i) \
;         __builtin_amdgcn_global_load_lds((const unsigned*)((const char*)(gbase) + (voff)[_i]), (LAS unsigned*)(lds + (bufoff) + ldsw + _i * 8192), 16, 0, 0); } while (0)
; #define PG8_LDA(dst, b, h) do { _Pragma("unroll") for (int m = 0; m < 4; ++m) _Pragma("unroll") for (int k = 0; k < 2; ++k) dst[m][k] = *(const LAS bf16x8*)(lds + PG8_SA(b, h) + aoff + m * 2048 + k * 1024); } while (0)
; #define PG8_LDB(dst, b, h) do { _Pragma("unroll") for (int n = 0; n < 2; ++n) _Pragma("unroll") for (int k = 0; k < 2; ++k) dst[n][k] = *(const LAS bf16x8*)(lds + PG8_SB(b, h) + boff + n * 2048 + k * 1024); } while (0)
; #define PG8_MMA(ai, bj, At, Bt) do { __builtin_amdgcn_s_setprio(1); _Pragma("unroll") for (int m = 0; m < 4; ++m) _Pragma("unroll") for (int n = 0; n < 2; ++n) _Pragma("unroll") for (int k = 0; k < 2; ++k) \
;         acc[ai][bj][m][n] = __builtin_amdgcn_mfma_f32_16x16x32_bf16(Bt[n][k], At[m][k], acc[ai][bj][m][n], 0, 0, 0); __builtin_amdgcn_s_setprio(0); } while (0)
; #define PG8_WAIT_V(n) asm volatile("s_waitcnt vmcnt(" #n ")" ::: "memory")
; #define PG8_WAIT_L(n) asm volatile("s_waitcnt lgkmcnt(" #n ")" ::: "memory")
; #define PG8_BAR __builtin_amdgcn_s_barrier()
; #define PG8_SCHED __builtin_amdgcn_sched_barrier(0)
; template <class Epi>
; __device__ __forceinline__ void gemm_phase(LAS unsigned char* lds, const Gemm g, const StaticOrder& S, const Epi& E) {
;     ...
;             PG8_BAR; PG8_WAIT_L(0); PG8_MMA(0, 1, At, B1); PG8_BAR;
;             PG8_LDA(At, 0, 1); PG8_STAGE(PG8_SA(0, 0), a2, voffA);
;             PG8_BAR; PG8_WAIT_L(0); PG8_MMA(1, 0, At, B0); PG8_BAR; PG8_SCHED;
;             PG8_STAGE(PG8_SB(0, 1), b2 + hstepB, voffB);
;             PG8_WAIT_V(6); PG8_BAR; PG8_MMA(1, 1, At, B1); PG8_BAR;
;             PG8_LDB(B0, 1, 0); PG8_SCHED; PG8_LDA(At, 1, 0); PG8_STAGE(PG8_SA(0, 1), a2 + hstepA, voffA);
	s_waitcnt lgkmcnt(0)
	s_setprio 1
	s_waitcnt lgkmcnt(0)
	v_mfma_f32_16x16x32_bf16 v[116:119], v[206:209], v[166:169], v[116:119]
	v_mfma_f32_16x16x32_bf16 v[108:111], v[214:217], v[166:169], v[108:111]
	v_mfma_f32_16x16x32_bf16 v[100:103], v[206:209], v[182:185], v[100:103]
	v_mfma_f32_16x16x32_bf16 v[96:99], v[214:217], v[182:185], v[96:99]
	v_mfma_f32_16x16x32_bf16 v[84:87], v[206:209], v[190:193], v[84:87]
	v_mfma_f32_16x16x32_bf16 v[76:79], v[214:217], v[190:193], v[76:79]
	v_mfma_f32_16x16x32_bf16 v[68:71], v[206:209], v[198:201], v[68:71]
	v_mfma_f32_16x16x32_bf16 v[64:67], v[214:217], v[198:201], v[64:67]
	v_mfma_f32_16x16x32_bf16 v[116:119], v[210:213], v[178:181], v[116:119]
	v_mfma_f32_16x16x32_bf16 v[108:111], v[218:221], v[178:181], v[108:111]
	v_mfma_f32_16x16x32_bf16 v[100:103], v[210:213], v[186:189], v[100:103]
	v_mfma_f32_16x16x32_bf16 v[96:99], v[218:221], v[186:189], v[96:99]
	v_mfma_f32_16x16x32_bf16 v[84:87], v[210:213], v[194:197], v[84:87]
	v_mfma_f32_16x16x32_bf16 v[76:79], v[218:221], v[194:197], v[76:79]
	v_mfma_f32_16x16x32_bf16 v[68:71], v[210:213], v[202:205], v[68:71]
	v_mfma_f32_16x16x32_bf16 v[64:67], v[218:221], v[202:205], v[64:67]
	s_setprio 0
	s_mov_b32 m0, s19
	v_lshl_add_u64 v[224:225], s[24:25], 0, v[134:135]
	s_barrier
	ds_read_b128 v[166:169], v174 offset:16384
	ds_read_b128 v[178:181], v174 offset:17408
	ds_read_b128 v[182:185], v174 offset:18432
	ds_read_b128 v[186:189], v174 offset:19456
	ds_read_b128 v[190:193], v174 offset:20480
	ds_read_b128 v[194:197], v174 offset:21504
	ds_read_b128 v[198:201], v174 offset:22528
	ds_read_b128 v[202:205], v174 offset:23552
	global_load_lds_dwordx4 v[224:225], off
	v_lshl_add_u64 v[226:227], s[24:25], 0, v[130:131]
	s_mov_b32 m0, s30
	s_nop 0
	global_load_lds_dwordx4 v[226:227], off
	s_barrier
	s_waitcnt lgkmcnt(0)
	s_setprio 1
	s_waitcnt lgkmcnt(0)
	v_mfma_f32_16x16x32_bf16 v[60:63], v[146:149], v[166:169], v[60:63]
	v_mfma_f32_16x16x32_bf16 v[56:59], v[158:161], v[166:169], v[56:59]
	v_mfma_f32_16x16x32_bf16 v[48:51], v[146:149], v[182:185], v[48:51]
	v_mfma_f32_16x16x32_bf16 v[40:43], v[158:161], v[182:185], v[40:43]
	v_mfma_f32_16x16x32_bf16 v[32:35], v[146:149], v[190:193], v[32:35]
	v_mfma_f32_16x16x32_bf16 v[24:27], v[158:161], v[190:193], v[24:27]
	v_mfma_f32_16x16x32_bf16 v[16:19], v[146:149], v[198:201], v[16:19]
	v_mfma_f32_16x16x32_bf16 v[8:11], v[158:161], v[198:201], v[8:11]
	v_mfma_f32_16x16x32_bf16 v[60:63], v[154:157], v[178:181], v[60:63]
	v_mfma_f32_16x16x32_bf16 v[56:59], v[162:165], v[178:181], v[56:59]
	v_mfma_f32_16x16x32_bf16 v[48:51], v[154:157], v[186:189], v[48:51]
	v_mfma_f32_16x16x32_bf16 v[40:43], v[162:165], v[186:189], v[40:43]
	v_mfma_f32_16x16x32_bf16 v[32:35], v[154:157], v[194:197], v[32:35]
	v_mfma_f32_16x16x32_bf16 v[24:27], v[162:165], v[194:197], v[24:27]
	v_mfma_f32_16x16x32_bf16 v[16:19], v[154:157], v[202:205], v[16:19]
	v_mfma_f32_16x16x32_bf16 v[8:11], v[162:165], v[202:205], v[8:11]
	s_setprio 0
	s_barrier
	s_add_u32 s48, s22, 0x40000
	s_addc_u32 s49, s23, 0
	s_add_i32 s50, s39, s27
	v_lshl_add_u64 v[146:147], s[48:49], 0, v[132:133]
	s_mov_b32 m0, s50
	s_nop 0
	global_load_lds_dwordx4 v[146:147], off
	v_lshl_add_u64 v[146:147], s[48:49], 0, v[128:129]
	s_add_i32 m0, s50, 0x2000
	s_nop 0
	global_load_lds_dwordx4 v[146:147], off
	s_waitcnt vmcnt(6)
	s_barrier
	s_setprio 1
	v_mfma_f32_16x16x32_bf16 v[52:55], v[206:209], v[166:169], v[52:55]
	v_mfma_f32_16x16x32_bf16 v[44:47], v[214:217], v[166:169], v[44:47]
	v_mfma_f32_16x16x32_bf16 v[36:39], v[206:209], v[182:185], v[36:39]
	v_mfma_f32_16x16x32_bf16 v[28:31], v[214:217], v[182:185], v[28:31]
	v_mfma_f32_16x16x32_bf16 v[20:23], v[206:209], v[190:193], v[20:23]
	v_mfma_f32_16x16x32_bf16 v[12:15], v[214:217], v[190:193], v[12:15]
	v_mfma_f32_16x16x32_bf16 v[4:7], v[206:209], v[198:201], v[4:7]
	v_mfma_f32_16x16x32_bf16 v[0:3], v[214:217], v[198:201], v[0:3]
	v_mfma_f32_16x16x32_bf16 v[52:55], v[210:213], v[178:181], v[52:55]
	v_mfma_f32_16x16x32_bf16 v[44:47], v[218:221], v[178:181], v[44:47]
	v_mfma_f32_16x16x32_bf16 v[36:39], v[210:213], v[186:189], v[36:39]
	v_mfma_f32_16x16x32_bf16 v[28:31], v[218:221], v[186:189], v[28:31]
	v_mfma_f32_16x16x32_bf16 v[20:23], v[210:213], v[194:197], v[20:23]
	v_mfma_f32_16x16x32_bf16 v[12:15], v[218:221], v[194:197], v[12:15]
	v_mfma_f32_16x16x32_bf16 v[4:7], v[210:213], v[202:205], v[4:7]
	v_mfma_f32_16x16x32_bf16 v[0:3], v[218:221], v[202:205], v[0:3]
	s_setprio 0
	s_add_i32 s48, 0, 0x18000
	v_add_u32_e32 v162, s48, v171
	s_barrier
	ds_read_b128 v[146:149], v162
	ds_read_b128 v[154:157], v162 offset:1024
	ds_read_b128 v[158:161], v162 offset:2048
	ds_read_b128 v[162:165], v162 offset:3072
	s_add_u32 s24, s24, 0x40000
	s_addc_u32 s25, s25, 0
	s_mov_b32 m0, s31
	v_lshl_add_u64 v[206:207], s[24:25], 0, v[134:135]
	ds_read_b128 v[166:169], v174 offset:32768
	ds_read_b128 v[178:181], v174 offset:33792
	ds_read_b128 v[182:185], v174 offset:34816
	ds_read_b128 v[186:189], v174 offset:35840
	ds_read_b128 v[190:193], v174 offset:36864
	ds_read_b128 v[194:197], v174 offset:37888
	ds_read_b128 v[198:201], v174 offset:38912
	ds_read_b128 v[202:205], v174 offset:39936
	global_load_lds_dwordx4 v[206:207], off
	v_lshl_add_u64 v[206:207], s[24:25], 0, v[130:131]
	s_mov_b32 m0, s33
	s_nop 0
	global_load_lds_dwordx4 v[206:207], off
	s_waitcnt lgkmcnt(8)
	s_barrier
; #define PG8_STAGE(bufoff, gbase, voff) do { _Pragma("unroll") for (int _i = 0; _i < 2; ++_i) \
;         __builtin_amdgcn_global_load_lds((const unsigned*)((const char*)(gbase) + (voff)[_i]), (LAS unsigned*)(lds + (bufoff) + ldsw + _i * 8192), 16, 0, 0); } while (0)
; #define PG8_LDA(dst, b, h) do { _Pragma("unroll") for (int m = 0; m < 4; ++m) _Pragma("unroll") for (int k = 0; k < 2; ++k) dst[m][k] = *(const LAS bf16x8*)(lds + PG8_SA(b, h) + aoff + m * 2048 + k * 1024); } while (0)
; #define PG8_LDB(dst, b, h) do { _Pragma("unroll") for (int n = 0; n < 2; ++n) _Pragma("unroll") for (int k = 0; k < 2; ++k) dst[n][k] = *(const LAS bf16x8*)(lds + PG8_SB(b, h) + boff + n * 2048 + k * 1024); } while (0)
; #define PG8_MMA(ai, bj, At, Bt) do { __builtin_amdgcn_s_setprio(1); _Pragma("unroll") for (int m = 0; m < 4; ++m) _Pragma("unroll") for (int n = 0; n < 2; ++n) _Pragma("unroll") for (int k = 0; k < 2; ++k) \
;         acc[ai][bj][m][n] = __builtin_amdgcn_mfma_f32_16x16x32_bf16(Bt[n][k], At[m][k], acc[ai][bj][m][n], 0, 0, 0); __builtin_amdgcn_s_setprio(0); } while (0)
; #define PG8_WAIT_L(n) asm volatile("s_waitcnt lgkmcnt(" #n ")" ::: "memory")
; #define PG8_BAR __builtin_amdgcn_s_barrier()
; #define PG8_SCHED __builtin_amdgcn_sched_barrier(0)
; template <class Epi>
; __device__ __forceinline__ void gemm_phase(LAS unsigned char* lds, const Gemm g, const StaticOrder& S, const Epi& E) {
;     ...
;             PG8_WAIT_L(8); PG8_BAR; PG8_WAIT_L(0); PG8_MMA(0, 0, At, B0); PG8_BAR; PG8_SCHED;
;             PG8_LDB(B1, 1, 1); PG8_STAGE(PG8_SB(1, 0), b3, voffB);
;             PG8_BAR; PG8_WAIT_L(0); PG8_MMA(0, 1, At, B1); PG8_BAR;
;             PG8_LDA(At, 1, 1); PG8_STAGE(PG8_SA(1, 0), a3, voffA);
;             PG8_BAR; PG8_WAIT_L(0); PG8_MMA(1, 0, At, B0); PG8_BAR; PG8_SCHED;
;             PG8_STAGE(PG8_SB(1, 1), b3 + hstepB, voffB);
	s_waitcnt lgkmcnt(0)
	s_setprio 1
	s_waitcnt lgkmcnt(0)
	v_mfma_f32_16x16x32_bf16 v[124:127], v[146:149], v[166:169], v[124:127]
	v_mfma_f32_16x16x32_bf16 v[120:123], v[158:161], v[166:169], v[120:123]
	v_mfma_f32_16x16x32_bf16 v[112:115], v[146:149], v[182:185], v[112:115]
	v_mfma_f32_16x16x32_bf16 v[104:107], v[158:161], v[182:185], v[104:107]
	v_mfma_f32_16x16x32_bf16 v[92:95], v[146:149], v[190:193], v[92:95]
	v_mfma_f32_16x16x32_bf16 v[88:91], v[158:161], v[190:193], v[88:91]
	v_mfma_f32_16x16x32_bf16 v[80:83], v[146:149], v[198:201], v[80:83]
	v_mfma_f32_16x16x32_bf16 v[72:75], v[158:161], v[198:201], v[72:75]
	v_mfma_f32_16x16x32_bf16 v[124:127], v[154:157], v[178:181], v[124:127]
	v_mfma_f32_16x16x32_bf16 v[120:123], v[162:165], v[178:181], v[120:123]
	v_mfma_f32_16x16x32_bf16 v[112:115], v[154:157], v[186:189], v[112:115]
	v_mfma_f32_16x16x32_bf16 v[104:107], v[162:165], v[186:189], v[104:107]
	v_mfma_f32_16x16x32_bf16 v[92:95], v[154:157], v[194:197], v[92:95]
	v_mfma_f32_16x16x32_bf16 v[88:91], v[162:165], v[194:197], v[88:91]
	v_mfma_f32_16x16x32_bf16 v[80:83], v[154:157], v[202:205], v[80:83]
	v_mfma_f32_16x16x32_bf16 v[72:75], v[162:165], v[202:205], v[72:75]
	s_setprio 0
	s_barrier
	s_add_i32 s24, 0, 0x1c000
	s_add_i32 s25, s48, s27
	v_add_u32_e32 v177, s24, v171
	v_lshl_add_u64 v[150:151], v[150:151], 0, s[4:5]
	s_mov_b32 m0, s25
	ds_read_b128 v[206:209], v177
	ds_read_b128 v[210:213], v177 offset:1024
	ds_read_b128 v[214:217], v177 offset:2048
	ds_read_b128 v[218:221], v177 offset:3072
	global_load_lds_dwordx4 v[150:151], off
	v_lshl_add_u64 v[150:151], v[222:223], 0, s[4:5]
	s_add_i32 m0, s25, 0x2000
	s_nop 0
	global_load_lds_dwordx4 v[150:151], off
	s_barrier
	s_waitcnt lgkmcnt(0)
	s_setprio 1
	s_waitcnt lgkmcnt(0)
	v_mfma_f32_16x16x32_bf16 v[116:119], v[206:209], v[166:169], v[116:119]
	v_mfma_f32_16x16x32_bf16 v[108:111], v[214:217], v[166:169], v[108:111]
	v_mfma_f32_16x16x32_bf16 v[100:103], v[206:209], v[182:185], v[100:103]
	v_mfma_f32_16x16x32_bf16 v[96:99], v[214:217], v[182:185], v[96:99]
	v_mfma_f32_16x16x32_bf16 v[84:87], v[206:209], v[190:193], v[84:87]
	v_mfma_f32_16x16x32_bf16 v[76:79], v[214:217], v[190:193], v[76:79]
	v_mfma_f32_16x16x32_bf16 v[68:71], v[206:209], v[198:201], v[68:71]
	v_mfma_f32_16x16x32_bf16 v[64:67], v[214:217], v[198:201], v[64:67]
	v_mfma_f32_16x16x32_bf16 v[116:119], v[210:213], v[178:181], v[116:119]
	v_mfma_f32_16x16x32_bf16 v[108:111], v[218:221], v[178:181], v[108:111]
	v_mfma_f32_16x16x32_bf16 v[100:103], v[210:213], v[186:189], v[100:103]
	v_mfma_f32_16x16x32_bf16 v[96:99], v[218:221], v[186:189], v[96:99]
	v_mfma_f32_16x16x32_bf16 v[84:87], v[210:213], v[194:197], v[84:87]
	v_mfma_f32_16x16x32_bf16 v[76:79], v[218:221], v[194:197], v[76:79]
	v_mfma_f32_16x16x32_bf16 v[68:71], v[210:213], v[202:205], v[68:71]
	v_mfma_f32_16x16x32_bf16 v[64:67], v[218:221], v[202:205], v[64:67]
	s_setprio 0
	s_mov_b32 m0, s35
	v_lshl_add_u64 v[150:151], v[224:225], 0, s[4:5]
	s_barrier
	ds_read_b128 v[166:169], v174 offset:49152
	ds_read_b128 v[178:181], v174 offset:50176
	ds_read_b128 v[182:185], v174 offset:51200
	ds_read_b128 v[186:189], v174 offset:52224
	ds_read_b128 v[190:193], v174 offset:53248
	ds_read_b128 v[194:197], v174 offset:54272
	ds_read_b128 v[198:201], v174 offset:55296
	ds_read_b128 v[202:205], v174 offset:56320
	global_load_lds_dwordx4 v[150:151], off
	v_lshl_add_u64 v[150:151], v[226:227], 0, s[4:5]
	s_mov_b32 m0, s36
	s_nop 0
	global_load_lds_dwordx4 v[150:151], off
	s_barrier
	s_waitcnt lgkmcnt(0)
	s_setprio 1
	s_waitcnt lgkmcnt(0)
	v_mfma_f32_16x16x32_bf16 v[60:63], v[146:149], v[166:169], v[60:63]
	v_mfma_f32_16x16x32_bf16 v[56:59], v[158:161], v[166:169], v[56:59]
	v_mfma_f32_16x16x32_bf16 v[48:51], v[146:149], v[182:185], v[48:51]
	v_mfma_f32_16x16x32_bf16 v[40:43], v[158:161], v[182:185], v[40:43]
	v_mfma_f32_16x16x32_bf16 v[32:35], v[146:149], v[190:193], v[32:35]
	v_mfma_f32_16x16x32_bf16 v[24:27], v[158:161], v[190:193], v[24:27]
	v_mfma_f32_16x16x32_bf16 v[16:19], v[146:149], v[198:201], v[16:19]
	v_mfma_f32_16x16x32_bf16 v[8:11], v[158:161], v[198:201], v[8:11]
	v_mfma_f32_16x16x32_bf16 v[60:63], v[154:157], v[178:181], v[60:63]
	v_mfma_f32_16x16x32_bf16 v[56:59], v[162:165], v[178:181], v[56:59]
	v_mfma_f32_16x16x32_bf16 v[48:51], v[154:157], v[186:189], v[48:51]
	v_mfma_f32_16x16x32_bf16 v[40:43], v[162:165], v[186:189], v[40:43]
	v_mfma_f32_16x16x32_bf16 v[32:35], v[154:157], v[194:197], v[32:35]
	v_mfma_f32_16x16x32_bf16 v[24:27], v[162:165], v[194:197], v[24:27]
	v_mfma_f32_16x16x32_bf16 v[16:19], v[154:157], v[202:205], v[16:19]
	v_mfma_f32_16x16x32_bf16 v[8:11], v[162:165], v[202:205], v[8:11]
	s_setprio 0
	s_barrier
	s_add_u32 s22, s22, 0x40080
	s_addc_u32 s23, s23, 0
	s_add_i32 s24, s24, s27
	v_lshl_add_u64 v[146:147], s[22:23], 0, v[132:133]
	s_mov_b32 m0, s24
	s_nop 0
	global_load_lds_dwordx4 v[146:147], off
	v_lshl_add_u64 v[146:147], s[22:23], 0, v[128:129]
	s_add_i32 m0, s24, 0x2000
	s_nop 0
	global_load_lds_dwordx4 v[146:147], off
	s_waitcnt vmcnt(6)
	s_barrier
; __device__ __forceinline__ unsigned pk2(float lo, float hi) { const f32x2 v = (f32x2){lo, hi}; const bf16x2_t b = __builtin_convertvector(v, bf16x2_t); return __builtin_bit_cast(unsigned, b); }
; #define PG8_MMA(ai, bj, At, Bt) do { __builtin_amdgcn_s_setprio(1); _Pragma("unroll") for (int m = 0; m < 4; ++m) _Pragma("unroll") for (int n = 0; n < 2; ++n) _Pragma("unroll") for (int k = 0; k < 2; ++k) \
;         acc[ai][bj][m][n] = __builtin_amdgcn_mfma_f32_16x16x32_bf16(Bt[n][k], At[m][k], acc[ai][bj][m][n], 0, 0, 0); __builtin_amdgcn_s_setprio(0); } while (0)
; #define PG8_WAIT_V(n) asm volatile("s_waitcnt vmcnt(" #n ")" ::: "memory")
; #define PG8_BAR __builtin_amdgcn_s_barrier()
;     __device__ __forceinline__ void operator()(const f32x4 (&acc)[2][2][4][2], const Unit& u, int wr, int wc, int fr, int fq, const float (&)[8]) const {
;     ...
;         const int col0 = u.pn * BM + wc * 32 + 8 * fq;
; #pragma unroll
;         for (int ai = 0; ai < 2; ++ai)
; #pragma unroll
;             for (int m = 0; m < 4; ++m) { const int row = row0 + ai * HALF + m * 16; const float rs = rsqrtf(ep[ai * 4 + m] * (1.0f / 1024.0f) + EPS);
;                 u16* rowp = O + (size_t)row * ldc + col0;
; #pragma unroll
;                 for (int bj = 0; bj < 2; ++bj) { f32x4 v0 = acc[ai][bj][m][0] * rs, v1 = acc[ai][bj][m][1] * rs;
;                     if (ACT == 1) {
; #pragma unroll
;                         for (int j = 0; j < 4; ++j) { const float a0 = fmaxf(v0[j], 0.f), a1 = fmaxf(v1[j], 0.f); v0[j] = a0 * a0; v1[j] = a1 * a1; } }
;                     u32x4 w; w.x = pk2(v0[0], v0[1]); w.y = pk2(v0[2], v0[3]); w.z = pk2(v1[0], v1[1]); w.w = pk2(v1[2], v1[3]);
;                     *(u32x4*)(rowp + bj * HALF) = w; } }
; template <class Epi>
; __device__ __forceinline__ void gemm_phase(LAS unsigned char* lds, const Gemm g, const StaticOrder& S, const Epi& E) {
;     ...
;             PG8_WAIT_V(6); PG8_BAR; PG8_MMA(1, 1, At, B1); PG8_BAR;
;         }
;         E(acc, cur, wr, wc, fr, fq, epre);
	s_setprio 1
	v_mfma_f32_16x16x32_bf16 v[52:55], v[206:209], v[166:169], v[52:55]
	v_mfma_f32_16x16x32_bf16 v[44:47], v[214:217], v[166:169], v[44:47]
	v_mfma_f32_16x16x32_bf16 v[36:39], v[206:209], v[182:185], v[36:39]
	v_mfma_f32_16x16x32_bf16 v[28:31], v[214:217], v[182:185], v[28:31]
	v_mfma_f32_16x16x32_bf16 v[20:23], v[206:209], v[190:193], v[20:23]
	v_mfma_f32_16x16x32_bf16 v[12:15], v[214:217], v[190:193], v[12:15]
	v_mfma_f32_16x16x32_bf16 v[4:7], v[206:209], v[198:201], v[4:7]
	v_mfma_f32_16x16x32_bf16 v[0:3], v[214:217], v[198:201], v[0:3]
	v_mfma_f32_16x16x32_bf16 v[52:55], v[210:213], v[178:181], v[52:55]
	v_mfma_f32_16x16x32_bf16 v[44:47], v[218:221], v[178:181], v[44:47]
	v_mfma_f32_16x16x32_bf16 v[36:39], v[210:213], v[186:189], v[36:39]
	v_mfma_f32_16x16x32_bf16 v[28:31], v[218:221], v[186:189], v[28:31]
	v_mfma_f32_16x16x32_bf16 v[20:23], v[210:213], v[194:197], v[20:23]
	v_mfma_f32_16x16x32_bf16 v[12:15], v[218:221], v[194:197], v[12:15]
	v_mfma_f32_16x16x32_bf16 v[4:7], v[210:213], v[202:205], v[4:7]
	v_mfma_f32_16x16x32_bf16 v[0:3], v[218:221], v[202:205], v[0:3]
	s_setprio 0
	s_add_i32 s47, s47, 2
	s_add_u32 s20, s20, 0x100
	s_addc_u32 s21, s21, 0
	s_add_u32 s45, s45, 0x100
	s_addc_u32 s46, s46, 0
	s_cmp_gt_u32 s47, 13
	s_barrier
	s_cbranch_scc0 .LBB0_922
	s_bfe_u32 vcc_lo, s18, 0x20003
	s_lshl_b32 vcc_lo, vcc_lo, 10
	s_add_i32 vcc_lo, vcc_lo, 0x20010
	v_lshl_add_u32 v236, v170, 2, vcc_lo
	ds_read_b32 v228, v236
	ds_read_b32 v229, v236 offset:64
	ds_read_b32 v230, v236 offset:128
	ds_read_b32 v231, v236 offset:192
	ds_read_b32 v232, v236 offset:512
	ds_read_b32 v233, v236 offset:576
	ds_read_b32 v234, v236 offset:640
	ds_read_b32 v235, v236 offset:704
	s_waitcnt lgkmcnt(0)
	s_add_u32 vcc_lo, s43, 0x40080
	s_addc_u32 vcc_hi, s13, 0
	s_add_i32 m0, s19, 0xc000
	v_lshl_add_u64 v[236:237], vcc, 0, v[138:139]
	v_lshl_add_u64 v[238:239], vcc, 0, v[140:141]
	global_load_lds_dwordx4 v[236:237], off
	s_add_i32 m0, s19, 0xe000
	s_nop 0
	global_load_lds_dwordx4 v[238:239], off
	v_lshl_add_u32 v154, s18, 8, v170
	v_or_b32_e32 v206, 16, v154
	v_or_b32_e32 v168, 32, v154
	v_or_b32_e32 v162, 48, v154
	v_add_u32_e32 v160, 0x80, v154
	v_add_u32_e32 v156, 0x90, v154
	v_add_u32_e32 v150, 0xa0, v154
	v_add_u32_e32 v146, 0xb0, v154
	v_lshl_or_b32 v208, s42, 8, v172
	v_mov_b64_e32 v[148:149], s[96:97]
	v_ashrrev_i32_e32 v209, 31, v208
	v_mad_i64_i32 v[210:211], s[20:21], v154, s40, v[148:149]
	s_nop 0
	v_lshlrev_b64 v[154:155], 1, v[208:209]
	v_lshl_add_u64 v[208:209], v[210:211], 0, v[154:155]
	s_mov_b32 s42, s10
	s_mov_b32 s18, s12
	s_mov_b64 s[22:23], s[16:17]
	s_waitcnt vmcnt(10)
	s_waitcnt lgkmcnt(0)
	s_waitcnt lgkmcnt(0)
	v_mov_b32_e32 v178, v228
	v_pk_mul_f32 v[126:127], v[126:127], v[178:179] op_sel_hi:[1,0]
	v_pk_mul_f32 v[124:125], v[124:125], v[178:179] op_sel_hi:[1,0]
	v_pk_mul_f32 v[190:191], v[122:123], v[178:179] op_sel_hi:[1,0]
	v_pk_mul_f32 v[122:123], v[120:121], v[178:179] op_sel_hi:[1,0]
	v_cvt_pk_bf16_f32 v120, v124, v125
	v_cvt_pk_bf16_f32 v121, v126, v127
	v_cvt_pk_bf16_f32 v122, v122, v123
	v_cvt_pk_bf16_f32 v123, v190, v191
	v_pk_mul_f32 v[116:117], v[116:117], v[178:179] op_sel_hi:[1,0]
	global_store_dwordx4 v[208:209], v[120:123], off
	s_nop 0
	v_pk_mul_f32 v[118:119], v[118:119], v[178:179] op_sel_hi:[1,0]
	v_pk_mul_f32 v[120:121], v[110:111], v[178:179] op_sel_hi:[1,0]
	v_pk_mul_f32 v[110:111], v[108:109], v[178:179] op_sel_hi:[1,0]
	v_cvt_pk_bf16_f32 v108, v116, v117
	v_cvt_pk_bf16_f32 v109, v118, v119
	v_cvt_pk_bf16_f32 v110, v110, v111
	v_cvt_pk_bf16_f32 v111, v120, v121
	global_store_dwordx4 v[208:209], v[108:111], off offset:256
	s_nop 1
	v_mov_b32_e32 v108, v229
	v_mad_i64_i32 v[110:111], s[20:21], v206, s40, v[148:149]
	v_pk_mul_f32 v[114:115], v[114:115], v[108:109] op_sel_hi:[1,0]
	v_pk_mul_f32 v[112:113], v[112:113], v[108:109] op_sel_hi:[1,0]
	v_pk_mul_f32 v[116:117], v[106:107], v[108:109] op_sel_hi:[1,0]
	v_pk_mul_f32 v[106:107], v[104:105], v[108:109] op_sel_hi:[1,0]
	v_lshl_add_u64 v[110:111], v[110:111], 0, v[154:155]
	v_cvt_pk_bf16_f32 v104, v112, v113
	v_cvt_pk_bf16_f32 v105, v114, v115
	v_cvt_pk_bf16_f32 v106, v106, v107
	v_cvt_pk_bf16_f32 v107, v116, v117
	global_store_dwordx4 v[110:111], v[104:107], off
	v_pk_mul_f32 v[100:101], v[100:101], v[108:109] op_sel_hi:[1,0]
	v_pk_mul_f32 v[112:113], v[98:99], v[108:109] op_sel_hi:[1,0]
	v_pk_mul_f32 v[98:99], v[96:97], v[108:109] op_sel_hi:[1,0]
	v_cvt_pk_bf16_f32 v96, v100, v101
	v_pk_mul_f32 v[102:103], v[102:103], v[108:109] op_sel_hi:[1,0]
	v_cvt_pk_bf16_f32 v98, v98, v99
	s_waitcnt lgkmcnt(0)
	v_cvt_pk_bf16_f32 v97, v102, v103
	v_cvt_pk_bf16_f32 v99, v112, v113
	global_store_dwordx4 v[110:111], v[96:99], off offset:256
	s_nop 0
	s_waitcnt lgkmcnt(0)
; __device__ __forceinline__ unsigned pk2(float lo, float hi) { const f32x2 v = (f32x2){lo, hi}; const bf16x2_t b = __builtin_convertvector(v, bf16x2_t); return __builtin_bit_cast(unsigned, b); }
; #define PG8_WAIT_V(n) asm volatile("s_waitcnt vmcnt(" #n ")" ::: "memory")
; #define PG8_BAR __builtin_amdgcn_s_barrier()
;     __device__ __forceinline__ void operator()(const f32x4 (&acc)[2][2][4][2], const Unit& u, int wr, int wc, int fr, int fq, const float (&)[8]) const {
;     ...
;             for (int m = 0; m < 4; ++m) { const int row = row0 + ai * HALF + m * 16; const float rs = rsqrtf(ep[ai * 4 + m] * (1.0f / 1024.0f) + EPS);
;                 u16* rowp = O + (size_t)row * ldc + col0;
; #pragma unroll
;                 for (int bj = 0; bj < 2; ++bj) { f32x4 v0 = acc[ai][bj][m][0] * rs, v1 = acc[ai][bj][m][1] * rs;
;                     if (ACT == 1) {
; #pragma unroll
;                         for (int j = 0; j < 4; ++j) { const float a0 = fmaxf(v0[j], 0.f), a1 = fmaxf(v1[j], 0.f); v0[j] = a0 * a0; v1[j] = a1 * a1; } }
;                     u32x4 w; w.x = pk2(v0[0], v0[1]); w.y = pk2(v0[2], v0[3]); w.z = pk2(v1[0], v1[1]); w.w = pk2(v1[2], v1[3]);
;                     *(u32x4*)(rowp + bj * HALF) = w; } }
; template <class Epi>
; __device__ __forceinline__ void gemm_phase(LAS unsigned char* lds, const Gemm g, const StaticOrder& S, const Epi& E) {
;     ...
;         if (!has_next) break;
; #pragma unroll
;         for (int a = 0; a < 2; ++a)
; #pragma unroll
;             for (int b = 0; b < 2; ++b)
; #pragma unroll
;                 for (int m = 0; m < 4; ++m)
; #pragma unroll
;                     for (int n = 0; n < 2; ++n) acc[a][b][m][n] = (f32x4){0.f, 0.f, 0.f, 0.f};
;         cur = nxt; cA = nA; cB = nB; ++ui;
;     }
;     PG8_WAIT_V(0);
;     if (wr == 0) PG8_BAR;
;     PG8_BAR;
	v_mad_i64_i32 v[98:99], s[20:21], v168, s40, v[148:149]
	v_lshl_add_u64 v[98:99], v[98:99], 0, v[154:155]
	v_mov_b32_e32 v100, v230
	v_pk_mul_f32 v[94:95], v[94:95], v[100:101] op_sel_hi:[1,0]
	v_pk_mul_f32 v[92:93], v[92:93], v[100:101] op_sel_hi:[1,0]
	v_pk_mul_f32 v[102:103], v[90:91], v[100:101] op_sel_hi:[1,0]
	v_pk_mul_f32 v[90:91], v[88:89], v[100:101] op_sel_hi:[1,0]
	v_cvt_pk_bf16_f32 v88, v92, v93
	v_cvt_pk_bf16_f32 v89, v94, v95
	v_cvt_pk_bf16_f32 v90, v90, v91
	v_cvt_pk_bf16_f32 v91, v102, v103
	v_pk_mul_f32 v[84:85], v[84:85], v[100:101] op_sel_hi:[1,0]
	global_store_dwordx4 v[98:99], v[88:91], off
	s_nop 0
	v_pk_mul_f32 v[86:87], v[86:87], v[100:101] op_sel_hi:[1,0]
	v_pk_mul_f32 v[88:89], v[78:79], v[100:101] op_sel_hi:[1,0]
	v_pk_mul_f32 v[78:79], v[76:77], v[100:101] op_sel_hi:[1,0]
	v_cvt_pk_bf16_f32 v76, v84, v85
	v_cvt_pk_bf16_f32 v77, v86, v87
	v_cvt_pk_bf16_f32 v78, v78, v79
	v_cvt_pk_bf16_f32 v79, v88, v89
	global_store_dwordx4 v[98:99], v[76:79], off offset:256
	s_nop 1
	v_mov_b32_e32 v76, v231
	v_mad_i64_i32 v[78:79], s[20:21], v162, s40, v[148:149]
	v_pk_mul_f32 v[82:83], v[82:83], v[76:77] op_sel_hi:[1,0]
	v_pk_mul_f32 v[80:81], v[80:81], v[76:77] op_sel_hi:[1,0]
	v_pk_mul_f32 v[84:85], v[74:75], v[76:77] op_sel_hi:[1,0]
	v_pk_mul_f32 v[74:75], v[72:73], v[76:77] op_sel_hi:[1,0]
	v_lshl_add_u64 v[78:79], v[78:79], 0, v[154:155]
	v_cvt_pk_bf16_f32 v72, v80, v81
	v_cvt_pk_bf16_f32 v73, v82, v83
	v_cvt_pk_bf16_f32 v74, v74, v75
	v_cvt_pk_bf16_f32 v75, v84, v85
	global_store_dwordx4 v[78:79], v[72:75], off
	v_pk_mul_f32 v[68:69], v[68:69], v[76:77] op_sel_hi:[1,0]
	v_pk_mul_f32 v[80:81], v[66:67], v[76:77] op_sel_hi:[1,0]
	v_pk_mul_f32 v[66:67], v[64:65], v[76:77] op_sel_hi:[1,0]
	v_cvt_pk_bf16_f32 v64, v68, v69
	v_pk_mul_f32 v[70:71], v[70:71], v[76:77] op_sel_hi:[1,0]
	v_cvt_pk_bf16_f32 v66, v66, v67
	s_waitcnt lgkmcnt(0)
	v_cvt_pk_bf16_f32 v65, v70, v71
	v_cvt_pk_bf16_f32 v67, v80, v81
	global_store_dwordx4 v[78:79], v[64:67], off offset:256
	s_waitcnt lgkmcnt(0)
	s_nop 0
	s_nop 0
	s_nop 0
	s_nop 1
	v_mad_i64_i32 v[66:67], s[20:21], v160, s40, v[148:149]
	v_lshl_add_u64 v[66:67], v[66:67], 0, v[154:155]
	v_mov_b32_e32 v68, v232
	v_pk_mul_f32 v[62:63], v[62:63], v[68:69] op_sel_hi:[1,0]
	v_pk_mul_f32 v[60:61], v[60:61], v[68:69] op_sel_hi:[1,0]
	v_pk_mul_f32 v[70:71], v[58:59], v[68:69] op_sel_hi:[1,0]
	v_pk_mul_f32 v[58:59], v[56:57], v[68:69] op_sel_hi:[1,0]
	v_cvt_pk_bf16_f32 v56, v60, v61
	v_cvt_pk_bf16_f32 v57, v62, v63
	v_cvt_pk_bf16_f32 v58, v58, v59
	v_cvt_pk_bf16_f32 v59, v70, v71
	v_pk_mul_f32 v[52:53], v[52:53], v[68:69] op_sel_hi:[1,0]
	global_store_dwordx4 v[66:67], v[56:59], off
	s_nop 0
	v_pk_mul_f32 v[54:55], v[54:55], v[68:69] op_sel_hi:[1,0]
	v_pk_mul_f32 v[56:57], v[46:47], v[68:69] op_sel_hi:[1,0]
	v_pk_mul_f32 v[46:47], v[44:45], v[68:69] op_sel_hi:[1,0]
	v_cvt_pk_bf16_f32 v44, v52, v53
	v_cvt_pk_bf16_f32 v45, v54, v55
	v_cvt_pk_bf16_f32 v46, v46, v47
	v_cvt_pk_bf16_f32 v47, v56, v57
	global_store_dwordx4 v[66:67], v[44:47], off offset:256
	s_nop 1
	v_mov_b32_e32 v44, v233
	v_mad_i64_i32 v[46:47], s[20:21], v156, s40, v[148:149]
	v_pk_mul_f32 v[50:51], v[50:51], v[44:45] op_sel_hi:[1,0]
	v_pk_mul_f32 v[48:49], v[48:49], v[44:45] op_sel_hi:[1,0]
	v_pk_mul_f32 v[52:53], v[42:43], v[44:45] op_sel_hi:[1,0]
	v_pk_mul_f32 v[42:43], v[40:41], v[44:45] op_sel_hi:[1,0]
	v_lshl_add_u64 v[46:47], v[46:47], 0, v[154:155]
	v_cvt_pk_bf16_f32 v40, v48, v49
	v_cvt_pk_bf16_f32 v41, v50, v51
	v_cvt_pk_bf16_f32 v42, v42, v43
	v_cvt_pk_bf16_f32 v43, v52, v53
	global_store_dwordx4 v[46:47], v[40:43], off
	v_pk_mul_f32 v[36:37], v[36:37], v[44:45] op_sel_hi:[1,0]
	v_pk_mul_f32 v[48:49], v[30:31], v[44:45] op_sel_hi:[1,0]
	v_pk_mul_f32 v[30:31], v[28:29], v[44:45] op_sel_hi:[1,0]
	v_cvt_pk_bf16_f32 v28, v36, v37
	v_pk_mul_f32 v[38:39], v[38:39], v[44:45] op_sel_hi:[1,0]
	v_cvt_pk_bf16_f32 v30, v30, v31
	s_waitcnt lgkmcnt(0)
	v_cvt_pk_bf16_f32 v29, v38, v39
	v_cvt_pk_bf16_f32 v31, v48, v49
	global_store_dwordx4 v[46:47], v[28:31], off offset:256
	s_waitcnt lgkmcnt(0)
	s_nop 0
	s_nop 0
	s_nop 0
	s_nop 1
	v_mad_i64_i32 v[30:31], s[20:21], v150, s40, v[148:149]
	v_lshl_add_u64 v[30:31], v[30:31], 0, v[154:155]
	v_mov_b32_e32 v36, v234
	v_pk_mul_f32 v[34:35], v[34:35], v[36:37] op_sel_hi:[1,0]
	v_pk_mul_f32 v[32:33], v[32:33], v[36:37] op_sel_hi:[1,0]
	v_pk_mul_f32 v[38:39], v[26:27], v[36:37] op_sel_hi:[1,0]
	v_pk_mul_f32 v[26:27], v[24:25], v[36:37] op_sel_hi:[1,0]
	v_cvt_pk_bf16_f32 v24, v32, v33
	v_cvt_pk_bf16_f32 v25, v34, v35
	v_cvt_pk_bf16_f32 v26, v26, v27
	v_cvt_pk_bf16_f32 v27, v38, v39
	v_pk_mul_f32 v[20:21], v[20:21], v[36:37] op_sel_hi:[1,0]
	global_store_dwordx4 v[30:31], v[24:27], off
	s_nop 0
	v_pk_mul_f32 v[22:23], v[22:23], v[36:37] op_sel_hi:[1,0]
	v_pk_mul_f32 v[24:25], v[14:15], v[36:37] op_sel_hi:[1,0]
	v_pk_mul_f32 v[14:15], v[12:13], v[36:37] op_sel_hi:[1,0]
	v_cvt_pk_bf16_f32 v12, v20, v21
	v_cvt_pk_bf16_f32 v13, v22, v23
	v_cvt_pk_bf16_f32 v14, v14, v15
	v_cvt_pk_bf16_f32 v15, v24, v25
	global_store_dwordx4 v[30:31], v[12:15], off offset:256
	s_nop 1
	v_mov_b32_e32 v12, v235
	v_mad_i64_i32 v[14:15], s[20:21], v146, s40, v[148:149]
	v_pk_mul_f32 v[18:19], v[18:19], v[12:13] op_sel_hi:[1,0]
	v_pk_mul_f32 v[16:17], v[16:17], v[12:13] op_sel_hi:[1,0]
	v_pk_mul_f32 v[20:21], v[10:11], v[12:13] op_sel_hi:[1,0]
	v_pk_mul_f32 v[10:11], v[8:9], v[12:13] op_sel_hi:[1,0]
	v_lshl_add_u64 v[14:15], v[14:15], 0, v[154:155]
	v_cvt_pk_bf16_f32 v8, v16, v17
	v_cvt_pk_bf16_f32 v9, v18, v19
	v_cvt_pk_bf16_f32 v10, v10, v11
	v_cvt_pk_bf16_f32 v11, v20, v21
	global_store_dwordx4 v[14:15], v[8:11], off
	v_pk_mul_f32 v[6:7], v[6:7], v[12:13] op_sel_hi:[1,0]
	v_pk_mul_f32 v[4:5], v[4:5], v[12:13] op_sel_hi:[1,0]
	v_pk_mul_f32 v[8:9], v[2:3], v[12:13] op_sel_hi:[1,0]
	v_pk_mul_f32 v[2:3], v[0:1], v[12:13] op_sel_hi:[1,0]
	v_cvt_pk_bf16_f32 v0, v4, v5
	v_cvt_pk_bf16_f32 v1, v6, v7
	v_cvt_pk_bf16_f32 v2, v2, v3
	v_cvt_pk_bf16_f32 v3, v8, v9
	s_and_b64 vcc, exec, s[0:1]
	s_mov_b64 s[20:21], s[14:15]
	global_store_dwordx4 v[14:15], v[0:3], off offset:256
	s_cbranch_vccz .LBB0_919
	s_waitcnt vmcnt(0)
	v_readlane_b32 s40, v251, 54
	s_cmpk_gt_u32 s7, 0xff
	v_readlane_b32 s41, v251, 55
	s_cbranch_scc1 .LBB0_926
	s_barrier

; #define PG8_STAGE(bufoff, gbase, voff) do { _Pragma("unroll") for (int _i = 0; _i < 2; ++_i) \
;         __builtin_amdgcn_global_load_lds((const unsigned*)((const char*)(gbase) + (voff)[_i]), (LAS unsigned*)(lds + (bufoff) + ldsw + _i * 8192), 16, 0, 0); } while (0)
; #define PG8_WAIT_V(n) asm volatile("s_waitcnt vmcnt(" #n ")" ::: "memory")
; #define PG8_BAR __builtin_amdgcn_s_barrier()
; template <class Epi>
; __device__ __forceinline__ void gemm_phase(LAS unsigned char* lds, const Gemm g, const StaticOrder& S, const Epi& E) {
;     const int tid = threadIdx.x, wid = __builtin_amdgcn_readfirstlane(tid >> 6), lane = tid & 63, wr = wid >> 2, wc = wid & 3, fr = lane & 15, fq = lane >> 4;
;     const int K = g.K, nt = K / BK, lda = g.lda;
;     unsigned voffA[2], voffB[2];
; #pragma unroll
;     for (int i = 0; i < 2; ++i) { int R, C; stage_rc(tid * 16 + i * 8192, R, C); const int Rb = Epi::PERM ? ((R & ~31) + perm32(R & 31)) : R;
;         voffA[i] = (unsigned)(R * lda + C) * 2u; voffB[i] = (unsigned)(Rb * K + C) * 2u; }
;     const size_t kstep = (size_t)(BK * 2);
;     const size_t hstepA = (size_t)HALF * lda * 2, hstepB = (size_t)HALF * K * 2;
;     const size_t tstepA = 2 * hstepA, tstepB = 2 * hstepB;
;     const unsigned ldsw = (unsigned)wid * 1024u;
;     const int aoff = lds_byte(wr * 64 + fr, fq * 8), boff = lds_byte(wc * 32 + fr, fq * 8);
;     ...
;     PG8_STAGE(PG8_SB(0, 0), cB, voffB); PG8_STAGE(PG8_SA(0, 0), cA, voffA); PG8_STAGE(PG8_SB(0, 1), cB + hstepB, voffB); PG8_STAGE(PG8_SA(0, 1), cA + hstepA, voffA);
;     if (wr == 1) PG8_BAR;
;     PG8_WAIT_V(4); PG8_BAR;
;     PG8_STAGE(PG8_SB(1, 0), cB + kstep, voffB); PG8_STAGE(PG8_SA(1, 0), cA + kstep, voffA); PG8_STAGE(PG8_SB(1, 1), cB + hstepB + kstep, voffB);
;     PG8_WAIT_V(6); PG8_BAR;
.LBB0_1196:
	s_lshl_b32 s4, s4, 5
	s_and_b32 s8, s4, 0x60
	s_mov_b64 s[4:5], 0x80
	s_add_i32 m0, s19, 0x18000
	v_lshl_add_u64 v[6:7], v[6:7], 0, s[4:5]
	s_lshl_b32 s6, s1, 13
	s_lshl_b32 s12, s8, 7
	s_waitcnt vmcnt(4)
	s_barrier
	global_load_lds_dwordx4 v[6:7], off
	v_lshl_add_u64 v[4:5], v[4:5], 0, s[4:5]
	s_add_i32 m0, s19, 0x1a000
	s_add_i32 s34, s19, 0x8000
	s_add_i32 s35, s19, 0xa000
	global_load_lds_dwordx4 v[4:5], off
	v_lshl_add_u64 v[2:3], v[2:3], 0, s[4:5]
	s_mov_b32 m0, s34
	s_add_u32 s10, s22, 0x40080
	global_load_lds_dwordx4 v[2:3], off
	v_lshl_add_u64 v[0:1], v[0:1], 0, s[4:5]
	s_mov_b32 m0, s35
	s_addc_u32 s11, s23, 0
	global_load_lds_dwordx4 v[0:1], off
	s_add_i32 m0, s19, 0x1c000
	v_lshl_add_u64 v[0:1], s[10:11], 0, v[130:131]
	global_load_lds_dwordx4 v[0:1], off
	v_lshl_add_u64 v[0:1], s[10:11], 0, v[134:135]
	s_add_i32 m0, s19, 0x1e000
	v_bfe_u32 v2, v152, 4, 2
	global_load_lds_dwordx4 v[0:1], off
	v_and_b32_e32 v1, 15, v152
	v_lshlrev_b32_e32 v0, 4, v2
	v_lshlrev_b32_e32 v3, 2, v152
	v_lshl_or_b32 v153, s1, 6, v1
	v_lshl_or_b32 v1, v1, 6, v0
	v_and_b32_e32 v3, 32, v3
	s_sext_i32_i8 s40, s0
	v_bitop3_b32 v4, v1, s6, v3 bitop3:0xde
	v_lshlrev_b32_e32 v1, 6, v152
	s_movk_i32 s0, 0x3c0
	v_and_or_b32 v1, v1, s0, v0
	v_bitop3_b32 v174, s12, v1, v3 bitop3:0xf6
	v_mov_b32_e32 v1, v131
	v_lshl_add_u64 v[0:1], s[74:75], 0, v[0:1]
	s_mov_b64 s[0:1], 0x3cbc4000
	v_lshl_add_u64 v[136:137], v[0:1], 0, s[0:1]
	v_lshlrev_b32_e32 v0, 8, v152
	v_and_b32_e32 v0, 0x38000, v0
	v_lshlrev_b32_e32 v1, 11, v10
	v_or3_b32 v0, v8, v0, v1
	v_add_u32_e32 v138, v0, v9
	v_lshlrev_b32_e32 v0, 4, v11
	v_and_b32_e32 v0, 0x78000, v0
	s_waitcnt vmcnt(6)
	v_or3_b32 v0, v8, v0, v1
	v_add_u32_e32 v140, v0, v9
	s_add_i32 s37, 0, 0x10000
	s_add_i32 s38, 0, 0x14000
	v_mbcnt_lo_u32_b32 v0, -1, 0
	s_ashr_i32 s36, s92, 31
	v_lshl_or_b32 v175, v2, 3, s8
	v_mov_b32_e32 v139, v131
	v_mov_b32_e32 v141, v131
	v_mov_b64_e32 v[142:143], 0x1000
	v_mov_b64_e32 v[144:145], 0xfff
	v_add_u32_e32 v176, s37, v174
	v_add_u32_e32 v177, 0, v4
	v_add_u32_e32 v178, s38, v174
	v_mbcnt_hi_u32_b32 v179, -1, v0
	s_mov_b32 s6, 0x3a800000
	s_mov_b32 s8, 0x358637bd
	s_mov_b32 s39, 0x800000
	s_add_u32 vcc_lo, s20, 0x40080
	s_addc_u32 vcc_hi, s21, 0
	s_add_i32 m0, s19, 0xc000
	v_lshl_add_u64 v[236:237], vcc, 0, v[138:139]
	v_lshl_add_u64 v[238:239], vcc, 0, v[140:141]
	global_load_lds_dwordx4 v[236:237], off
	s_add_i32 m0, s19, 0xe000
	s_nop 0
	global_load_lds_dwordx4 v[238:239], off
	s_waitcnt vmcnt(0)
	s_barrier

; #define PG8_STAGE(bufoff, gbase, voff) do { _Pragma("unroll") for (int _i = 0; _i < 2; ++_i) \
;         __builtin_amdgcn_global_load_lds((const unsigned*)((const char*)(gbase) + (voff)[_i]), (LAS unsigned*)(lds + (bufoff) + ldsw + _i * 8192), 16, 0, 0); } while (0)
; #define PG8_LDA(dst, b, h) do { _Pragma("unroll") for (int m = 0; m < 4; ++m) _Pragma("unroll") for (int k = 0; k < 2; ++k) dst[m][k] = *(const LAS bf16x8*)(lds + PG8_SA(b, h) + aoff + m * 2048 + k * 1024); } while (0)
; #define PG8_LDB(dst, b, h) do { _Pragma("unroll") for (int n = 0; n < 2; ++n) _Pragma("unroll") for (int k = 0; k < 2; ++k) dst[n][k] = *(const LAS bf16x8*)(lds + PG8_SB(b, h) + boff + n * 2048 + k * 1024); } while (0)
; #define PG8_MMA(ai, bj, At, Bt) do { __builtin_amdgcn_s_setprio(1); _Pragma("unroll") for (int m = 0; m < 4; ++m) _Pragma("unroll") for (int n = 0; n < 2; ++n) _Pragma("unroll") for (int k = 0; k < 2; ++k) \
;         acc[ai][bj][m][n] = __builtin_amdgcn_mfma_f32_16x16x32_bf16(Bt[n][k], At[m][k], acc[ai][bj][m][n], 0, 0, 0); __builtin_amdgcn_s_setprio(0); } while (0)
; #define PG8_WAIT_L(n) asm volatile("s_waitcnt lgkmcnt(" #n ")" ::: "memory")
; #define PG8_BAR __builtin_amdgcn_s_barrier()
; #define PG8_SCHED __builtin_amdgcn_sched_barrier(0)
; template <class Epi>
; __device__ __forceinline__ void gemm_phase(LAS unsigned char* lds, const Gemm g, const StaticOrder& S, const Epi& E) {
;     ...
;         for (int t = 0; t < nt; t += 2) {
;             const bool last = (t == nt - 2);
;             const char* a1 = cA + (size_t)(t + 1) * kstep;
;             const char* a2 = last ? nA : cA + (size_t)(t + 2) * kstep; const char* b2 = last ? nB : cB + (size_t)(t + 2) * kstep;
;             const char* a3 = a2 + kstep; const char* b3 = b2 + kstep;
;             if (last) E.pre(cur, wr, fr, epre);
;             PG8_LDB(B0, 0, 0); PG8_SCHED; PG8_LDA(At, 0, 0); PG8_STAGE(PG8_SA(1, 1), a1 + hstepA, voffA);
;             PG8_WAIT_L(8); PG8_BAR; PG8_WAIT_L(0); PG8_MMA(0, 0, At, B0); PG8_BAR; PG8_SCHED;
;             PG8_LDB(B1, 0, 1); PG8_STAGE(PG8_SB(0, 0), b2, voffB);
;             PG8_BAR; PG8_WAIT_L(0); PG8_MMA(0, 1, At, B1); PG8_BAR;
;             PG8_LDA(At, 0, 1); PG8_STAGE(PG8_SA(0, 0), a2, voffA);
;             PG8_BAR; PG8_WAIT_L(0); PG8_MMA(1, 0, At, B0); PG8_BAR; PG8_SCHED;
.LBB0_1203:
	s_ashr_i32 s13, s12, 31
	v_cmp_lt_i64_e32 vcc, s[14:15], v[142:143]
	s_lshl_b64 s[14:15], s[12:13], 19
	s_add_u32 s14, s76, s14
	s_addc_u32 s15, s77, s15
	s_and_b64 s[16:17], vcc, exec
	s_cselect_b32 s13, s15, s21
	s_cselect_b32 s41, s14, s20
	s_ashr_i32 s11, s10, 31
	s_lshl_b64 s[16:17], s[10:11], 19
	s_add_u32 s16, s26, s16
	s_addc_u32 s17, s27, s17
	s_and_b64 s[24:25], vcc, exec
	s_cselect_b32 s11, s17, s23
	s_cselect_b32 s42, s16, s22
	s_add_u32 s20, s20, 0x40080
	s_addc_u32 s21, s21, 0
	s_add_u32 s43, s22, 0x100
	s_addc_u32 s44, s23, 0
	s_mov_b32 s45, -2
	ds_read_b128 v[146:149], v176
	ds_read_b128 v[154:157], v176 offset:1024
	ds_read_b128 v[158:161], v176 offset:2048
	ds_read_b128 v[162:165], v176 offset:3072
	s_add_u32 s22, s20, 0xfffc0080
	s_addc_u32 s23, s21, -1
	s_cmp_eq_u32 s45, 12
	s_cselect_b32 s25, s13, s23
	s_cselect_b32 s24, s41, s22
	s_cselect_b32 s23, s11, s44
	s_cselect_b32 s22, s42, s43
	ds_read_b128 v[166:169], v177
	ds_read_b128 v[170:173], v177 offset:1024
	ds_read_b128 v[180:183], v177 offset:2048
	ds_read_b128 v[184:187], v177 offset:3072
	ds_read_b128 v[188:191], v177 offset:4096
	ds_read_b128 v[192:195], v177 offset:5120
	ds_read_b128 v[196:199], v177 offset:6144
	ds_read_b128 v[200:203], v177 offset:7168
	s_waitcnt lgkmcnt(8)
	s_barrier
	s_waitcnt lgkmcnt(0)
	s_setprio 1
	s_waitcnt lgkmcnt(0)
	v_mfma_f32_16x16x32_bf16 v[124:127], v[146:149], v[166:169], 0
	v_mfma_f32_16x16x32_bf16 v[120:123], v[158:161], v[166:169], 0
	v_mfma_f32_16x16x32_bf16 v[108:111], v[146:149], v[180:183], 0
	v_mfma_f32_16x16x32_bf16 v[104:107], v[158:161], v[180:183], 0
	v_mfma_f32_16x16x32_bf16 v[92:95], v[146:149], v[188:191], 0
	v_mfma_f32_16x16x32_bf16 v[88:91], v[158:161], v[188:191], 0
	v_mfma_f32_16x16x32_bf16 v[76:79], v[146:149], v[196:199], 0
	v_mfma_f32_16x16x32_bf16 v[72:75], v[158:161], v[196:199], 0
	v_mfma_f32_16x16x32_bf16 v[124:127], v[154:157], v[170:173], v[124:127]
	v_mfma_f32_16x16x32_bf16 v[120:123], v[162:165], v[170:173], v[120:123]
	v_mfma_f32_16x16x32_bf16 v[108:111], v[154:157], v[184:187], v[108:111]
	v_mfma_f32_16x16x32_bf16 v[104:107], v[162:165], v[184:187], v[104:107]
	v_mfma_f32_16x16x32_bf16 v[92:95], v[154:157], v[192:195], v[92:95]
	v_mfma_f32_16x16x32_bf16 v[88:91], v[162:165], v[192:195], v[88:91]
	v_mfma_f32_16x16x32_bf16 v[76:79], v[154:157], v[200:203], v[76:79]
	v_mfma_f32_16x16x32_bf16 v[72:75], v[162:165], v[200:203], v[72:75]
	s_setprio 0
	s_barrier
	s_add_i32 s46, s37, s28
	v_lshl_add_u64 v[150:151], s[22:23], 0, v[130:131]
	s_mov_b32 m0, s46
	ds_read_b128 v[204:207], v178
	ds_read_b128 v[208:211], v178 offset:1024
	ds_read_b128 v[212:215], v178 offset:2048
	ds_read_b128 v[216:219], v178 offset:3072
	global_load_lds_dwordx4 v[150:151], off
	v_lshl_add_u64 v[220:221], s[22:23], 0, v[134:135]
	s_add_i32 m0, s46, 0x2000
	s_nop 0
	global_load_lds_dwordx4 v[220:221], off
	s_barrier
	s_waitcnt lgkmcnt(0)
	s_setprio 1
	s_waitcnt lgkmcnt(0)
	v_mfma_f32_16x16x32_bf16 v[116:119], v[204:207], v[166:169], 0
	v_mfma_f32_16x16x32_bf16 v[112:115], v[212:215], v[166:169], 0
	v_mfma_f32_16x16x32_bf16 v[100:103], v[204:207], v[180:183], 0
	v_mfma_f32_16x16x32_bf16 v[96:99], v[212:215], v[180:183], 0
	v_mfma_f32_16x16x32_bf16 v[84:87], v[204:207], v[188:191], 0
	v_mfma_f32_16x16x32_bf16 v[80:83], v[212:215], v[188:191], 0
	v_mfma_f32_16x16x32_bf16 v[68:71], v[204:207], v[196:199], 0
	v_mfma_f32_16x16x32_bf16 v[64:67], v[212:215], v[196:199], 0
	v_mfma_f32_16x16x32_bf16 v[116:119], v[208:211], v[170:173], v[116:119]
	v_mfma_f32_16x16x32_bf16 v[112:115], v[216:219], v[170:173], v[112:115]
	v_mfma_f32_16x16x32_bf16 v[100:103], v[208:211], v[184:187], v[100:103]
	v_mfma_f32_16x16x32_bf16 v[96:99], v[216:219], v[184:187], v[96:99]
	v_mfma_f32_16x16x32_bf16 v[84:87], v[208:211], v[192:195], v[84:87]
	v_mfma_f32_16x16x32_bf16 v[80:83], v[216:219], v[192:195], v[80:83]
	v_mfma_f32_16x16x32_bf16 v[68:71], v[208:211], v[200:203], v[68:71]
	v_mfma_f32_16x16x32_bf16 v[64:67], v[216:219], v[200:203], v[64:67]
	s_setprio 0
	s_mov_b32 m0, s19
	v_lshl_add_u64 v[222:223], s[24:25], 0, v[128:129]
	s_barrier
	ds_read_b128 v[166:169], v177 offset:16384
	ds_read_b128 v[170:173], v177 offset:17408
	ds_read_b128 v[180:183], v177 offset:18432
	ds_read_b128 v[184:187], v177 offset:19456
	ds_read_b128 v[188:191], v177 offset:20480
	ds_read_b128 v[192:195], v177 offset:21504
	ds_read_b128 v[196:199], v177 offset:22528
	ds_read_b128 v[200:203], v177 offset:23552
	global_load_lds_dwordx4 v[222:223], off
	v_lshl_add_u64 v[224:225], s[24:25], 0, v[132:133]
	s_mov_b32 m0, s29
	s_nop 0
	global_load_lds_dwordx4 v[224:225], off
	s_barrier
	s_waitcnt lgkmcnt(0)
	s_setprio 1
	s_waitcnt lgkmcnt(0)
	v_mfma_f32_16x16x32_bf16 v[60:63], v[146:149], v[166:169], 0
	v_mfma_f32_16x16x32_bf16 v[56:59], v[158:161], v[166:169], 0
	v_mfma_f32_16x16x32_bf16 v[44:47], v[146:149], v[180:183], 0
	v_mfma_f32_16x16x32_bf16 v[40:43], v[158:161], v[180:183], 0
	v_mfma_f32_16x16x32_bf16 v[28:31], v[146:149], v[188:191], 0
	v_mfma_f32_16x16x32_bf16 v[24:27], v[158:161], v[188:191], 0
	v_mfma_f32_16x16x32_bf16 v[12:15], v[146:149], v[196:199], 0
	v_mfma_f32_16x16x32_bf16 v[8:11], v[158:161], v[196:199], 0
	v_mfma_f32_16x16x32_bf16 v[60:63], v[154:157], v[170:173], v[60:63]
	v_mfma_f32_16x16x32_bf16 v[56:59], v[162:165], v[170:173], v[56:59]
	v_mfma_f32_16x16x32_bf16 v[44:47], v[154:157], v[184:187], v[44:47]
	v_mfma_f32_16x16x32_bf16 v[40:43], v[162:165], v[184:187], v[40:43]
	v_mfma_f32_16x16x32_bf16 v[28:31], v[154:157], v[192:195], v[28:31]
	v_mfma_f32_16x16x32_bf16 v[24:27], v[162:165], v[192:195], v[24:27]
	v_mfma_f32_16x16x32_bf16 v[12:15], v[154:157], v[200:203], v[12:15]
	v_mfma_f32_16x16x32_bf16 v[8:11], v[162:165], v[200:203], v[8:11]
	s_setprio 0
	s_barrier
; #define PG8_STAGE(bufoff, gbase, voff) do { _Pragma("unroll") for (int _i = 0; _i < 2; ++_i) \
;         __builtin_amdgcn_global_load_lds((const unsigned*)((const char*)(gbase) + (voff)[_i]), (LAS unsigned*)(lds + (bufoff) + ldsw + _i * 8192), 16, 0, 0); } while (0)
; #define PG8_LDA(dst, b, h) do { _Pragma("unroll") for (int m = 0; m < 4; ++m) _Pragma("unroll") for (int k = 0; k < 2; ++k) dst[m][k] = *(const LAS bf16x8*)(lds + PG8_SA(b, h) + aoff + m * 2048 + k * 1024); } while (0)
; #define PG8_LDB(dst, b, h) do { _Pragma("unroll") for (int n = 0; n < 2; ++n) _Pragma("unroll") for (int k = 0; k < 2; ++k) dst[n][k] = *(const LAS bf16x8*)(lds + PG8_SB(b, h) + boff + n * 2048 + k * 1024); } while (0)
; #define PG8_MMA(ai, bj, At, Bt) do { __builtin_amdgcn_s_setprio(1); _Pragma("unroll") for (int m = 0; m < 4; ++m) _Pragma("unroll") for (int n = 0; n < 2; ++n) _Pragma("unroll") for (int k = 0; k < 2; ++k) \
;         acc[ai][bj][m][n] = __builtin_amdgcn_mfma_f32_16x16x32_bf16(Bt[n][k], At[m][k], acc[ai][bj][m][n], 0, 0, 0); __builtin_amdgcn_s_setprio(0); } while (0)
; #define PG8_WAIT_V(n) asm volatile("s_waitcnt vmcnt(" #n ")" ::: "memory")
; #define PG8_WAIT_L(n) asm volatile("s_waitcnt lgkmcnt(" #n ")" ::: "memory")
; #define PG8_BAR __builtin_amdgcn_s_barrier()
; #define PG8_SCHED __builtin_amdgcn_sched_barrier(0)
; template <class Epi>
; __device__ __forceinline__ void gemm_phase(LAS unsigned char* lds, const Gemm g, const StaticOrder& S, const Epi& E) {
;     ...
;             PG8_BAR; PG8_WAIT_L(0); PG8_MMA(1, 0, At, B0); PG8_BAR; PG8_SCHED;
;             PG8_STAGE(PG8_SB(0, 1), b2 + hstepB, voffB);
;             PG8_WAIT_V(6); PG8_BAR; PG8_MMA(1, 1, At, B1); PG8_BAR;
;             PG8_LDB(B0, 1, 0); PG8_SCHED; PG8_LDA(At, 1, 0); PG8_STAGE(PG8_SA(0, 1), a2 + hstepA, voffA);
;             PG8_WAIT_L(8); PG8_BAR; PG8_WAIT_L(0); PG8_MMA(0, 0, At, B0); PG8_BAR; PG8_SCHED;
;             PG8_LDB(B1, 1, 1); PG8_STAGE(PG8_SB(1, 0), b3, voffB);
;             PG8_BAR; PG8_WAIT_L(0); PG8_MMA(0, 1, At, B1); PG8_BAR;
;             PG8_LDA(At, 1, 1); PG8_STAGE(PG8_SA(1, 0), a3, voffA);
;             PG8_BAR; PG8_WAIT_L(0); PG8_MMA(1, 0, At, B0); PG8_BAR; PG8_SCHED;
	s_add_u32 s46, s22, 0x40000
	s_addc_u32 s47, s23, 0
	s_add_i32 s48, s38, s28
	v_lshl_add_u64 v[146:147], s[46:47], 0, v[130:131]
	s_mov_b32 m0, s48
	s_nop 0
	global_load_lds_dwordx4 v[146:147], off
	v_lshl_add_u64 v[146:147], s[46:47], 0, v[134:135]
	s_add_i32 m0, s48, 0x2000
	s_nop 0
	global_load_lds_dwordx4 v[146:147], off
	s_waitcnt vmcnt(22)
	s_barrier
	s_setprio 1
	v_mfma_f32_16x16x32_bf16 v[52:55], v[204:207], v[166:169], 0
	v_mfma_f32_16x16x32_bf16 v[48:51], v[212:215], v[166:169], 0
	v_mfma_f32_16x16x32_bf16 v[36:39], v[204:207], v[180:183], 0
	v_mfma_f32_16x16x32_bf16 v[32:35], v[212:215], v[180:183], 0
	v_mfma_f32_16x16x32_bf16 v[20:23], v[204:207], v[188:191], 0
	v_mfma_f32_16x16x32_bf16 v[16:19], v[212:215], v[188:191], 0
	v_mfma_f32_16x16x32_bf16 v[4:7], v[204:207], v[196:199], 0
	v_mfma_f32_16x16x32_bf16 v[0:3], v[212:215], v[196:199], 0
	v_mfma_f32_16x16x32_bf16 v[52:55], v[208:211], v[170:173], v[52:55]
	v_mfma_f32_16x16x32_bf16 v[48:51], v[216:219], v[170:173], v[48:51]
	v_mfma_f32_16x16x32_bf16 v[36:39], v[208:211], v[184:187], v[36:39]
	v_mfma_f32_16x16x32_bf16 v[32:35], v[216:219], v[184:187], v[32:35]
	v_mfma_f32_16x16x32_bf16 v[20:23], v[208:211], v[192:195], v[20:23]
	v_mfma_f32_16x16x32_bf16 v[16:19], v[216:219], v[192:195], v[16:19]
	v_mfma_f32_16x16x32_bf16 v[4:7], v[208:211], v[200:203], v[4:7]
	v_mfma_f32_16x16x32_bf16 v[0:3], v[216:219], v[200:203], v[0:3]
	s_setprio 0
	s_add_i32 s46, 0, 0x18000
	v_add_u32_e32 v162, s46, v174
	s_barrier
	ds_read_b128 v[146:149], v162
	ds_read_b128 v[154:157], v162 offset:1024
	ds_read_b128 v[158:161], v162 offset:2048
	ds_read_b128 v[162:165], v162 offset:3072
	s_add_u32 s24, s24, 0x40000
	s_addc_u32 s25, s25, 0
	s_mov_b32 m0, s30
	v_lshl_add_u64 v[204:205], s[24:25], 0, v[128:129]
	ds_read_b128 v[166:169], v177 offset:32768
	ds_read_b128 v[170:173], v177 offset:33792
	ds_read_b128 v[180:183], v177 offset:34816
	ds_read_b128 v[184:187], v177 offset:35840
	ds_read_b128 v[188:191], v177 offset:36864
	ds_read_b128 v[192:195], v177 offset:37888
	ds_read_b128 v[196:199], v177 offset:38912
	ds_read_b128 v[200:203], v177 offset:39936
	global_load_lds_dwordx4 v[204:205], off
	v_lshl_add_u64 v[204:205], s[24:25], 0, v[132:133]
	s_mov_b32 m0, s31
	s_nop 0
	global_load_lds_dwordx4 v[204:205], off
	s_waitcnt lgkmcnt(8)
	s_barrier
	s_waitcnt lgkmcnt(0)
	s_setprio 1
	s_waitcnt lgkmcnt(0)
	v_mfma_f32_16x16x32_bf16 v[124:127], v[146:149], v[166:169], v[124:127]
	v_mfma_f32_16x16x32_bf16 v[120:123], v[158:161], v[166:169], v[120:123]
	v_mfma_f32_16x16x32_bf16 v[108:111], v[146:149], v[180:183], v[108:111]
	v_mfma_f32_16x16x32_bf16 v[104:107], v[158:161], v[180:183], v[104:107]
	v_mfma_f32_16x16x32_bf16 v[92:95], v[146:149], v[188:191], v[92:95]
	v_mfma_f32_16x16x32_bf16 v[88:91], v[158:161], v[188:191], v[88:91]
	v_mfma_f32_16x16x32_bf16 v[76:79], v[146:149], v[196:199], v[76:79]
	v_mfma_f32_16x16x32_bf16 v[72:75], v[158:161], v[196:199], v[72:75]
	v_mfma_f32_16x16x32_bf16 v[124:127], v[154:157], v[170:173], v[124:127]
	v_mfma_f32_16x16x32_bf16 v[120:123], v[162:165], v[170:173], v[120:123]
	v_mfma_f32_16x16x32_bf16 v[108:111], v[154:157], v[184:187], v[108:111]
	v_mfma_f32_16x16x32_bf16 v[104:107], v[162:165], v[184:187], v[104:107]
	v_mfma_f32_16x16x32_bf16 v[92:95], v[154:157], v[192:195], v[92:95]
	v_mfma_f32_16x16x32_bf16 v[88:91], v[162:165], v[192:195], v[88:91]
	v_mfma_f32_16x16x32_bf16 v[76:79], v[154:157], v[200:203], v[76:79]
	v_mfma_f32_16x16x32_bf16 v[72:75], v[162:165], v[200:203], v[72:75]
	s_setprio 0
	s_barrier
	s_add_i32 s24, 0, 0x1c000
	s_add_i32 s25, s46, s28
	v_add_u32_e32 v216, s24, v174
	v_lshl_add_u64 v[150:151], v[150:151], 0, s[4:5]
	s_mov_b32 m0, s25
	ds_read_b128 v[204:207], v216
	ds_read_b128 v[208:211], v216 offset:1024
	ds_read_b128 v[212:215], v216 offset:2048
	ds_read_b128 v[216:219], v216 offset:3072
	global_load_lds_dwordx4 v[150:151], off
	v_lshl_add_u64 v[150:151], v[220:221], 0, s[4:5]
	s_add_i32 m0, s25, 0x2000
	s_nop 0
	global_load_lds_dwordx4 v[150:151], off
	s_barrier
	s_waitcnt lgkmcnt(0)
	s_setprio 1
	s_waitcnt lgkmcnt(0)
	v_mfma_f32_16x16x32_bf16 v[116:119], v[204:207], v[166:169], v[116:119]
	v_mfma_f32_16x16x32_bf16 v[112:115], v[212:215], v[166:169], v[112:115]
	v_mfma_f32_16x16x32_bf16 v[100:103], v[204:207], v[180:183], v[100:103]
	v_mfma_f32_16x16x32_bf16 v[96:99], v[212:215], v[180:183], v[96:99]
	v_mfma_f32_16x16x32_bf16 v[84:87], v[204:207], v[188:191], v[84:87]
	v_mfma_f32_16x16x32_bf16 v[80:83], v[212:215], v[188:191], v[80:83]
	v_mfma_f32_16x16x32_bf16 v[68:71], v[204:207], v[196:199], v[68:71]
	v_mfma_f32_16x16x32_bf16 v[64:67], v[212:215], v[196:199], v[64:67]
	v_mfma_f32_16x16x32_bf16 v[116:119], v[208:211], v[170:173], v[116:119]
	v_mfma_f32_16x16x32_bf16 v[112:115], v[216:219], v[170:173], v[112:115]
	v_mfma_f32_16x16x32_bf16 v[100:103], v[208:211], v[184:187], v[100:103]
	v_mfma_f32_16x16x32_bf16 v[96:99], v[216:219], v[184:187], v[96:99]
	v_mfma_f32_16x16x32_bf16 v[84:87], v[208:211], v[192:195], v[84:87]
	v_mfma_f32_16x16x32_bf16 v[80:83], v[216:219], v[192:195], v[80:83]
	v_mfma_f32_16x16x32_bf16 v[68:71], v[208:211], v[200:203], v[68:71]
	v_mfma_f32_16x16x32_bf16 v[64:67], v[216:219], v[200:203], v[64:67]
	s_setprio 0
	s_mov_b32 m0, s34
	v_lshl_add_u64 v[150:151], v[222:223], 0, s[4:5]
	s_barrier
	ds_read_b128 v[166:169], v177 offset:49152
	ds_read_b128 v[170:173], v177 offset:50176
	ds_read_b128 v[180:183], v177 offset:51200
	ds_read_b128 v[184:187], v177 offset:52224
	ds_read_b128 v[188:191], v177 offset:53248
	ds_read_b128 v[192:195], v177 offset:54272
	ds_read_b128 v[196:199], v177 offset:55296
	ds_read_b128 v[200:203], v177 offset:56320
	global_load_lds_dwordx4 v[150:151], off
	v_lshl_add_u64 v[150:151], v[224:225], 0, s[4:5]
	s_mov_b32 m0, s35
	s_nop 0
	global_load_lds_dwordx4 v[150:151], off
	s_barrier
; #define PG8_STAGE(bufoff, gbase, voff) do { _Pragma("unroll") for (int _i = 0; _i < 2; ++_i) \
;         __builtin_amdgcn_global_load_lds((const unsigned*)((const char*)(gbase) + (voff)[_i]), (LAS unsigned*)(lds + (bufoff) + ldsw + _i * 8192), 16, 0, 0); } while (0)
; #define PG8_LDA(dst, b, h) do { _Pragma("unroll") for (int m = 0; m < 4; ++m) _Pragma("unroll") for (int k = 0; k < 2; ++k) dst[m][k] = *(const LAS bf16x8*)(lds + PG8_SA(b, h) + aoff + m * 2048 + k * 1024); } while (0)
; #define PG8_LDB(dst, b, h) do { _Pragma("unroll") for (int n = 0; n < 2; ++n) _Pragma("unroll") for (int k = 0; k < 2; ++k) dst[n][k] = *(const LAS bf16x8*)(lds + PG8_SB(b, h) + boff + n * 2048 + k * 1024); } while (0)
; #define PG8_WAIT_V(n) asm volatile("s_waitcnt vmcnt(" #n ")" ::: "memory")
; #define PG8_WAIT_L(n) asm volatile("s_waitcnt lgkmcnt(" #n ")" ::: "memory")
; #define PG8_BAR __builtin_amdgcn_s_barrier()
; #define PG8_SCHED __builtin_amdgcn_sched_barrier(0)
; template <class Epi>
; __device__ __forceinline__ void gemm_phase(LAS unsigned char* lds, const Gemm g, const StaticOrder& S, const Epi& E) {
;     ...
;             PG8_LDB(B0, 0, 0); PG8_SCHED; PG8_LDA(At, 0, 0); PG8_STAGE(PG8_SA(1, 1), a1 + hstepA, voffA);
;             PG8_WAIT_L(8); PG8_BAR; PG8_WAIT_L(0); PG8_MMA(0, 0, At, B0); PG8_BAR; PG8_SCHED;
;             PG8_LDB(B1, 0, 1); PG8_STAGE(PG8_SB(0, 0), b2, voffB);
;             PG8_BAR; PG8_WAIT_L(0); PG8_MMA(0, 1, At, B1); PG8_BAR;
;             PG8_LDA(At, 0, 1); PG8_STAGE(PG8_SA(0, 0), a2, voffA);
;             PG8_BAR; PG8_WAIT_L(0); PG8_MMA(1, 0, At, B0); PG8_BAR; PG8_SCHED;
;             PG8_STAGE(PG8_SB(0, 1), b2 + hstepB, voffB);
;             PG8_WAIT_V(6); PG8_BAR; PG8_MMA(1, 1, At, B1); PG8_BAR;
;             PG8_LDB(B0, 1, 0); PG8_SCHED; PG8_LDA(At, 1, 0); PG8_STAGE(PG8_SA(0, 1), a2 + hstepA, voffA);
;             PG8_WAIT_L(8); PG8_BAR; PG8_WAIT_L(0); PG8_MMA(0, 0, At, B0); PG8_BAR; PG8_SCHED;
;             PG8_LDB(B1, 1, 1); PG8_STAGE(PG8_SB(1, 0), b3, voffB);
;             PG8_BAR; PG8_WAIT_L(0); PG8_MMA(0, 1, At, B1); PG8_BAR;
;             PG8_LDA(At, 1, 1); PG8_STAGE(PG8_SA(1, 0), a3, voffA);
;             PG8_BAR; PG8_WAIT_L(0); PG8_MMA(1, 0, At, B0); PG8_BAR; PG8_SCHED;
;             PG8_STAGE(PG8_SB(1, 1), b3 + hstepB, voffB);
;             PG8_WAIT_V(6); PG8_BAR; PG8_MMA(1, 1, At, B1); PG8_BAR;
	s_waitcnt lgkmcnt(0)
	s_setprio 1
	s_waitcnt lgkmcnt(0)
	v_mfma_f32_16x16x32_bf16 v[60:63], v[146:149], v[166:169], v[60:63]
	v_mfma_f32_16x16x32_bf16 v[56:59], v[158:161], v[166:169], v[56:59]
	v_mfma_f32_16x16x32_bf16 v[44:47], v[146:149], v[180:183], v[44:47]
	v_mfma_f32_16x16x32_bf16 v[40:43], v[158:161], v[180:183], v[40:43]
	v_mfma_f32_16x16x32_bf16 v[28:31], v[146:149], v[188:191], v[28:31]
	v_mfma_f32_16x16x32_bf16 v[24:27], v[158:161], v[188:191], v[24:27]
	v_mfma_f32_16x16x32_bf16 v[12:15], v[146:149], v[196:199], v[12:15]
	v_mfma_f32_16x16x32_bf16 v[8:11], v[158:161], v[196:199], v[8:11]
	v_mfma_f32_16x16x32_bf16 v[60:63], v[154:157], v[170:173], v[60:63]
	v_mfma_f32_16x16x32_bf16 v[56:59], v[162:165], v[170:173], v[56:59]
	v_mfma_f32_16x16x32_bf16 v[44:47], v[154:157], v[184:187], v[44:47]
	v_mfma_f32_16x16x32_bf16 v[40:43], v[162:165], v[184:187], v[40:43]
	v_mfma_f32_16x16x32_bf16 v[28:31], v[154:157], v[192:195], v[28:31]
	v_mfma_f32_16x16x32_bf16 v[24:27], v[162:165], v[192:195], v[24:27]
	v_mfma_f32_16x16x32_bf16 v[12:15], v[154:157], v[200:203], v[12:15]
	v_mfma_f32_16x16x32_bf16 v[8:11], v[162:165], v[200:203], v[8:11]
	s_setprio 0
	s_barrier
	s_add_u32 s22, s22, 0x40080
	s_addc_u32 s23, s23, 0
	s_add_i32 s24, s24, s28
	v_lshl_add_u64 v[146:147], s[22:23], 0, v[130:131]
	s_mov_b32 m0, s24
	s_nop 0
	global_load_lds_dwordx4 v[146:147], off
	v_lshl_add_u64 v[146:147], s[22:23], 0, v[134:135]
	s_add_i32 m0, s24, 0x2000
	s_nop 0
	global_load_lds_dwordx4 v[146:147], off
	s_waitcnt vmcnt(6)
	s_barrier
	s_setprio 1
	v_mfma_f32_16x16x32_bf16 v[52:55], v[204:207], v[166:169], v[52:55]
	v_mfma_f32_16x16x32_bf16 v[48:51], v[212:215], v[166:169], v[48:51]
	v_mfma_f32_16x16x32_bf16 v[36:39], v[204:207], v[180:183], v[36:39]
	v_mfma_f32_16x16x32_bf16 v[32:35], v[212:215], v[180:183], v[32:35]
	v_mfma_f32_16x16x32_bf16 v[20:23], v[204:207], v[188:191], v[20:23]
	v_mfma_f32_16x16x32_bf16 v[16:19], v[212:215], v[188:191], v[16:19]
	v_mfma_f32_16x16x32_bf16 v[4:7], v[204:207], v[196:199], v[4:7]
	v_mfma_f32_16x16x32_bf16 v[0:3], v[212:215], v[196:199], v[0:3]
	v_mfma_f32_16x16x32_bf16 v[52:55], v[208:211], v[170:173], v[52:55]
	v_mfma_f32_16x16x32_bf16 v[48:51], v[216:219], v[170:173], v[48:51]
	v_mfma_f32_16x16x32_bf16 v[36:39], v[208:211], v[184:187], v[36:39]
	v_mfma_f32_16x16x32_bf16 v[32:35], v[216:219], v[184:187], v[32:35]
	v_mfma_f32_16x16x32_bf16 v[20:23], v[208:211], v[192:195], v[20:23]
	v_mfma_f32_16x16x32_bf16 v[16:19], v[216:219], v[192:195], v[16:19]
	v_mfma_f32_16x16x32_bf16 v[4:7], v[208:211], v[200:203], v[4:7]
	v_mfma_f32_16x16x32_bf16 v[0:3], v[216:219], v[200:203], v[0:3]
	s_setprio 0
	s_add_i32 s45, s45, 2
	s_add_u32 s20, s20, 0x100
	s_addc_u32 s21, s21, 0
	s_add_u32 s43, s43, 0x100
	s_addc_u32 s44, s44, 0
	s_cmp_gt_u32 s45, 13
	s_barrier
.LBB0_1204:
	ds_read_b128 v[146:149], v176
	ds_read_b128 v[154:157], v176 offset:1024
	ds_read_b128 v[158:161], v176 offset:2048
	ds_read_b128 v[162:165], v176 offset:3072
	s_add_u32 s22, s20, 0xfffc0080
	s_addc_u32 s23, s21, -1
	s_cmp_eq_u32 s45, 12
	s_cselect_b32 s25, s13, s23
	s_cselect_b32 s24, s41, s22
	s_cselect_b32 s23, s11, s44
	s_cselect_b32 s22, s42, s43
	v_lshl_add_u64 v[150:151], s[20:21], 0, v[138:139]
	s_add_i32 m0, s19, 0xc000
	ds_read_b128 v[166:169], v177
	ds_read_b128 v[170:173], v177 offset:1024
	ds_read_b128 v[180:183], v177 offset:2048
	ds_read_b128 v[184:187], v177 offset:3072
	ds_read_b128 v[188:191], v177 offset:4096
	ds_read_b128 v[192:195], v177 offset:5120
	ds_read_b128 v[196:199], v177 offset:6144
	ds_read_b128 v[200:203], v177 offset:7168
	global_load_lds_dwordx4 v[150:151], off
	v_lshl_add_u64 v[150:151], s[20:21], 0, v[140:141]
	s_add_i32 m0, s19, 0xe000
	s_nop 0
	global_load_lds_dwordx4 v[150:151], off
	s_waitcnt lgkmcnt(8)
	s_barrier
	s_waitcnt lgkmcnt(0)
	s_setprio 1
	s_waitcnt lgkmcnt(0)
	v_mfma_f32_16x16x32_bf16 v[124:127], v[146:149], v[166:169], v[124:127]
	v_mfma_f32_16x16x32_bf16 v[120:123], v[158:161], v[166:169], v[120:123]
	v_mfma_f32_16x16x32_bf16 v[108:111], v[146:149], v[180:183], v[108:111]
	v_mfma_f32_16x16x32_bf16 v[104:107], v[158:161], v[180:183], v[104:107]
	v_mfma_f32_16x16x32_bf16 v[92:95], v[146:149], v[188:191], v[92:95]
	v_mfma_f32_16x16x32_bf16 v[88:91], v[158:161], v[188:191], v[88:91]
	v_mfma_f32_16x16x32_bf16 v[76:79], v[146:149], v[196:199], v[76:79]
	v_mfma_f32_16x16x32_bf16 v[72:75], v[158:161], v[196:199], v[72:75]
	v_mfma_f32_16x16x32_bf16 v[124:127], v[154:157], v[170:173], v[124:127]
	v_mfma_f32_16x16x32_bf16 v[120:123], v[162:165], v[170:173], v[120:123]
	v_mfma_f32_16x16x32_bf16 v[108:111], v[154:157], v[184:187], v[108:111]
	v_mfma_f32_16x16x32_bf16 v[104:107], v[162:165], v[184:187], v[104:107]
	v_mfma_f32_16x16x32_bf16 v[92:95], v[154:157], v[192:195], v[92:95]
	v_mfma_f32_16x16x32_bf16 v[88:91], v[162:165], v[192:195], v[88:91]
	v_mfma_f32_16x16x32_bf16 v[76:79], v[154:157], v[200:203], v[76:79]
	v_mfma_f32_16x16x32_bf16 v[72:75], v[162:165], v[200:203], v[72:75]
	s_setprio 0
	s_barrier
	s_add_i32 s46, s37, s28
	v_lshl_add_u64 v[150:151], s[22:23], 0, v[130:131]
	s_mov_b32 m0, s46
	ds_read_b128 v[204:207], v178
	ds_read_b128 v[208:211], v178 offset:1024
	ds_read_b128 v[212:215], v178 offset:2048
	ds_read_b128 v[216:219], v178 offset:3072
	global_load_lds_dwordx4 v[150:151], off
	v_lshl_add_u64 v[220:221], s[22:23], 0, v[134:135]
	s_add_i32 m0, s46, 0x2000
	s_nop 0
	global_load_lds_dwordx4 v[220:221], off
	s_barrier
; #define PG8_STAGE(bufoff, gbase, voff) do { _Pragma("unroll") for (int _i = 0; _i < 2; ++_i) \
;         __builtin_amdgcn_global_load_lds((const unsigned*)((const char*)(gbase) + (voff)[_i]), (LAS unsigned*)(lds + (bufoff) + ldsw + _i * 8192), 16, 0, 0); } while (0)
; #define PG8_LDA(dst, b, h) do { _Pragma("unroll") for (int m = 0; m < 4; ++m) _Pragma("unroll") for (int k = 0; k < 2; ++k) dst[m][k] = *(const LAS bf16x8*)(lds + PG8_SA(b, h) + aoff + m * 2048 + k * 1024); } while (0)
; #define PG8_LDB(dst, b, h) do { _Pragma("unroll") for (int n = 0; n < 2; ++n) _Pragma("unroll") for (int k = 0; k < 2; ++k) dst[n][k] = *(const LAS bf16x8*)(lds + PG8_SB(b, h) + boff + n * 2048 + k * 1024); } while (0)
; #define PG8_MMA(ai, bj, At, Bt) do { __builtin_amdgcn_s_setprio(1); _Pragma("unroll") for (int m = 0; m < 4; ++m) _Pragma("unroll") for (int n = 0; n < 2; ++n) _Pragma("unroll") for (int k = 0; k < 2; ++k) \
;         acc[ai][bj][m][n] = __builtin_amdgcn_mfma_f32_16x16x32_bf16(Bt[n][k], At[m][k], acc[ai][bj][m][n], 0, 0, 0); __builtin_amdgcn_s_setprio(0); } while (0)
; #define PG8_WAIT_V(n) asm volatile("s_waitcnt vmcnt(" #n ")" ::: "memory")
; #define PG8_WAIT_L(n) asm volatile("s_waitcnt lgkmcnt(" #n ")" ::: "memory")
; #define PG8_BAR __builtin_amdgcn_s_barrier()
; #define PG8_SCHED __builtin_amdgcn_sched_barrier(0)
; template <class Epi>
; __device__ __forceinline__ void gemm_phase(LAS unsigned char* lds, const Gemm g, const StaticOrder& S, const Epi& E) {
;     ...
;             PG8_BAR; PG8_WAIT_L(0); PG8_MMA(0, 1, At, B1); PG8_BAR;
;             PG8_LDA(At, 0, 1); PG8_STAGE(PG8_SA(0, 0), a2, voffA);
;             PG8_BAR; PG8_WAIT_L(0); PG8_MMA(1, 0, At, B0); PG8_BAR; PG8_SCHED;
;             PG8_STAGE(PG8_SB(0, 1), b2 + hstepB, voffB);
;             PG8_WAIT_V(6); PG8_BAR; PG8_MMA(1, 1, At, B1); PG8_BAR;
;             PG8_LDB(B0, 1, 0); PG8_SCHED; PG8_LDA(At, 1, 0); PG8_STAGE(PG8_SA(0, 1), a2 + hstepA, voffA);
;             PG8_WAIT_L(8); PG8_BAR; PG8_WAIT_L(0); PG8_MMA(0, 0, At, B0); PG8_BAR; PG8_SCHED;
;             PG8_LDB(B1, 1, 1); PG8_STAGE(PG8_SB(1, 0), b3, voffB);
;             PG8_BAR; PG8_WAIT_L(0); PG8_MMA(0, 1, At, B1); PG8_BAR;
;             PG8_LDA(At, 1, 1); PG8_STAGE(PG8_SA(1, 0), a3, voffA);
	s_waitcnt lgkmcnt(0)
	s_setprio 1
	s_waitcnt lgkmcnt(0)
	v_mfma_f32_16x16x32_bf16 v[116:119], v[204:207], v[166:169], v[116:119]
	v_mfma_f32_16x16x32_bf16 v[112:115], v[212:215], v[166:169], v[112:115]
	v_mfma_f32_16x16x32_bf16 v[100:103], v[204:207], v[180:183], v[100:103]
	v_mfma_f32_16x16x32_bf16 v[96:99], v[212:215], v[180:183], v[96:99]
	v_mfma_f32_16x16x32_bf16 v[84:87], v[204:207], v[188:191], v[84:87]
	v_mfma_f32_16x16x32_bf16 v[80:83], v[212:215], v[188:191], v[80:83]
	v_mfma_f32_16x16x32_bf16 v[68:71], v[204:207], v[196:199], v[68:71]
	v_mfma_f32_16x16x32_bf16 v[64:67], v[212:215], v[196:199], v[64:67]
	v_mfma_f32_16x16x32_bf16 v[116:119], v[208:211], v[170:173], v[116:119]
	v_mfma_f32_16x16x32_bf16 v[112:115], v[216:219], v[170:173], v[112:115]
	v_mfma_f32_16x16x32_bf16 v[100:103], v[208:211], v[184:187], v[100:103]
	v_mfma_f32_16x16x32_bf16 v[96:99], v[216:219], v[184:187], v[96:99]
	v_mfma_f32_16x16x32_bf16 v[84:87], v[208:211], v[192:195], v[84:87]
	v_mfma_f32_16x16x32_bf16 v[80:83], v[216:219], v[192:195], v[80:83]
	v_mfma_f32_16x16x32_bf16 v[68:71], v[208:211], v[200:203], v[68:71]
	v_mfma_f32_16x16x32_bf16 v[64:67], v[216:219], v[200:203], v[64:67]
	s_setprio 0
	s_mov_b32 m0, s19
	v_lshl_add_u64 v[222:223], s[24:25], 0, v[128:129]
	s_barrier
	ds_read_b128 v[166:169], v177 offset:16384
	ds_read_b128 v[170:173], v177 offset:17408
	ds_read_b128 v[180:183], v177 offset:18432
	ds_read_b128 v[184:187], v177 offset:19456
	ds_read_b128 v[188:191], v177 offset:20480
	ds_read_b128 v[192:195], v177 offset:21504
	ds_read_b128 v[196:199], v177 offset:22528
	ds_read_b128 v[200:203], v177 offset:23552
	global_load_lds_dwordx4 v[222:223], off
	v_lshl_add_u64 v[224:225], s[24:25], 0, v[132:133]
	s_mov_b32 m0, s29
	s_nop 0
	global_load_lds_dwordx4 v[224:225], off
	s_barrier
	s_waitcnt lgkmcnt(0)
	s_setprio 1
	s_waitcnt lgkmcnt(0)
	v_mfma_f32_16x16x32_bf16 v[60:63], v[146:149], v[166:169], v[60:63]
	v_mfma_f32_16x16x32_bf16 v[56:59], v[158:161], v[166:169], v[56:59]
	v_mfma_f32_16x16x32_bf16 v[44:47], v[146:149], v[180:183], v[44:47]
	v_mfma_f32_16x16x32_bf16 v[40:43], v[158:161], v[180:183], v[40:43]
	v_mfma_f32_16x16x32_bf16 v[28:31], v[146:149], v[188:191], v[28:31]
	v_mfma_f32_16x16x32_bf16 v[24:27], v[158:161], v[188:191], v[24:27]
	v_mfma_f32_16x16x32_bf16 v[12:15], v[146:149], v[196:199], v[12:15]
	v_mfma_f32_16x16x32_bf16 v[8:11], v[158:161], v[196:199], v[8:11]
	v_mfma_f32_16x16x32_bf16 v[60:63], v[154:157], v[170:173], v[60:63]
	v_mfma_f32_16x16x32_bf16 v[56:59], v[162:165], v[170:173], v[56:59]
	v_mfma_f32_16x16x32_bf16 v[44:47], v[154:157], v[184:187], v[44:47]
	v_mfma_f32_16x16x32_bf16 v[40:43], v[162:165], v[184:187], v[40:43]
	v_mfma_f32_16x16x32_bf16 v[28:31], v[154:157], v[192:195], v[28:31]
	v_mfma_f32_16x16x32_bf16 v[24:27], v[162:165], v[192:195], v[24:27]
	v_mfma_f32_16x16x32_bf16 v[12:15], v[154:157], v[200:203], v[12:15]
	v_mfma_f32_16x16x32_bf16 v[8:11], v[162:165], v[200:203], v[8:11]
	s_setprio 0
	s_barrier
	s_add_u32 s46, s22, 0x40000
	s_addc_u32 s47, s23, 0
	s_add_i32 s48, s38, s28
	v_lshl_add_u64 v[146:147], s[46:47], 0, v[130:131]
	s_mov_b32 m0, s48
	s_nop 0
	global_load_lds_dwordx4 v[146:147], off
	v_lshl_add_u64 v[146:147], s[46:47], 0, v[134:135]
	s_add_i32 m0, s48, 0x2000
	s_nop 0
	global_load_lds_dwordx4 v[146:147], off
	s_waitcnt vmcnt(6)
	s_barrier
	s_setprio 1
	v_mfma_f32_16x16x32_bf16 v[52:55], v[204:207], v[166:169], v[52:55]
	v_mfma_f32_16x16x32_bf16 v[48:51], v[212:215], v[166:169], v[48:51]
	v_mfma_f32_16x16x32_bf16 v[36:39], v[204:207], v[180:183], v[36:39]
	v_mfma_f32_16x16x32_bf16 v[32:35], v[212:215], v[180:183], v[32:35]
	v_mfma_f32_16x16x32_bf16 v[20:23], v[204:207], v[188:191], v[20:23]
	v_mfma_f32_16x16x32_bf16 v[16:19], v[212:215], v[188:191], v[16:19]
	v_mfma_f32_16x16x32_bf16 v[4:7], v[204:207], v[196:199], v[4:7]
	v_mfma_f32_16x16x32_bf16 v[0:3], v[212:215], v[196:199], v[0:3]
	v_mfma_f32_16x16x32_bf16 v[52:55], v[208:211], v[170:173], v[52:55]
	v_mfma_f32_16x16x32_bf16 v[48:51], v[216:219], v[170:173], v[48:51]
	v_mfma_f32_16x16x32_bf16 v[36:39], v[208:211], v[184:187], v[36:39]
	v_mfma_f32_16x16x32_bf16 v[32:35], v[216:219], v[184:187], v[32:35]
	v_mfma_f32_16x16x32_bf16 v[20:23], v[208:211], v[192:195], v[20:23]
	v_mfma_f32_16x16x32_bf16 v[16:19], v[216:219], v[192:195], v[16:19]
	v_mfma_f32_16x16x32_bf16 v[4:7], v[208:211], v[200:203], v[4:7]
	v_mfma_f32_16x16x32_bf16 v[0:3], v[216:219], v[200:203], v[0:3]
	s_setprio 0
	s_add_i32 s46, 0, 0x18000
	v_add_u32_e32 v162, s46, v174
	s_barrier
	ds_read_b128 v[146:149], v162
	ds_read_b128 v[154:157], v162 offset:1024
	ds_read_b128 v[158:161], v162 offset:2048
	ds_read_b128 v[162:165], v162 offset:3072
	s_add_u32 s24, s24, 0x40000
	s_addc_u32 s25, s25, 0
	s_mov_b32 m0, s30
	v_lshl_add_u64 v[204:205], s[24:25], 0, v[128:129]
	ds_read_b128 v[166:169], v177 offset:32768
	ds_read_b128 v[170:173], v177 offset:33792
	ds_read_b128 v[180:183], v177 offset:34816
	ds_read_b128 v[184:187], v177 offset:35840
	ds_read_b128 v[188:191], v177 offset:36864
	ds_read_b128 v[192:195], v177 offset:37888
	ds_read_b128 v[196:199], v177 offset:38912
	ds_read_b128 v[200:203], v177 offset:39936
	global_load_lds_dwordx4 v[204:205], off
	v_lshl_add_u64 v[204:205], s[24:25], 0, v[132:133]
	s_mov_b32 m0, s31
	s_nop 0
	global_load_lds_dwordx4 v[204:205], off
	s_waitcnt lgkmcnt(8)
	s_barrier
; #define PG8_STAGE(bufoff, gbase, voff) do { _Pragma("unroll") for (int _i = 0; _i < 2; ++_i) \
;         __builtin_amdgcn_global_load_lds((const unsigned*)((const char*)(gbase) + (voff)[_i]), (LAS unsigned*)(lds + (bufoff) + ldsw + _i * 8192), 16, 0, 0); } while (0)
; #define PG8_LDA(dst, b, h) do { _Pragma("unroll") for (int m = 0; m < 4; ++m) _Pragma("unroll") for (int k = 0; k < 2; ++k) dst[m][k] = *(const LAS bf16x8*)(lds + PG8_SA(b, h) + aoff + m * 2048 + k * 1024); } while (0)
; #define PG8_LDB(dst, b, h) do { _Pragma("unroll") for (int n = 0; n < 2; ++n) _Pragma("unroll") for (int k = 0; k < 2; ++k) dst[n][k] = *(const LAS bf16x8*)(lds + PG8_SB(b, h) + boff + n * 2048 + k * 1024); } while (0)
; #define PG8_MMA(ai, bj, At, Bt) do { __builtin_amdgcn_s_setprio(1); _Pragma("unroll") for (int m = 0; m < 4; ++m) _Pragma("unroll") for (int n = 0; n < 2; ++n) _Pragma("unroll") for (int k = 0; k < 2; ++k) \
;         acc[ai][bj][m][n] = __builtin_amdgcn_mfma_f32_16x16x32_bf16(Bt[n][k], At[m][k], acc[ai][bj][m][n], 0, 0, 0); __builtin_amdgcn_s_setprio(0); } while (0)
; #define PG8_WAIT_V(n) asm volatile("s_waitcnt vmcnt(" #n ")" ::: "memory")
; #define PG8_WAIT_L(n) asm volatile("s_waitcnt lgkmcnt(" #n ")" ::: "memory")
; #define PG8_BAR __builtin_amdgcn_s_barrier()
; #define PG8_SCHED __builtin_amdgcn_sched_barrier(0)
; template <class Epi>
; __device__ __forceinline__ void gemm_phase(LAS unsigned char* lds, const Gemm g, const StaticOrder& S, const Epi& E) {
;     ...
;             PG8_LDB(B0, 1, 0); PG8_SCHED; PG8_LDA(At, 1, 0); PG8_STAGE(PG8_SA(0, 1), a2 + hstepA, voffA);
;             PG8_WAIT_L(8); PG8_BAR; PG8_WAIT_L(0); PG8_MMA(0, 0, At, B0); PG8_BAR; PG8_SCHED;
;             PG8_LDB(B1, 1, 1); PG8_STAGE(PG8_SB(1, 0), b3, voffB);
;             PG8_BAR; PG8_WAIT_L(0); PG8_MMA(0, 1, At, B1); PG8_BAR;
;             PG8_LDA(At, 1, 1); PG8_STAGE(PG8_SA(1, 0), a3, voffA);
;             PG8_BAR; PG8_WAIT_L(0); PG8_MMA(1, 0, At, B0); PG8_BAR; PG8_SCHED;
;             PG8_STAGE(PG8_SB(1, 1), b3 + hstepB, voffB);
;             PG8_WAIT_V(6); PG8_BAR; PG8_MMA(1, 1, At, B1); PG8_BAR;
	s_waitcnt lgkmcnt(0)
	s_setprio 1
	s_waitcnt lgkmcnt(0)
	v_mfma_f32_16x16x32_bf16 v[124:127], v[146:149], v[166:169], v[124:127]
	v_mfma_f32_16x16x32_bf16 v[120:123], v[158:161], v[166:169], v[120:123]
	v_mfma_f32_16x16x32_bf16 v[108:111], v[146:149], v[180:183], v[108:111]
	v_mfma_f32_16x16x32_bf16 v[104:107], v[158:161], v[180:183], v[104:107]
	v_mfma_f32_16x16x32_bf16 v[92:95], v[146:149], v[188:191], v[92:95]
	v_mfma_f32_16x16x32_bf16 v[88:91], v[158:161], v[188:191], v[88:91]
	v_mfma_f32_16x16x32_bf16 v[76:79], v[146:149], v[196:199], v[76:79]
	v_mfma_f32_16x16x32_bf16 v[72:75], v[158:161], v[196:199], v[72:75]
	v_mfma_f32_16x16x32_bf16 v[124:127], v[154:157], v[170:173], v[124:127]
	v_mfma_f32_16x16x32_bf16 v[120:123], v[162:165], v[170:173], v[120:123]
	v_mfma_f32_16x16x32_bf16 v[108:111], v[154:157], v[184:187], v[108:111]
	v_mfma_f32_16x16x32_bf16 v[104:107], v[162:165], v[184:187], v[104:107]
	v_mfma_f32_16x16x32_bf16 v[92:95], v[154:157], v[192:195], v[92:95]
	v_mfma_f32_16x16x32_bf16 v[88:91], v[162:165], v[192:195], v[88:91]
	v_mfma_f32_16x16x32_bf16 v[76:79], v[154:157], v[200:203], v[76:79]
	v_mfma_f32_16x16x32_bf16 v[72:75], v[162:165], v[200:203], v[72:75]
	s_setprio 0
	s_barrier
	s_add_i32 s24, 0, 0x1c000
	s_add_i32 s25, s46, s28
	v_add_u32_e32 v216, s24, v174
	v_lshl_add_u64 v[150:151], v[150:151], 0, s[4:5]
	s_mov_b32 m0, s25
	ds_read_b128 v[204:207], v216
	ds_read_b128 v[208:211], v216 offset:1024
	ds_read_b128 v[212:215], v216 offset:2048
	ds_read_b128 v[216:219], v216 offset:3072
	global_load_lds_dwordx4 v[150:151], off
	v_lshl_add_u64 v[150:151], v[220:221], 0, s[4:5]
	s_add_i32 m0, s25, 0x2000
	s_nop 0
	global_load_lds_dwordx4 v[150:151], off
	s_barrier
	s_waitcnt lgkmcnt(0)
	s_setprio 1
	s_waitcnt lgkmcnt(0)
	v_mfma_f32_16x16x32_bf16 v[116:119], v[204:207], v[166:169], v[116:119]
	v_mfma_f32_16x16x32_bf16 v[112:115], v[212:215], v[166:169], v[112:115]
	v_mfma_f32_16x16x32_bf16 v[100:103], v[204:207], v[180:183], v[100:103]
	v_mfma_f32_16x16x32_bf16 v[96:99], v[212:215], v[180:183], v[96:99]
	v_mfma_f32_16x16x32_bf16 v[84:87], v[204:207], v[188:191], v[84:87]
	v_mfma_f32_16x16x32_bf16 v[80:83], v[212:215], v[188:191], v[80:83]
	v_mfma_f32_16x16x32_bf16 v[68:71], v[204:207], v[196:199], v[68:71]
	v_mfma_f32_16x16x32_bf16 v[64:67], v[212:215], v[196:199], v[64:67]
	v_mfma_f32_16x16x32_bf16 v[116:119], v[208:211], v[170:173], v[116:119]
	v_mfma_f32_16x16x32_bf16 v[112:115], v[216:219], v[170:173], v[112:115]
	v_mfma_f32_16x16x32_bf16 v[100:103], v[208:211], v[184:187], v[100:103]
	v_mfma_f32_16x16x32_bf16 v[96:99], v[216:219], v[184:187], v[96:99]
	v_mfma_f32_16x16x32_bf16 v[84:87], v[208:211], v[192:195], v[84:87]
	v_mfma_f32_16x16x32_bf16 v[80:83], v[216:219], v[192:195], v[80:83]
	v_mfma_f32_16x16x32_bf16 v[68:71], v[208:211], v[200:203], v[68:71]
	v_mfma_f32_16x16x32_bf16 v[64:67], v[216:219], v[200:203], v[64:67]
	s_setprio 0
	s_mov_b32 m0, s34
	v_lshl_add_u64 v[150:151], v[222:223], 0, s[4:5]
	s_barrier
	ds_read_b128 v[166:169], v177 offset:49152
	ds_read_b128 v[170:173], v177 offset:50176
	ds_read_b128 v[180:183], v177 offset:51200
	ds_read_b128 v[184:187], v177 offset:52224
	ds_read_b128 v[188:191], v177 offset:53248
	ds_read_b128 v[192:195], v177 offset:54272
	ds_read_b128 v[196:199], v177 offset:55296
	ds_read_b128 v[200:203], v177 offset:56320
	global_load_lds_dwordx4 v[150:151], off
	v_lshl_add_u64 v[150:151], v[224:225], 0, s[4:5]
	s_mov_b32 m0, s35
	s_nop 0
	global_load_lds_dwordx4 v[150:151], off
	s_barrier
	s_waitcnt lgkmcnt(0)
	s_setprio 1
	s_waitcnt lgkmcnt(0)
	v_mfma_f32_16x16x32_bf16 v[60:63], v[146:149], v[166:169], v[60:63]
	v_mfma_f32_16x16x32_bf16 v[56:59], v[158:161], v[166:169], v[56:59]
	v_mfma_f32_16x16x32_bf16 v[44:47], v[146:149], v[180:183], v[44:47]
	v_mfma_f32_16x16x32_bf16 v[40:43], v[158:161], v[180:183], v[40:43]
	v_mfma_f32_16x16x32_bf16 v[28:31], v[146:149], v[188:191], v[28:31]
	v_mfma_f32_16x16x32_bf16 v[24:27], v[158:161], v[188:191], v[24:27]
	v_mfma_f32_16x16x32_bf16 v[12:15], v[146:149], v[196:199], v[12:15]
	v_mfma_f32_16x16x32_bf16 v[8:11], v[158:161], v[196:199], v[8:11]
	v_mfma_f32_16x16x32_bf16 v[60:63], v[154:157], v[170:173], v[60:63]
	v_mfma_f32_16x16x32_bf16 v[56:59], v[162:165], v[170:173], v[56:59]
	v_mfma_f32_16x16x32_bf16 v[44:47], v[154:157], v[184:187], v[44:47]
	v_mfma_f32_16x16x32_bf16 v[40:43], v[162:165], v[184:187], v[40:43]
	v_mfma_f32_16x16x32_bf16 v[28:31], v[154:157], v[192:195], v[28:31]
	v_mfma_f32_16x16x32_bf16 v[24:27], v[162:165], v[192:195], v[24:27]
	v_mfma_f32_16x16x32_bf16 v[12:15], v[154:157], v[200:203], v[12:15]
	v_mfma_f32_16x16x32_bf16 v[8:11], v[162:165], v[200:203], v[8:11]
	s_setprio 0
	s_barrier
	s_add_u32 s22, s22, 0x40080
	s_addc_u32 s23, s23, 0
	s_add_i32 s24, s24, s28
	v_lshl_add_u64 v[146:147], s[22:23], 0, v[130:131]
	s_mov_b32 m0, s24
	s_nop 0
	global_load_lds_dwordx4 v[146:147], off
	v_lshl_add_u64 v[146:147], s[22:23], 0, v[134:135]
	s_add_i32 m0, s24, 0x2000
	s_nop 0
	global_load_lds_dwordx4 v[146:147], off
	s_waitcnt vmcnt(6)
	s_barrier
; __device__ __forceinline__ unsigned pk2(float lo, float hi) { const f32x2 v = (f32x2){lo, hi}; const bf16x2_t b = __builtin_convertvector(v, bf16x2_t); return __builtin_bit_cast(unsigned, b); }
; #define PG8_STAGE(bufoff, gbase, voff) do { _Pragma("unroll") for (int _i = 0; _i < 2; ++_i) \
;         __builtin_amdgcn_global_load_lds((const unsigned*)((const char*)(gbase) + (voff)[_i]), (LAS unsigned*)(lds + (bufoff) + ldsw + _i * 8192), 16, 0, 0); } while (0)
; #define PG8_LDA(dst, b, h) do { _Pragma("unroll") for (int m = 0; m < 4; ++m) _Pragma("unroll") for (int k = 0; k < 2; ++k) dst[m][k] = *(const LAS bf16x8*)(lds + PG8_SA(b, h) + aoff + m * 2048 + k * 1024); } while (0)
; #define PG8_SCHED __builtin_amdgcn_sched_barrier(0)
;     __device__ __forceinline__ void operator()(const f32x4 (&acc)[2][2][4][2], const Unit& u, int wr, int wc, int fr, int fq, const float (&)[8]) const {
;     ...
;         const int col0 = u.pn * BM + wc * 32 + 8 * fq;
; #pragma unroll
;         for (int ai = 0; ai < 2; ++ai)
; #pragma unroll
;             for (int m = 0; m < 4; ++m) { const int row = row0 + ai * HALF + m * 16; const float rs = rsqrtf(ep[ai * 4 + m] * (1.0f / 1024.0f) + EPS);
;                 u16* rowp = O + (size_t)row * ldc + col0;
; #pragma unroll
;                 for (int bj = 0; bj < 2; ++bj) { f32x4 v0 = acc[ai][bj][m][0] * rs, v1 = acc[ai][bj][m][1] * rs;
;                     if (ACT == 1) {
; #pragma unroll
;                         for (int j = 0; j < 4; ++j) { const float a0 = fmaxf(v0[j], 0.f), a1 = fmaxf(v1[j], 0.f); v0[j] = a0 * a0; v1[j] = a1 * a1; } }
;                     u32x4 w; w.x = pk2(v0[0], v0[1]); w.y = pk2(v0[2], v0[3]); w.z = pk2(v1[0], v1[1]); w.w = pk2(v1[2], v1[3]);
;                     *(u32x4*)(rowp + bj * HALF) = w; } }
; template <class Epi>
; __device__ __forceinline__ void gemm_phase(LAS unsigned char* lds, const Gemm g, const StaticOrder& S, const Epi& E) {
;     ...
;             const char* a1 = cA + (size_t)(t + 1) * kstep;
;             const char* a2 = last ? nA : cA + (size_t)(t + 2) * kstep; const char* b2 = last ? nB : cB + (size_t)(t + 2) * kstep;
;             const char* a3 = a2 + kstep; const char* b3 = b2 + kstep;
;             if (last) E.pre(cur, wr, fr, epre);
;             PG8_LDB(B0, 0, 0); PG8_SCHED; PG8_LDA(At, 0, 0); PG8_STAGE(PG8_SA(1, 1), a1 + hstepA, voffA);
	s_setprio 1
	v_mfma_f32_16x16x32_bf16 v[52:55], v[204:207], v[166:169], v[52:55]
	v_mfma_f32_16x16x32_bf16 v[48:51], v[212:215], v[166:169], v[48:51]
	v_mfma_f32_16x16x32_bf16 v[36:39], v[204:207], v[180:183], v[36:39]
	v_mfma_f32_16x16x32_bf16 v[32:35], v[212:215], v[180:183], v[32:35]
	v_mfma_f32_16x16x32_bf16 v[20:23], v[204:207], v[188:191], v[20:23]
	v_mfma_f32_16x16x32_bf16 v[16:19], v[212:215], v[188:191], v[16:19]
	v_mfma_f32_16x16x32_bf16 v[4:7], v[204:207], v[196:199], v[4:7]
	v_mfma_f32_16x16x32_bf16 v[0:3], v[212:215], v[196:199], v[0:3]
	v_mfma_f32_16x16x32_bf16 v[52:55], v[208:211], v[170:173], v[52:55]
	v_mfma_f32_16x16x32_bf16 v[48:51], v[216:219], v[170:173], v[48:51]
	v_mfma_f32_16x16x32_bf16 v[36:39], v[208:211], v[184:187], v[36:39]
	v_mfma_f32_16x16x32_bf16 v[32:35], v[216:219], v[184:187], v[32:35]
	v_mfma_f32_16x16x32_bf16 v[20:23], v[208:211], v[192:195], v[20:23]
	v_mfma_f32_16x16x32_bf16 v[16:19], v[216:219], v[192:195], v[16:19]
	v_mfma_f32_16x16x32_bf16 v[4:7], v[208:211], v[200:203], v[4:7]
	v_mfma_f32_16x16x32_bf16 v[0:3], v[216:219], v[200:203], v[0:3]
	s_setprio 0
	s_add_i32 s45, s45, 2
	s_add_u32 s20, s20, 0x100
	s_addc_u32 s21, s21, 0
	s_add_u32 s43, s43, 0x100
	s_addc_u32 s44, s44, 0
	s_cmp_gt_u32 s45, 13
	s_barrier
	s_cbranch_scc0 .LBB0_1204
	s_bfe_u32 vcc_lo, s18, 0x20003
	s_lshl_b32 vcc_lo, vcc_lo, 10
	s_add_i32 vcc_lo, vcc_lo, 0x20010
	v_lshl_add_u32 v236, v153, 2, vcc_lo
	ds_read_b32 v228, v236
	ds_read_b32 v229, v236 offset:64
	ds_read_b32 v230, v236 offset:128
	ds_read_b32 v231, v236 offset:192
	ds_read_b32 v232, v236 offset:512
	ds_read_b32 v233, v236 offset:576
	ds_read_b32 v234, v236 offset:640
	ds_read_b32 v235, v236 offset:704
	s_waitcnt lgkmcnt(0)
	s_add_u32 vcc_lo, s41, 0x40080
	s_addc_u32 vcc_hi, s13, 0
	s_add_i32 m0, s19, 0xc000
	v_lshl_add_u64 v[236:237], vcc, 0, v[138:139]
	v_lshl_add_u64 v[238:239], vcc, 0, v[140:141]
	global_load_lds_dwordx4 v[236:237], off
	s_add_i32 m0, s19, 0xe000
	s_nop 0
	global_load_lds_dwordx4 v[238:239], off
	v_lshl_add_u32 v148, s18, 8, v153
	v_ashrrev_i32_e32 v149, 31, v148
	v_or_b32_e32 v172, 16, v148
	v_ashrrev_i32_e32 v173, 31, v172
	v_or_b32_e32 v168, 32, v148
	v_or_b32_e32 v164, 48, v148
	v_ashrrev_i32_e32 v169, 31, v168
	v_ashrrev_i32_e32 v165, 31, v164
	v_add_u32_e32 v162, 0x80, v148
	v_add_u32_e32 v156, 0x90, v148
	v_ashrrev_i32_e32 v163, 31, v162
	v_ashrrev_i32_e32 v157, 31, v156
	v_add_u32_e32 v150, 0xa0, v148
	v_ashrrev_i32_e32 v151, 31, v150
	v_add_u32_e32 v146, 0xb0, v148
	v_ashrrev_i32_e32 v147, 31, v146
	v_lshl_or_b32 v166, s40, 8, v175
	v_ashrrev_i32_e32 v167, 31, v166
	v_lshlrev_b64 v[170:171], 13, v[148:149]
	v_lshlrev_b64 v[148:149], 1, v[166:167]
	v_lshl_add_u64 v[166:167], s[96:97], 0, v[170:171]
	v_lshl_add_u64 v[210:211], v[166:167], 0, v[148:149]
	s_mov_b32 s40, s10
	s_mov_b32 s18, s12
	s_mov_b64 s[22:23], s[16:17]
	s_mov_b64 s[20:21], s[14:15]
	s_waitcnt vmcnt(10)
	s_waitcnt lgkmcnt(0)
	s_waitcnt lgkmcnt(0)
	v_mov_b32_e32 v182, v228
	v_pk_mul_f32 v[120:121], v[120:121], v[182:183] op_sel_hi:[1,0]
	v_pk_mul_f32 v[126:127], v[126:127], v[182:183] op_sel_hi:[1,0]
	v_pk_mul_f32 v[124:125], v[124:125], v[182:183] op_sel_hi:[1,0]
	v_pk_mul_f32 v[122:123], v[122:123], v[182:183] op_sel_hi:[1,0]
	v_max_f32_e32 v120, 0, v120
	v_max_f32_e32 v121, 0, v121
	v_max_f32_e32 v124, 0, v124
	v_max_f32_e32 v125, 0, v125
	v_pk_mul_f32 v[188:189], v[120:121], v[120:121]
	v_max_f32_e32 v120, 0, v126
	v_max_f32_e32 v122, 0, v122
	v_max_f32_e32 v121, 0, v127
	v_max_f32_e32 v123, 0, v123
	v_pk_mul_f32 v[124:125], v[124:125], v[124:125]
	v_pk_mul_f32 v[126:127], v[120:121], v[120:121]
	v_pk_mul_f32 v[192:193], v[122:123], v[122:123]
	v_pk_mul_f32 v[114:115], v[114:115], v[182:183] op_sel_hi:[1,0]
	v_cvt_pk_bf16_f32 v120, v124, v125
	v_cvt_pk_bf16_f32 v121, v126, v127
	v_cvt_pk_bf16_f32 v122, v188, v189
	v_cvt_pk_bf16_f32 v123, v192, v193
	v_pk_mul_f32 v[116:117], v[116:117], v[182:183] op_sel_hi:[1,0]
	v_pk_mul_f32 v[112:113], v[112:113], v[182:183] op_sel_hi:[1,0]
	v_max_f32_e32 v114, 0, v114
	v_max_f32_e32 v115, 0, v115
	global_store_dwordx4 v[210:211], v[120:123], off
	v_pk_mul_f32 v[118:119], v[118:119], v[182:183] op_sel_hi:[1,0]
	v_max_f32_e32 v116, 0, v116
	v_max_f32_e32 v112, 0, v112
	v_max_f32_e32 v117, 0, v117
	v_max_f32_e32 v113, 0, v113
	v_pk_mul_f32 v[122:123], v[114:115], v[114:115]
	v_pk_mul_f32 v[116:117], v[116:117], v[116:117]
	v_pk_mul_f32 v[120:121], v[112:113], v[112:113]
	v_max_f32_e32 v112, 0, v118
	v_max_f32_e32 v113, 0, v119
	v_pk_mul_f32 v[118:119], v[112:113], v[112:113]
	v_cvt_pk_bf16_f32 v112, v116, v117
	v_cvt_pk_bf16_f32 v113, v118, v119
	v_cvt_pk_bf16_f32 v114, v120, v121
	v_cvt_pk_bf16_f32 v115, v122, v123
	global_store_dwordx4 v[210:211], v[112:115], off offset:256
	s_nop 1
	v_mov_b32_e32 v112, v229
	v_pk_mul_f32 v[104:105], v[104:105], v[112:113] op_sel_hi:[1,0]
	v_pk_mul_f32 v[110:111], v[110:111], v[112:113] op_sel_hi:[1,0]
	v_pk_mul_f32 v[108:109], v[108:109], v[112:113] op_sel_hi:[1,0]
	v_pk_mul_f32 v[106:107], v[106:107], v[112:113] op_sel_hi:[1,0]
	v_max_f32_e32 v104, 0, v104
	v_max_f32_e32 v105, 0, v105
	v_lshlrev_b64 v[114:115], 13, v[172:173]
	v_max_f32_e32 v108, 0, v108
	v_max_f32_e32 v109, 0, v109
	v_pk_mul_f32 v[116:117], v[104:105], v[104:105]
	v_max_f32_e32 v104, 0, v110
	v_max_f32_e32 v106, 0, v106
	v_max_f32_e32 v105, 0, v111
	v_max_f32_e32 v107, 0, v107
	v_lshl_add_u64 v[114:115], s[96:97], 0, v[114:115]
	v_pk_mul_f32 v[108:109], v[108:109], v[108:109]
	v_pk_mul_f32 v[110:111], v[104:105], v[104:105]
	v_pk_mul_f32 v[118:119], v[106:107], v[106:107]
	v_pk_mul_f32 v[96:97], v[96:97], v[112:113] op_sel_hi:[1,0]
	v_lshl_add_u64 v[114:115], v[114:115], 0, v[148:149]
	v_cvt_pk_bf16_f32 v104, v108, v109
	v_cvt_pk_bf16_f32 v105, v110, v111
	v_cvt_pk_bf16_f32 v106, v116, v117
	v_cvt_pk_bf16_f32 v107, v118, v119
	v_pk_mul_f32 v[102:103], v[102:103], v[112:113] op_sel_hi:[1,0]
	v_max_f32_e32 v96, 0, v96
	v_max_f32_e32 v97, 0, v97
	global_store_dwordx4 v[114:115], v[104:107], off
	v_pk_mul_f32 v[100:101], v[100:101], v[112:113] op_sel_hi:[1,0]
	v_pk_mul_f32 v[98:99], v[98:99], v[112:113] op_sel_hi:[1,0]
	v_pk_mul_f32 v[104:105], v[96:97], v[96:97]
	v_max_f32_e32 v96, 0, v102
	v_max_f32_e32 v97, 0, v103
	v_max_f32_e32 v100, 0, v100
	v_max_f32_e32 v101, 0, v101
	v_pk_mul_f32 v[100:101], v[100:101], v[100:101]
	v_pk_mul_f32 v[108:109], v[96:97], v[96:97]
	v_cvt_pk_bf16_f32 v96, v100, v101
	s_waitcnt lgkmcnt(0)
; __device__ __forceinline__ unsigned pk2(float lo, float hi) { const f32x2 v = (f32x2){lo, hi}; const bf16x2_t b = __builtin_convertvector(v, bf16x2_t); return __builtin_bit_cast(unsigned, b); }
;     __device__ __forceinline__ void operator()(const f32x4 (&acc)[2][2][4][2], const Unit& u, int wr, int wc, int fr, int fq, const float (&)[8]) const {
;     ...
;             for (int m = 0; m < 4; ++m) { const int row = row0 + ai * HALF + m * 16; const float rs = rsqrtf(ep[ai * 4 + m] * (1.0f / 1024.0f) + EPS);
;                 u16* rowp = O + (size_t)row * ldc + col0;
; #pragma unroll
;                 for (int bj = 0; bj < 2; ++bj) { f32x4 v0 = acc[ai][bj][m][0] * rs, v1 = acc[ai][bj][m][1] * rs;
;                     if (ACT == 1) {
; #pragma unroll
;                         for (int j = 0; j < 4; ++j) { const float a0 = fmaxf(v0[j], 0.f), a1 = fmaxf(v1[j], 0.f); v0[j] = a0 * a0; v1[j] = a1 * a1; } }
;                     u32x4 w; w.x = pk2(v0[0], v0[1]); w.y = pk2(v0[2], v0[3]); w.z = pk2(v1[0], v1[1]); w.w = pk2(v1[2], v1[3]);
;                     *(u32x4*)(rowp + bj * HALF) = w; } }
	v_max_f32_e32 v98, 0, v98
	v_max_f32_e32 v99, 0, v99
	v_pk_mul_f32 v[110:111], v[98:99], v[98:99]
	v_cvt_pk_bf16_f32 v97, v108, v109
	v_cvt_pk_bf16_f32 v98, v104, v105
	v_cvt_pk_bf16_f32 v99, v110, v111
	global_store_dwordx4 v[114:115], v[96:99], off offset:256
	s_waitcnt lgkmcnt(0)
	s_nop 0
	s_nop 0
	s_nop 0
	s_nop 1
	v_lshlrev_b64 v[98:99], 13, v[168:169]
	v_lshl_add_u64 v[98:99], s[96:97], 0, v[98:99]
	v_lshl_add_u64 v[98:99], v[98:99], 0, v[148:149]
	v_mov_b32_e32 v100, v230
	v_pk_mul_f32 v[88:89], v[88:89], v[100:101] op_sel_hi:[1,0]
	v_pk_mul_f32 v[94:95], v[94:95], v[100:101] op_sel_hi:[1,0]
	v_pk_mul_f32 v[92:93], v[92:93], v[100:101] op_sel_hi:[1,0]
	v_pk_mul_f32 v[90:91], v[90:91], v[100:101] op_sel_hi:[1,0]
	v_max_f32_e32 v88, 0, v88
	v_max_f32_e32 v89, 0, v89
	v_max_f32_e32 v92, 0, v92
	v_max_f32_e32 v93, 0, v93
	v_pk_mul_f32 v[102:103], v[88:89], v[88:89]
	v_max_f32_e32 v88, 0, v94
	v_max_f32_e32 v90, 0, v90
	v_max_f32_e32 v89, 0, v95
	v_max_f32_e32 v91, 0, v91
	v_pk_mul_f32 v[92:93], v[92:93], v[92:93]
	v_pk_mul_f32 v[94:95], v[88:89], v[88:89]
	v_pk_mul_f32 v[104:105], v[90:91], v[90:91]
	v_pk_mul_f32 v[82:83], v[82:83], v[100:101] op_sel_hi:[1,0]
	v_cvt_pk_bf16_f32 v88, v92, v93
	v_cvt_pk_bf16_f32 v89, v94, v95
	v_cvt_pk_bf16_f32 v90, v102, v103
	v_cvt_pk_bf16_f32 v91, v104, v105
	v_pk_mul_f32 v[84:85], v[84:85], v[100:101] op_sel_hi:[1,0]
	v_pk_mul_f32 v[80:81], v[80:81], v[100:101] op_sel_hi:[1,0]
	v_max_f32_e32 v82, 0, v82
	v_max_f32_e32 v83, 0, v83
	global_store_dwordx4 v[98:99], v[88:91], off
	v_pk_mul_f32 v[86:87], v[86:87], v[100:101] op_sel_hi:[1,0]
	v_max_f32_e32 v84, 0, v84
	v_max_f32_e32 v80, 0, v80
	v_max_f32_e32 v85, 0, v85
	v_max_f32_e32 v81, 0, v81
	v_pk_mul_f32 v[90:91], v[82:83], v[82:83]
	v_pk_mul_f32 v[84:85], v[84:85], v[84:85]
	v_pk_mul_f32 v[88:89], v[80:81], v[80:81]
	v_max_f32_e32 v80, 0, v86
	v_max_f32_e32 v81, 0, v87
	v_pk_mul_f32 v[86:87], v[80:81], v[80:81]
	v_cvt_pk_bf16_f32 v80, v84, v85
	v_cvt_pk_bf16_f32 v81, v86, v87
	v_cvt_pk_bf16_f32 v82, v88, v89
	v_cvt_pk_bf16_f32 v83, v90, v91
	global_store_dwordx4 v[98:99], v[80:83], off offset:256
	s_nop 1
	v_mov_b32_e32 v80, v231
	v_pk_mul_f32 v[72:73], v[72:73], v[80:81] op_sel_hi:[1,0]
	v_pk_mul_f32 v[78:79], v[78:79], v[80:81] op_sel_hi:[1,0]
	v_pk_mul_f32 v[76:77], v[76:77], v[80:81] op_sel_hi:[1,0]
	v_pk_mul_f32 v[74:75], v[74:75], v[80:81] op_sel_hi:[1,0]
	v_max_f32_e32 v72, 0, v72
	v_max_f32_e32 v73, 0, v73
	v_lshlrev_b64 v[82:83], 13, v[164:165]
	v_max_f32_e32 v76, 0, v76
	v_max_f32_e32 v77, 0, v77
	v_pk_mul_f32 v[84:85], v[72:73], v[72:73]
	v_max_f32_e32 v72, 0, v78
	v_max_f32_e32 v74, 0, v74
	v_max_f32_e32 v73, 0, v79
	v_max_f32_e32 v75, 0, v75
	v_lshl_add_u64 v[82:83], s[96:97], 0, v[82:83]
	v_pk_mul_f32 v[76:77], v[76:77], v[76:77]
	v_pk_mul_f32 v[78:79], v[72:73], v[72:73]
	v_pk_mul_f32 v[86:87], v[74:75], v[74:75]
	v_pk_mul_f32 v[64:65], v[64:65], v[80:81] op_sel_hi:[1,0]
	v_lshl_add_u64 v[82:83], v[82:83], 0, v[148:149]
	v_cvt_pk_bf16_f32 v72, v76, v77
	v_cvt_pk_bf16_f32 v73, v78, v79
	v_cvt_pk_bf16_f32 v74, v84, v85
	v_cvt_pk_bf16_f32 v75, v86, v87
	v_pk_mul_f32 v[70:71], v[70:71], v[80:81] op_sel_hi:[1,0]
	v_max_f32_e32 v64, 0, v64
	v_max_f32_e32 v65, 0, v65
	global_store_dwordx4 v[82:83], v[72:75], off
	v_pk_mul_f32 v[68:69], v[68:69], v[80:81] op_sel_hi:[1,0]
	v_pk_mul_f32 v[66:67], v[66:67], v[80:81] op_sel_hi:[1,0]
	v_pk_mul_f32 v[72:73], v[64:65], v[64:65]
	v_max_f32_e32 v64, 0, v70
	v_max_f32_e32 v65, 0, v71
	v_max_f32_e32 v68, 0, v68
	v_max_f32_e32 v69, 0, v69
	v_pk_mul_f32 v[68:69], v[68:69], v[68:69]
	v_pk_mul_f32 v[76:77], v[64:65], v[64:65]
	v_cvt_pk_bf16_f32 v64, v68, v69
	s_waitcnt lgkmcnt(0)
	v_max_f32_e32 v66, 0, v66
	v_max_f32_e32 v67, 0, v67
	v_pk_mul_f32 v[78:79], v[66:67], v[66:67]
	v_cvt_pk_bf16_f32 v65, v76, v77
	v_cvt_pk_bf16_f32 v66, v72, v73
	v_cvt_pk_bf16_f32 v67, v78, v79
	global_store_dwordx4 v[82:83], v[64:67], off offset:256
	s_waitcnt lgkmcnt(0)
	s_nop 0
	s_nop 0
	s_nop 0
	s_nop 1
	v_lshlrev_b64 v[66:67], 13, v[162:163]
	v_lshl_add_u64 v[66:67], s[96:97], 0, v[66:67]
	v_lshl_add_u64 v[66:67], v[66:67], 0, v[148:149]
	v_mov_b32_e32 v68, v232
	v_pk_mul_f32 v[56:57], v[56:57], v[68:69] op_sel_hi:[1,0]
	v_pk_mul_f32 v[62:63], v[62:63], v[68:69] op_sel_hi:[1,0]
	v_pk_mul_f32 v[60:61], v[60:61], v[68:69] op_sel_hi:[1,0]
	v_pk_mul_f32 v[58:59], v[58:59], v[68:69] op_sel_hi:[1,0]
	v_max_f32_e32 v56, 0, v56
	v_max_f32_e32 v57, 0, v57
	v_max_f32_e32 v60, 0, v60
	v_max_f32_e32 v61, 0, v61
	v_pk_mul_f32 v[70:71], v[56:57], v[56:57]
	v_max_f32_e32 v56, 0, v62
	v_max_f32_e32 v58, 0, v58
	v_max_f32_e32 v57, 0, v63
	v_max_f32_e32 v59, 0, v59
	v_pk_mul_f32 v[60:61], v[60:61], v[60:61]
	v_pk_mul_f32 v[62:63], v[56:57], v[56:57]
	v_pk_mul_f32 v[72:73], v[58:59], v[58:59]
	v_pk_mul_f32 v[50:51], v[50:51], v[68:69] op_sel_hi:[1,0]
	v_cvt_pk_bf16_f32 v56, v60, v61
	v_cvt_pk_bf16_f32 v57, v62, v63
	v_cvt_pk_bf16_f32 v58, v70, v71
	v_cvt_pk_bf16_f32 v59, v72, v73
	v_pk_mul_f32 v[52:53], v[52:53], v[68:69] op_sel_hi:[1,0]
	v_pk_mul_f32 v[48:49], v[48:49], v[68:69] op_sel_hi:[1,0]
	v_max_f32_e32 v50, 0, v50
	v_max_f32_e32 v51, 0, v51
	global_store_dwordx4 v[66:67], v[56:59], off
	v_pk_mul_f32 v[54:55], v[54:55], v[68:69] op_sel_hi:[1,0]
	v_max_f32_e32 v52, 0, v52
	v_max_f32_e32 v48, 0, v48
	v_max_f32_e32 v53, 0, v53
	v_max_f32_e32 v49, 0, v49
	v_pk_mul_f32 v[58:59], v[50:51], v[50:51]
	v_pk_mul_f32 v[52:53], v[52:53], v[52:53]
	v_pk_mul_f32 v[56:57], v[48:49], v[48:49]
	v_max_f32_e32 v48, 0, v54
	v_max_f32_e32 v49, 0, v55
	v_pk_mul_f32 v[54:55], v[48:49], v[48:49]
	v_cvt_pk_bf16_f32 v48, v52, v53
; __device__ __forceinline__ unsigned pk2(float lo, float hi) { const f32x2 v = (f32x2){lo, hi}; const bf16x2_t b = __builtin_convertvector(v, bf16x2_t); return __builtin_bit_cast(unsigned, b); }
; #define PG8_WAIT_V(n) asm volatile("s_waitcnt vmcnt(" #n ")" ::: "memory")
; #define PG8_BAR __builtin_amdgcn_s_barrier()
;     __device__ __forceinline__ void operator()(const f32x4 (&acc)[2][2][4][2], const Unit& u, int wr, int wc, int fr, int fq, const float (&)[8]) const {
;     ...
;             for (int m = 0; m < 4; ++m) { const int row = row0 + ai * HALF + m * 16; const float rs = rsqrtf(ep[ai * 4 + m] * (1.0f / 1024.0f) + EPS);
;                 u16* rowp = O + (size_t)row * ldc + col0;
; #pragma unroll
;                 for (int bj = 0; bj < 2; ++bj) { f32x4 v0 = acc[ai][bj][m][0] * rs, v1 = acc[ai][bj][m][1] * rs;
;                     if (ACT == 1) {
; #pragma unroll
;                         for (int j = 0; j < 4; ++j) { const float a0 = fmaxf(v0[j], 0.f), a1 = fmaxf(v1[j], 0.f); v0[j] = a0 * a0; v1[j] = a1 * a1; } }
;                     u32x4 w; w.x = pk2(v0[0], v0[1]); w.y = pk2(v0[2], v0[3]); w.z = pk2(v1[0], v1[1]); w.w = pk2(v1[2], v1[3]);
;                     *(u32x4*)(rowp + bj * HALF) = w; } }
; template <class Epi>
; __device__ __forceinline__ void gemm_phase(LAS unsigned char* lds, const Gemm g, const StaticOrder& S, const Epi& E) {
;     ...
;         if (!has_next) break;
; #pragma unroll
;         for (int a = 0; a < 2; ++a)
; #pragma unroll
;             for (int b = 0; b < 2; ++b)
; #pragma unroll
;                 for (int m = 0; m < 4; ++m)
; #pragma unroll
;                     for (int n = 0; n < 2; ++n) acc[a][b][m][n] = (f32x4){0.f, 0.f, 0.f, 0.f};
;         cur = nxt; cA = nA; cB = nB; ++ui;
;     }
;     PG8_WAIT_V(0);
;     if (wr == 0) PG8_BAR;
;     PG8_BAR;
	v_cvt_pk_bf16_f32 v49, v54, v55
	v_cvt_pk_bf16_f32 v50, v56, v57
	v_cvt_pk_bf16_f32 v51, v58, v59
	global_store_dwordx4 v[66:67], v[48:51], off offset:256
	s_nop 1
	v_mov_b32_e32 v48, v233
	v_pk_mul_f32 v[40:41], v[40:41], v[48:49] op_sel_hi:[1,0]
	v_pk_mul_f32 v[46:47], v[46:47], v[48:49] op_sel_hi:[1,0]
	v_pk_mul_f32 v[44:45], v[44:45], v[48:49] op_sel_hi:[1,0]
	v_pk_mul_f32 v[42:43], v[42:43], v[48:49] op_sel_hi:[1,0]
	v_max_f32_e32 v40, 0, v40
	v_max_f32_e32 v41, 0, v41
	v_lshlrev_b64 v[50:51], 13, v[156:157]
	v_max_f32_e32 v44, 0, v44
	v_max_f32_e32 v45, 0, v45
	v_pk_mul_f32 v[52:53], v[40:41], v[40:41]
	v_max_f32_e32 v40, 0, v46
	v_max_f32_e32 v42, 0, v42
	v_max_f32_e32 v41, 0, v47
	v_max_f32_e32 v43, 0, v43
	v_lshl_add_u64 v[50:51], s[96:97], 0, v[50:51]
	v_pk_mul_f32 v[44:45], v[44:45], v[44:45]
	v_pk_mul_f32 v[46:47], v[40:41], v[40:41]
	v_pk_mul_f32 v[54:55], v[42:43], v[42:43]
	v_pk_mul_f32 v[32:33], v[32:33], v[48:49] op_sel_hi:[1,0]
	v_lshl_add_u64 v[50:51], v[50:51], 0, v[148:149]
	v_cvt_pk_bf16_f32 v40, v44, v45
	v_cvt_pk_bf16_f32 v41, v46, v47
	v_cvt_pk_bf16_f32 v42, v52, v53
	v_cvt_pk_bf16_f32 v43, v54, v55
	v_pk_mul_f32 v[38:39], v[38:39], v[48:49] op_sel_hi:[1,0]
	v_max_f32_e32 v32, 0, v32
	v_max_f32_e32 v33, 0, v33
	global_store_dwordx4 v[50:51], v[40:43], off
	v_pk_mul_f32 v[36:37], v[36:37], v[48:49] op_sel_hi:[1,0]
	v_pk_mul_f32 v[34:35], v[34:35], v[48:49] op_sel_hi:[1,0]
	v_pk_mul_f32 v[40:41], v[32:33], v[32:33]
	v_max_f32_e32 v32, 0, v38
	v_max_f32_e32 v33, 0, v39
	v_max_f32_e32 v36, 0, v36
	v_max_f32_e32 v37, 0, v37
	v_pk_mul_f32 v[36:37], v[36:37], v[36:37]
	v_pk_mul_f32 v[44:45], v[32:33], v[32:33]
	v_cvt_pk_bf16_f32 v32, v36, v37
	s_waitcnt lgkmcnt(0)
	v_max_f32_e32 v34, 0, v34
	v_max_f32_e32 v35, 0, v35
	v_pk_mul_f32 v[46:47], v[34:35], v[34:35]
	v_cvt_pk_bf16_f32 v33, v44, v45
	v_cvt_pk_bf16_f32 v34, v40, v41
	v_cvt_pk_bf16_f32 v35, v46, v47
	global_store_dwordx4 v[50:51], v[32:35], off offset:256
	s_waitcnt lgkmcnt(0)
	s_nop 0
	s_nop 0
	s_nop 0
	s_nop 1
	v_lshlrev_b64 v[34:35], 13, v[150:151]
	v_lshl_add_u64 v[34:35], s[96:97], 0, v[34:35]
	v_lshl_add_u64 v[34:35], v[34:35], 0, v[148:149]
	v_mov_b32_e32 v36, v234
	v_pk_mul_f32 v[24:25], v[24:25], v[36:37] op_sel_hi:[1,0]
	v_pk_mul_f32 v[30:31], v[30:31], v[36:37] op_sel_hi:[1,0]
	v_pk_mul_f32 v[28:29], v[28:29], v[36:37] op_sel_hi:[1,0]
	v_pk_mul_f32 v[26:27], v[26:27], v[36:37] op_sel_hi:[1,0]
	v_max_f32_e32 v24, 0, v24
	v_max_f32_e32 v25, 0, v25
	v_max_f32_e32 v28, 0, v28
	v_max_f32_e32 v29, 0, v29
	v_pk_mul_f32 v[38:39], v[24:25], v[24:25]
	v_max_f32_e32 v24, 0, v30
	v_max_f32_e32 v26, 0, v26
	v_max_f32_e32 v25, 0, v31
	v_max_f32_e32 v27, 0, v27
	v_pk_mul_f32 v[28:29], v[28:29], v[28:29]
	v_pk_mul_f32 v[30:31], v[24:25], v[24:25]
	v_pk_mul_f32 v[40:41], v[26:27], v[26:27]
	v_pk_mul_f32 v[18:19], v[18:19], v[36:37] op_sel_hi:[1,0]
	v_cvt_pk_bf16_f32 v24, v28, v29
	v_cvt_pk_bf16_f32 v25, v30, v31
	v_cvt_pk_bf16_f32 v26, v38, v39
	v_cvt_pk_bf16_f32 v27, v40, v41
	v_pk_mul_f32 v[20:21], v[20:21], v[36:37] op_sel_hi:[1,0]
	v_pk_mul_f32 v[16:17], v[16:17], v[36:37] op_sel_hi:[1,0]
	v_max_f32_e32 v18, 0, v18
	v_max_f32_e32 v19, 0, v19
	global_store_dwordx4 v[34:35], v[24:27], off
	v_pk_mul_f32 v[22:23], v[22:23], v[36:37] op_sel_hi:[1,0]
	v_max_f32_e32 v20, 0, v20
	v_max_f32_e32 v16, 0, v16
	v_max_f32_e32 v21, 0, v21
	v_max_f32_e32 v17, 0, v17
	v_pk_mul_f32 v[26:27], v[18:19], v[18:19]
	v_pk_mul_f32 v[20:21], v[20:21], v[20:21]
	v_pk_mul_f32 v[24:25], v[16:17], v[16:17]
	v_max_f32_e32 v16, 0, v22
	v_max_f32_e32 v17, 0, v23
	v_pk_mul_f32 v[22:23], v[16:17], v[16:17]
	v_cvt_pk_bf16_f32 v16, v20, v21
	v_cvt_pk_bf16_f32 v17, v22, v23
	v_cvt_pk_bf16_f32 v18, v24, v25
	v_cvt_pk_bf16_f32 v19, v26, v27
	global_store_dwordx4 v[34:35], v[16:19], off offset:256
	s_nop 1
	v_mov_b32_e32 v16, v235
	v_pk_mul_f32 v[8:9], v[8:9], v[16:17] op_sel_hi:[1,0]
	v_pk_mul_f32 v[14:15], v[14:15], v[16:17] op_sel_hi:[1,0]
	v_pk_mul_f32 v[12:13], v[12:13], v[16:17] op_sel_hi:[1,0]
	v_pk_mul_f32 v[10:11], v[10:11], v[16:17] op_sel_hi:[1,0]
	v_max_f32_e32 v8, 0, v8
	v_max_f32_e32 v9, 0, v9
	v_lshlrev_b64 v[18:19], 13, v[146:147]
	v_max_f32_e32 v12, 0, v12
	v_max_f32_e32 v13, 0, v13
	v_pk_mul_f32 v[20:21], v[8:9], v[8:9]
	v_max_f32_e32 v8, 0, v14
	v_max_f32_e32 v10, 0, v10
	v_max_f32_e32 v9, 0, v15
	v_max_f32_e32 v11, 0, v11
	v_lshl_add_u64 v[18:19], s[96:97], 0, v[18:19]
	v_pk_mul_f32 v[12:13], v[12:13], v[12:13]
	v_pk_mul_f32 v[14:15], v[8:9], v[8:9]
	v_pk_mul_f32 v[22:23], v[10:11], v[10:11]
	v_pk_mul_f32 v[0:1], v[0:1], v[16:17] op_sel_hi:[1,0]
	v_lshl_add_u64 v[18:19], v[18:19], 0, v[148:149]
	v_cvt_pk_bf16_f32 v8, v12, v13
	v_cvt_pk_bf16_f32 v9, v14, v15
	v_cvt_pk_bf16_f32 v10, v20, v21
	v_cvt_pk_bf16_f32 v11, v22, v23
	v_pk_mul_f32 v[6:7], v[6:7], v[16:17] op_sel_hi:[1,0]
	v_pk_mul_f32 v[4:5], v[4:5], v[16:17] op_sel_hi:[1,0]
	v_pk_mul_f32 v[2:3], v[2:3], v[16:17] op_sel_hi:[1,0]
	v_max_f32_e32 v0, 0, v0
	v_max_f32_e32 v1, 0, v1
	global_store_dwordx4 v[18:19], v[8:11], off
	v_max_f32_e32 v4, 0, v4
	v_max_f32_e32 v5, 0, v5
	v_pk_mul_f32 v[8:9], v[0:1], v[0:1]
	v_max_f32_e32 v0, 0, v6
	v_max_f32_e32 v2, 0, v2
	v_max_f32_e32 v1, 0, v7
	v_max_f32_e32 v3, 0, v3
	v_pk_mul_f32 v[4:5], v[4:5], v[4:5]
	v_pk_mul_f32 v[6:7], v[0:1], v[0:1]
	v_pk_mul_f32 v[10:11], v[2:3], v[2:3]
	v_cvt_pk_bf16_f32 v0, v4, v5
	v_cvt_pk_bf16_f32 v1, v6, v7
	v_cvt_pk_bf16_f32 v2, v8, v9
	v_cvt_pk_bf16_f32 v3, v10, v11
	s_and_b64 vcc, exec, s[0:1]
	global_store_dwordx4 v[18:19], v[0:3], off offset:256
	s_cbranch_vccz .LBB0_1197
	s_waitcnt vmcnt(0)
	s_cmpk_gt_u32 s7, 0xff
	s_cbranch_scc1 .LBB0_1208
	s_barrier
